# merge: even and odd waves prefetch K-tiles at different distances (5 vs 6 tiles ahead), otherwise as before
# speedup vs baseline: 1.0000x; 1.0000x over previous
; template <bool RFA, bool RFB, class LA, class LB, class EPI>
; DI void gemm_tile2s(u16* smem, int nk, LA la, LB lb, EPI epi) {
;   const int tid = tidx(), lane = tid & 63, wave = tid >> 6;
;   const int wm = wave >> 2, wn = wave & 3, lr = lane & 31, lh = lane >> 5;
;   u16* As = smem;
;   u16* Bs = smem + 2 * TILE_ELEMS;
;   f32x16 acc[2];
;   acc[0] = zero16(); acc[1] = zero16();
;   u32x4 ra0[2], rb0[2], ra1[2], rb1[2];
;   auto ld = [&](u32x4 (&ra)[2], u32x4 (&rb)[2], int kt) __attribute__((always_inline)) {
;     const int k0 = kt * 64;
; #pragma unroll
;     for (int i = 0; i < 2; ++i) { const int c = tid + NTH * i; ra[i] = la(A_ROW(c), k0 + A_KC(c) * 8); rb[i] = lb(B_ROW(c), k0 + B_KC(c) * 8); }
;   };
;   auto stl = [&](u32x4 (&ra)[2], u32x4 (&rb)[2], int buf) __attribute__((always_inline)) {
; #pragma unroll
;     for (int i = 0; i < 2; ++i) {
;       const int c = tid + NTH * i;
;       *(u32x4*)(As + buf * TILE_ELEMS + A_ROW(c) * LDT + A_KC(c) * 8) = ra[i];
;       *(u32x4*)(Bs + buf * TILE_ELEMS + B_ROW(c) * LDT + B_KC(c) * 8) = rb[i];
;     }
;   };
;   auto compute = [&](int buf) __attribute__((always_inline)) {
;     const u16* Ab = As + buf * TILE_ELEMS + (wm * 64 + lr) * LDT + lh * 8;
;     const u16* Bb = Bs + buf * TILE_ELEMS + (wn * 32 + lr) * LDT + lh * 8;
; #pragma unroll
;     for (int ks = 0; ks < 4; ++ks) {
;       const bf16x8 a0 = *(const bf16x8*)(Ab + ks * 16);
;       const bf16x8 a1 = *(const bf16x8*)(Ab + 32 * LDT + ks * 16);
;       const bf16x8 b = *(const bf16x8*)(Bb + ks * 16);
;       acc[0] = mfma(a0, b, acc[0]);
;       acc[1] = mfma(a1, b, acc[1]);
;     }
;   };
;   ld(ra0, rb0, 0);
;   if (nk > 1) ld(ra1, rb1, 1);
;   stl(ra0, rb0, 0);
;   if (nk > 2) ld(ra0, rb0, 2);
;   __syncthreads();
; template <class ACC>
; DI void merge_branch(const Prm& p, u16* smem, const u16* W, const u16* X, int ld, int bi, int n0, int m0, ACC& macc) {
;   auto la = [&](int row, int k) __attribute__((always_inline)) { return *(const u32x4*)(W + (size_t)(n0 + (row & ~31) + perm_m(row & 31)) * ld + k); };
;   auto lb = [&](int row, int k) __attribute__((always_inline)) { return *(const u32x4*)(X + (size_t)(m0 + row) * ld + k); };
;   auto epi = [&](f32x16 (&acc)[2], int wm, int wn, int lane) __attribute__((always_inline)) {
;     const int lr = lane & 31, lh = lane >> 5;
.LBB0_2250:
	v_and_b32_e32 v226, 64, v224
	v_cmp_ne_u32_e32 vcc, 0, v226
	s_nop 4
	s_cbranch_vccnz .Lmrg_oddw
	v_readlane_b32 s36, v253, 28
	v_readlane_b32 s37, v253, 29
	v_readlane_b32 s38, v253, 30
	v_readlane_b32 s39, v253, 31
	v_readlane_b32 s40, v252, 4
	v_readlane_b32 s41, v252, 5
	v_readlane_b32 s42, v252, 6
	v_readlane_b32 s43, v252, 7
	v_readlane_b32 s48, v253, 20
	v_readlane_b32 s49, v253, 21
	v_and_b32_e32 v226, 7, v224
	v_lshlrev_b32_e32 v226, 4, v226
	v_lshrrev_b32_e32 v227, 3, v224
	v_and_b32_e32 v228, 0xffffffe3, v227
	v_lshrrev_b32_e32 v229, 1, v227
	v_and_b32_e32 v229, 12, v229
	v_or_b32_e32 v228, v228, v229
	v_lshlrev_b32_e32 v229, 2, v227
	v_and_b32_e32 v229, 16, v229
	v_or_b32_e32 v228, v228, v229
	s_movk_i32 s52, 0x600
	v_mad_u32_u24 v210, v228, s52, v226
	v_mad_u32_u24 v214, v227, s52, v226
	s_movk_i32 s52, 0x100
	v_mad_u32_u24 v211, v228, s52, v226
	v_mad_u32_u24 v215, v227, s52, v226
	s_movk_i32 s52, 0x300
	v_mad_u32_u24 v212, v228, s52, v226
	v_mad_u32_u24 v216, v227, s52, v226
	s_movk_i32 s52, 0x200
	v_mad_u32_u24 v213, v228, s52, v226
	v_mad_u32_u24 v217, v227, s52, v226
	s_movk_i32 s52, 0x90
	v_mad_u32_u24 v218, v227, s52, v226
	v_lshrrev_b32_e32 v226, 1, v224
	v_and_b32_e32 v227, 16, v226
	v_and_b32_e32 v228, 31, v224
	v_lshrrev_b32_e32 v229, 2, v224
	v_and_b32_e32 v229, 64, v229
	v_and_b32_e32 v226, 0x60, v226
	v_or_b32_e32 v226, v226, v228
	v_or_b32_e32 v228, v229, v228
	v_mad_u32_u24 v219, v228, s52, v227
	v_mad_u32_u24 v220, v226, s52, v227
	v_add_u32_e32 v220, 0xd800, v220
	v_add_u32_e32 v223, 0xd800, v218
	v_or_b32_e32 v229, v229, v227
	v_lshlrev_b32_e32 v229, 1, v229
	v_lshl_add_u32 v221, v226, 13, v229
	v_lshl_add_u32 v222, v226, 11, v229
	s_and_b32 s58, s31, 7
	s_lshl_b32 s58, s58, 7
	s_lshr_b32 s59, s31, 3
	s_lshl_b32 s59, s59, 7
	s_mul_i32 s52, s58, 0x600
	s_add_u32 s0, s16, s52
	s_addc_u32 s1, s17, 0
	s_add_u32 s2, s0, 0x18000
	s_addc_u32 s3, s1, 0
	s_mul_i32 s52, s59, 0x600
	s_add_u32 s4, s14, s52
	s_addc_u32 s5, s15, 0
	s_add_u32 s6, s4, 0x18000
	s_addc_u32 s7, s5, 0
	global_load_dwordx4 v[66:69], v210, s[0:1]
	global_load_dwordx4 v[70:73], v210, s[2:3]
	global_load_dwordx4 v[74:77], v214, s[4:5]
	global_load_dwordx4 v[78:81], v214, s[6:7]
	global_load_dwordx4 v[82:85], v210, s[0:1] offset:128
	global_load_dwordx4 v[86:89], v210, s[2:3] offset:128
	global_load_dwordx4 v[90:93], v214, s[4:5] offset:128
	global_load_dwordx4 v[94:97], v214, s[6:7] offset:128
	global_load_dwordx4 v[98:101], v210, s[0:1] offset:256
	global_load_dwordx4 v[102:105], v210, s[2:3] offset:256
	global_load_dwordx4 v[106:109], v214, s[4:5] offset:256
	global_load_dwordx4 v[110:113], v214, s[6:7] offset:256
	s_waitcnt vmcnt(4)
	ds_write_b128 v218, v[66:69]
	ds_write_b128 v218, v[70:73] offset:9216
	ds_write_b128 v223, v[74:77]
	ds_write_b128 v223, v[78:81] offset:9216
	ds_write_b128 v218, v[82:85] offset:18432
	ds_write_b128 v218, v[86:89] offset:27648
	ds_write_b128 v223, v[90:93] offset:18432
	ds_write_b128 v223, v[94:97] offset:27648
	global_load_dwordx4 v[66:69], v210, s[0:1] offset:384
	global_load_dwordx4 v[70:73], v210, s[2:3] offset:384
	global_load_dwordx4 v[74:77], v214, s[4:5] offset:384
	global_load_dwordx4 v[78:81], v214, s[6:7] offset:384
	global_load_dwordx4 v[82:85], v210, s[0:1] offset:512
	global_load_dwordx4 v[86:89], v210, s[2:3] offset:512
	global_load_dwordx4 v[90:93], v214, s[4:5] offset:512
	global_load_dwordx4 v[94:97], v214, s[6:7] offset:512
	s_waitcnt vmcnt(0)
	s_waitcnt lgkmcnt(0)
	s_barrier
	ds_read_b128 v[130:133], v219
	ds_read_b128 v[134:137], v220
	ds_read_b128 v[138:141], v219 offset:4608
	ds_read_b128 v[142:145], v219 offset:32
	ds_read_b128 v[146:149], v220 offset:32
	ds_read_b128 v[150:153], v219 offset:4640
	s_waitcnt lgkmcnt(0)
.Lmrg_task_e:
	s_lshl_b32 s52, s59, 13
	s_lshl_b32 s53, s58, 1
	s_add_u32 s52, s52, s53
	s_add_u32 s8, s42, s52
	s_addc_u32 s9, s43, 0
	s_add_u32 s10, s8, 0x1000
	s_addc_u32 s11, s9, 0
	s_lshl_b32 s52, s59, 11
	s_add_u32 s52, s52, s53
	s_add_u32 s12, s48, s52
	s_addc_u32 s13, s49, 0
	ds_read_b128 v[154:157], v219 offset:64
	ds_read_b128 v[158:161], v220 offset:64
	ds_read_b128 v[162:165], v219 offset:4672
	v_mfma_f32_32x32x16_bf16 v[18:33], v[130:133], v[134:137], 0
	ds_read_b128 v[166:169], v219 offset:96
	ds_read_b128 v[170:173], v220 offset:96
	ds_read_b128 v[174:177], v219 offset:4704
	v_mfma_f32_32x32x16_bf16 v[2:17], v[138:141], v[134:137], 0
	s_waitcnt vmcnt(12)
	ds_write_b128 v218, v[98:101] offset:36864
	ds_write_b128 v218, v[102:105] offset:46080
	v_mfma_f32_32x32x16_bf16 v[18:33], v[142:145], v[146:149], v[18:33]
	ds_write_b128 v223, v[106:109] offset:36864
	ds_write_b128 v223, v[110:113] offset:46080
	v_mfma_f32_32x32x16_bf16 v[2:17], v[150:153], v[146:149], v[2:17]
	global_load_dwordx4 v[98:101], v210, s[0:1] offset:640
	global_load_dwordx4 v[102:105], v210, s[2:3] offset:640
	global_load_dwordx4 v[106:109], v214, s[4:5] offset:640
	global_load_dwordx4 v[110:113], v214, s[6:7] offset:640
	ds_read_b128 v[130:133], v219 offset:18432
	ds_read_b128 v[134:137], v220 offset:18432
	ds_read_b128 v[138:141], v219 offset:23040
	s_waitcnt lgkmcnt(11)
	v_mfma_f32_32x32x16_bf16 v[18:33], v[154:157], v[158:161], v[18:33]
	ds_read_b128 v[142:145], v219 offset:18464
	ds_read_b128 v[146:149], v220 offset:18464
	ds_read_b128 v[150:153], v219 offset:23072
	s_waitcnt lgkmcnt(13)
	v_mfma_f32_32x32x16_bf16 v[2:17], v[162:165], v[158:161], v[2:17]
	s_waitcnt lgkmcnt(11)
	v_mfma_f32_32x32x16_bf16 v[18:33], v[166:169], v[170:173], v[18:33]
	s_waitcnt lgkmcnt(10)
	v_mfma_f32_32x32x16_bf16 v[2:17], v[174:177], v[170:173], v[2:17]
	s_waitcnt lgkmcnt(0)
	s_barrier
; DI f32x16 mfma(bf16x8 a, bf16x8 b, f32x16 c) { return __builtin_amdgcn_mfma_f32_32x32x16_bf16(a, b, c, 0, 0, 0); }
; template <bool RFA, bool RFB, class LA, class LB, class EPI>
; DI void gemm_tile2s(u16* smem, int nk, LA la, LB lb, EPI epi) {
;     ...
;   auto ld = [&](u32x4 (&ra)[2], u32x4 (&rb)[2], int kt) __attribute__((always_inline)) {
;     const int k0 = kt * 64;
; #pragma unroll
;     for (int i = 0; i < 2; ++i) { const int c = tid + NTH * i; ra[i] = la(A_ROW(c), k0 + A_KC(c) * 8); rb[i] = lb(B_ROW(c), k0 + B_KC(c) * 8); }
;   };
;   auto stl = [&](u32x4 (&ra)[2], u32x4 (&rb)[2], int buf) __attribute__((always_inline)) {
; #pragma unroll
;     for (int i = 0; i < 2; ++i) {
;       const int c = tid + NTH * i;
;       *(u32x4*)(As + buf * TILE_ELEMS + A_ROW(c) * LDT + A_KC(c) * 8) = ra[i];
;       *(u32x4*)(Bs + buf * TILE_ELEMS + B_ROW(c) * LDT + B_KC(c) * 8) = rb[i];
;     }
;   };
;   auto compute = [&](int buf) __attribute__((always_inline)) {
;     const u16* Ab = As + buf * TILE_ELEMS + (wm * 64 + lr) * LDT + lh * 8;
;     const u16* Bb = Bs + buf * TILE_ELEMS + (wn * 32 + lr) * LDT + lh * 8;
; #pragma unroll
;     for (int ks = 0; ks < 4; ++ks) {
;       const bf16x8 a0 = *(const bf16x8*)(Ab + ks * 16);
;       const bf16x8 a1 = *(const bf16x8*)(Ab + 32 * LDT + ks * 16);
;       const bf16x8 b = *(const bf16x8*)(Bb + ks * 16);
;       acc[0] = mfma(a0, b, acc[0]);
;       acc[1] = mfma(a1, b, acc[1]);
;     }
;   };
;   ld(ra0, rb0, 0);
;   if (nk > 1) ld(ra1, rb1, 1);
;   stl(ra0, rb0, 0);
;   if (nk > 2) ld(ra0, rb0, 2);
;   __syncthreads();
; #pragma unroll 1
;   for (int kt = 0; kt < nk; kt += 2) {
;     compute(0);
;     if (kt + 1 < nk) { stl(ra1, rb1, 1); if (kt + 3 < nk) ld(ra1, rb1, kt + 3); }
;     __syncthreads();
;     if (kt + 1 < nk) {
;       compute(1);
;       if (kt + 2 < nk) { stl(ra0, rb0, 0); if (kt + 4 < nk) ld(ra0, rb0, kt + 4); }
;       __syncthreads();
	ds_read_b128 v[154:157], v219 offset:18496
	ds_read_b128 v[158:161], v220 offset:18496
	ds_read_b128 v[162:165], v219 offset:23104
	v_mfma_f32_32x32x16_bf16 v[18:33], v[130:133], v[134:137], v[18:33]
	ds_read_b128 v[166:169], v219 offset:18528
	ds_read_b128 v[170:173], v220 offset:18528
	ds_read_b128 v[174:177], v219 offset:23136
	v_mfma_f32_32x32x16_bf16 v[2:17], v[138:141], v[134:137], v[2:17]
	s_waitcnt vmcnt(12)
	ds_write_b128 v218, v[66:69]
	ds_write_b128 v218, v[70:73] offset:9216
	v_mfma_f32_32x32x16_bf16 v[18:33], v[142:145], v[146:149], v[18:33]
	ds_write_b128 v223, v[74:77]
	ds_write_b128 v223, v[78:81] offset:9216
	v_mfma_f32_32x32x16_bf16 v[2:17], v[150:153], v[146:149], v[2:17]
	global_load_dwordx4 v[66:69], v210, s[0:1] offset:768
	global_load_dwordx4 v[70:73], v210, s[2:3] offset:768
	global_load_dwordx4 v[74:77], v214, s[4:5] offset:768
	global_load_dwordx4 v[78:81], v214, s[6:7] offset:768
	ds_read_b128 v[130:133], v219 offset:36864
	ds_read_b128 v[134:137], v220 offset:36864
	ds_read_b128 v[138:141], v219 offset:41472
	s_waitcnt lgkmcnt(11)
	v_mfma_f32_32x32x16_bf16 v[18:33], v[154:157], v[158:161], v[18:33]
	ds_read_b128 v[142:145], v219 offset:36896
	ds_read_b128 v[146:149], v220 offset:36896
	ds_read_b128 v[150:153], v219 offset:41504
	s_waitcnt lgkmcnt(13)
	v_mfma_f32_32x32x16_bf16 v[2:17], v[162:165], v[158:161], v[2:17]
	s_waitcnt lgkmcnt(11)
	v_mfma_f32_32x32x16_bf16 v[18:33], v[166:169], v[170:173], v[18:33]
	s_waitcnt lgkmcnt(10)
	v_mfma_f32_32x32x16_bf16 v[2:17], v[174:177], v[170:173], v[2:17]
	s_waitcnt lgkmcnt(0)
	s_barrier
	ds_read_b128 v[154:157], v219 offset:36928
	ds_read_b128 v[158:161], v220 offset:36928
	ds_read_b128 v[162:165], v219 offset:41536
	v_mfma_f32_32x32x16_bf16 v[18:33], v[130:133], v[134:137], v[18:33]
	ds_read_b128 v[166:169], v219 offset:36960
	ds_read_b128 v[170:173], v220 offset:36960
	ds_read_b128 v[174:177], v219 offset:41568
	v_mfma_f32_32x32x16_bf16 v[2:17], v[138:141], v[134:137], v[2:17]
	s_waitcnt vmcnt(12)
	ds_write_b128 v218, v[82:85] offset:18432
	ds_write_b128 v218, v[86:89] offset:27648
	v_mfma_f32_32x32x16_bf16 v[18:33], v[142:145], v[146:149], v[18:33]
	ds_write_b128 v223, v[90:93] offset:18432
	ds_write_b128 v223, v[94:97] offset:27648
	v_mfma_f32_32x32x16_bf16 v[2:17], v[150:153], v[146:149], v[2:17]
	global_load_dwordx4 v[82:85], v210, s[0:1] offset:896
	global_load_dwordx4 v[86:89], v210, s[2:3] offset:896
	global_load_dwordx4 v[90:93], v214, s[4:5] offset:896
	global_load_dwordx4 v[94:97], v214, s[6:7] offset:896
	ds_read_b128 v[130:133], v219
	ds_read_b128 v[134:137], v220
	ds_read_b128 v[138:141], v219 offset:4608
	s_waitcnt lgkmcnt(11)
	v_mfma_f32_32x32x16_bf16 v[18:33], v[154:157], v[158:161], v[18:33]
	ds_read_b128 v[142:145], v219 offset:32
	ds_read_b128 v[146:149], v220 offset:32
	ds_read_b128 v[150:153], v219 offset:4640
	s_waitcnt lgkmcnt(13)
	v_mfma_f32_32x32x16_bf16 v[2:17], v[162:165], v[158:161], v[2:17]
	s_waitcnt lgkmcnt(11)
	v_mfma_f32_32x32x16_bf16 v[18:33], v[166:169], v[170:173], v[18:33]
	s_waitcnt lgkmcnt(10)
	v_mfma_f32_32x32x16_bf16 v[2:17], v[174:177], v[170:173], v[2:17]
	s_waitcnt lgkmcnt(0)
	s_barrier
	ds_read_b128 v[154:157], v219 offset:64
	ds_read_b128 v[158:161], v220 offset:64
	ds_read_b128 v[162:165], v219 offset:4672
	v_mfma_f32_32x32x16_bf16 v[18:33], v[130:133], v[134:137], v[18:33]
	ds_read_b128 v[166:169], v219 offset:96
	ds_read_b128 v[170:173], v220 offset:96
	ds_read_b128 v[174:177], v219 offset:4704
	v_mfma_f32_32x32x16_bf16 v[2:17], v[138:141], v[134:137], v[2:17]
	s_waitcnt vmcnt(8)
	ds_write_b128 v218, v[98:101] offset:36864
	ds_write_b128 v218, v[102:105] offset:46080
	v_mfma_f32_32x32x16_bf16 v[18:33], v[142:145], v[146:149], v[18:33]
	ds_write_b128 v223, v[106:109] offset:36864
	ds_write_b128 v223, v[110:113] offset:46080
	v_mfma_f32_32x32x16_bf16 v[2:17], v[150:153], v[146:149], v[2:17]
	global_load_dwordx4 v[98:101], v210, s[0:1] offset:1024
	global_load_dwordx4 v[102:105], v210, s[2:3] offset:1024
	global_load_dwordx4 v[106:109], v214, s[4:5] offset:1024
	global_load_dwordx4 v[110:113], v214, s[6:7] offset:1024
	ds_read_b128 v[130:133], v219 offset:18432
	ds_read_b128 v[134:137], v220 offset:18432
	ds_read_b128 v[138:141], v219 offset:23040
	s_waitcnt lgkmcnt(11)
	v_mfma_f32_32x32x16_bf16 v[18:33], v[154:157], v[158:161], v[18:33]
	ds_read_b128 v[142:145], v219 offset:18464
	ds_read_b128 v[146:149], v220 offset:18464
	ds_read_b128 v[150:153], v219 offset:23072
	s_waitcnt lgkmcnt(13)
	v_mfma_f32_32x32x16_bf16 v[2:17], v[162:165], v[158:161], v[2:17]
	s_waitcnt lgkmcnt(11)
	v_mfma_f32_32x32x16_bf16 v[18:33], v[166:169], v[170:173], v[18:33]
	s_waitcnt lgkmcnt(10)
	v_mfma_f32_32x32x16_bf16 v[2:17], v[174:177], v[170:173], v[2:17]
	s_waitcnt lgkmcnt(0)
	s_barrier
	ds_read_b128 v[154:157], v219 offset:18496
	ds_read_b128 v[158:161], v220 offset:18496
	ds_read_b128 v[162:165], v219 offset:23104
	v_mfma_f32_32x32x16_bf16 v[18:33], v[130:133], v[134:137], v[18:33]
	ds_read_b128 v[166:169], v219 offset:18528
	ds_read_b128 v[170:173], v220 offset:18528
	ds_read_b128 v[174:177], v219 offset:23136
	v_mfma_f32_32x32x16_bf16 v[2:17], v[138:141], v[134:137], v[2:17]
	s_waitcnt vmcnt(8)
	ds_write_b128 v218, v[66:69]
	ds_write_b128 v218, v[70:73] offset:9216
	v_mfma_f32_32x32x16_bf16 v[18:33], v[142:145], v[146:149], v[18:33]
	ds_write_b128 v223, v[74:77]
	ds_write_b128 v223, v[78:81] offset:9216
	v_mfma_f32_32x32x16_bf16 v[2:17], v[150:153], v[146:149], v[2:17]
	global_load_dwordx4 v[66:69], v210, s[0:1] offset:1152
	global_load_dwordx4 v[70:73], v210, s[2:3] offset:1152
	global_load_dwordx4 v[74:77], v214, s[4:5] offset:1152
	global_load_dwordx4 v[78:81], v214, s[6:7] offset:1152
	ds_read_b128 v[130:133], v219 offset:36864
	ds_read_b128 v[134:137], v220 offset:36864
	ds_read_b128 v[138:141], v219 offset:41472
	s_waitcnt lgkmcnt(11)
	v_mfma_f32_32x32x16_bf16 v[18:33], v[154:157], v[158:161], v[18:33]
	ds_read_b128 v[142:145], v219 offset:36896
	ds_read_b128 v[146:149], v220 offset:36896
	ds_read_b128 v[150:153], v219 offset:41504
	s_waitcnt lgkmcnt(13)
	v_mfma_f32_32x32x16_bf16 v[2:17], v[162:165], v[158:161], v[2:17]
	s_waitcnt lgkmcnt(11)
	v_mfma_f32_32x32x16_bf16 v[18:33], v[166:169], v[170:173], v[18:33]
	s_waitcnt lgkmcnt(10)
	v_mfma_f32_32x32x16_bf16 v[2:17], v[174:177], v[170:173], v[2:17]
	s_waitcnt lgkmcnt(0)
	s_barrier
; DI f32x16 mfma(bf16x8 a, bf16x8 b, f32x16 c) { return __builtin_amdgcn_mfma_f32_32x32x16_bf16(a, b, c, 0, 0, 0); }
; template <bool RFA, bool RFB, class LA, class LB, class EPI>
; DI void gemm_tile2s(u16* smem, int nk, LA la, LB lb, EPI epi) {
;     ...
;   auto compute = [&](int buf) __attribute__((always_inline)) {
;     const u16* Ab = As + buf * TILE_ELEMS + (wm * 64 + lr) * LDT + lh * 8;
;     const u16* Bb = Bs + buf * TILE_ELEMS + (wn * 32 + lr) * LDT + lh * 8;
; #pragma unroll
;     for (int ks = 0; ks < 4; ++ks) {
;       const bf16x8 a0 = *(const bf16x8*)(Ab + ks * 16);
;       const bf16x8 a1 = *(const bf16x8*)(Ab + 32 * LDT + ks * 16);
;       const bf16x8 b = *(const bf16x8*)(Bb + ks * 16);
;       acc[0] = mfma(a0, b, acc[0]);
;       acc[1] = mfma(a1, b, acc[1]);
;     }
;   };
;   ld(ra0, rb0, 0);
;   if (nk > 1) ld(ra1, rb1, 1);
;   stl(ra0, rb0, 0);
;   if (nk > 2) ld(ra0, rb0, 2);
;   __syncthreads();
; #pragma unroll 1
;   for (int kt = 0; kt < nk; kt += 2) {
;     compute(0);
;     if (kt + 1 < nk) { stl(ra1, rb1, 1); if (kt + 3 < nk) ld(ra1, rb1, kt + 3); }
;     __syncthreads();
;     if (kt + 1 < nk) {
;       compute(1);
;       if (kt + 2 < nk) { stl(ra0, rb0, 0); if (kt + 4 < nk) ld(ra0, rb0, kt + 4); }
;       __syncthreads();
; template <class ACC>
; DI void merge_branch(const Prm& p, u16* smem, const u16* W, const u16* X, int ld, int bi, int n0, int m0, ACC& macc) {
;   auto la = [&](int row, int k) __attribute__((always_inline)) { return *(const u32x4*)(W + (size_t)(n0 + (row & ~31) + perm_m(row & 31)) * ld + k); };
;   auto lb = [&](int row, int k) __attribute__((always_inline)) { return *(const u32x4*)(X + (size_t)(m0 + row) * ld + k); };
;     ...
;         const int n = n0 + wm * 64 + i * 32 + 16 * lh + 8 * h2;
;         const u32x4 gz = *(const u32x4*)(p.zg + (size_t)tok * 4096 + bi * 1024 + n);
	ds_read_b128 v[154:157], v219 offset:36928
	ds_read_b128 v[158:161], v220 offset:36928
	ds_read_b128 v[162:165], v219 offset:41536
	v_mfma_f32_32x32x16_bf16 v[18:33], v[130:133], v[134:137], v[18:33]
	ds_read_b128 v[166:169], v219 offset:36960
	ds_read_b128 v[170:173], v220 offset:36960
	ds_read_b128 v[174:177], v219 offset:41568
	v_mfma_f32_32x32x16_bf16 v[2:17], v[138:141], v[134:137], v[2:17]
	s_waitcnt vmcnt(8)
	ds_write_b128 v218, v[82:85] offset:18432
	ds_write_b128 v218, v[86:89] offset:27648
	v_mfma_f32_32x32x16_bf16 v[18:33], v[142:145], v[146:149], v[18:33]
	ds_write_b128 v223, v[90:93] offset:18432
	ds_write_b128 v223, v[94:97] offset:27648
	v_mfma_f32_32x32x16_bf16 v[2:17], v[150:153], v[146:149], v[2:17]
	global_load_dwordx4 v[82:85], v210, s[0:1] offset:1280
	global_load_dwordx4 v[86:89], v210, s[2:3] offset:1280
	global_load_dwordx4 v[90:93], v214, s[4:5] offset:1280
	global_load_dwordx4 v[94:97], v214, s[6:7] offset:1280
	global_load_dwordx4 v[178:181], v221, s[8:9]
	global_load_dwordx4 v[182:185], v221, s[8:9] offset:16
	global_load_dwordx4 v[186:189], v221, s[8:9] offset:64
	global_load_dwordx4 v[190:193], v221, s[8:9] offset:80
	ds_read_b128 v[130:133], v219
	ds_read_b128 v[134:137], v220
	ds_read_b128 v[138:141], v219 offset:4608
	s_waitcnt lgkmcnt(11)
	v_mfma_f32_32x32x16_bf16 v[18:33], v[154:157], v[158:161], v[18:33]
	ds_read_b128 v[142:145], v219 offset:32
	ds_read_b128 v[146:149], v220 offset:32
	ds_read_b128 v[150:153], v219 offset:4640
	s_waitcnt lgkmcnt(13)
	v_mfma_f32_32x32x16_bf16 v[2:17], v[162:165], v[158:161], v[2:17]
	s_waitcnt lgkmcnt(11)
	v_mfma_f32_32x32x16_bf16 v[18:33], v[166:169], v[170:173], v[18:33]
	s_waitcnt lgkmcnt(10)
	v_mfma_f32_32x32x16_bf16 v[2:17], v[174:177], v[170:173], v[2:17]
	s_waitcnt lgkmcnt(0)
	s_barrier
	ds_read_b128 v[154:157], v219 offset:64
	ds_read_b128 v[158:161], v220 offset:64
	ds_read_b128 v[162:165], v219 offset:4672
	v_mfma_f32_32x32x16_bf16 v[18:33], v[130:133], v[134:137], v[18:33]
	ds_read_b128 v[166:169], v219 offset:96
	ds_read_b128 v[170:173], v220 offset:96
	ds_read_b128 v[174:177], v219 offset:4704
	v_mfma_f32_32x32x16_bf16 v[2:17], v[138:141], v[134:137], v[2:17]
	s_waitcnt vmcnt(12)
	ds_write_b128 v218, v[98:101] offset:36864
	ds_write_b128 v218, v[102:105] offset:46080
	v_mfma_f32_32x32x16_bf16 v[18:33], v[142:145], v[146:149], v[18:33]
	ds_write_b128 v223, v[106:109] offset:36864
	ds_write_b128 v223, v[110:113] offset:46080
	v_mfma_f32_32x32x16_bf16 v[2:17], v[150:153], v[146:149], v[2:17]
	global_load_dwordx4 v[98:101], v210, s[0:1] offset:1408
	global_load_dwordx4 v[102:105], v210, s[2:3] offset:1408
	global_load_dwordx4 v[106:109], v214, s[4:5] offset:1408
	global_load_dwordx4 v[110:113], v214, s[6:7] offset:1408
	ds_read_b128 v[130:133], v219 offset:18432
	ds_read_b128 v[134:137], v220 offset:18432
	ds_read_b128 v[138:141], v219 offset:23040
	s_waitcnt lgkmcnt(11)
	v_mfma_f32_32x32x16_bf16 v[18:33], v[154:157], v[158:161], v[18:33]
	ds_read_b128 v[142:145], v219 offset:18464
	ds_read_b128 v[146:149], v220 offset:18464
	ds_read_b128 v[150:153], v219 offset:23072
	s_waitcnt lgkmcnt(13)
	v_mfma_f32_32x32x16_bf16 v[2:17], v[162:165], v[158:161], v[2:17]
	s_waitcnt lgkmcnt(11)
	v_mfma_f32_32x32x16_bf16 v[18:33], v[166:169], v[170:173], v[18:33]
	s_waitcnt lgkmcnt(10)
	v_mfma_f32_32x32x16_bf16 v[2:17], v[174:177], v[170:173], v[2:17]
	s_waitcnt lgkmcnt(0)
	s_barrier
	ds_read_b128 v[154:157], v219 offset:18496
	ds_read_b128 v[158:161], v220 offset:18496
	ds_read_b128 v[162:165], v219 offset:23104
	v_mfma_f32_32x32x16_bf16 v[18:33], v[130:133], v[134:137], v[18:33]
	ds_read_b128 v[166:169], v219 offset:18528
	ds_read_b128 v[170:173], v220 offset:18528
	ds_read_b128 v[174:177], v219 offset:23136
	v_mfma_f32_32x32x16_bf16 v[2:17], v[138:141], v[134:137], v[2:17]
	s_waitcnt vmcnt(12)
	ds_write_b128 v218, v[66:69]
	ds_write_b128 v218, v[70:73] offset:9216
	v_mfma_f32_32x32x16_bf16 v[18:33], v[142:145], v[146:149], v[18:33]
	ds_write_b128 v223, v[74:77]
	ds_write_b128 v223, v[78:81] offset:9216
	v_mfma_f32_32x32x16_bf16 v[2:17], v[150:153], v[146:149], v[2:17]
	s_mul_i32 s52, s58, 0x100
	s_add_u32 s0, s20, s52
	s_addc_u32 s1, s21, 0
	s_add_u32 s2, s0, 0x4000
	s_addc_u32 s3, s1, 0
	s_mul_i32 s52, s59, 0x100
	s_add_u32 s4, s36, s52
	s_addc_u32 s5, s37, 0
	s_add_u32 s6, s4, 0x4000
	s_addc_u32 s7, s5, 0
	global_load_dwordx4 v[66:69], v211, s[0:1]
	global_load_dwordx4 v[70:73], v211, s[2:3]
	global_load_dwordx4 v[74:77], v215, s[4:5]
	global_load_dwordx4 v[78:81], v215, s[6:7]
	global_load_dwordx4 v[194:197], v221, s[8:9] offset:2048
	global_load_dwordx4 v[198:201], v221, s[8:9] offset:2064
	global_load_dwordx4 v[202:205], v221, s[8:9] offset:2112
	global_load_dwordx4 v[206:209], v221, s[8:9] offset:2128
	ds_read_b128 v[130:133], v219 offset:36864
	ds_read_b128 v[134:137], v220 offset:36864
	ds_read_b128 v[138:141], v219 offset:41472
	s_waitcnt lgkmcnt(11)
	v_mfma_f32_32x32x16_bf16 v[18:33], v[154:157], v[158:161], v[18:33]
	ds_read_b128 v[142:145], v219 offset:36896
	ds_read_b128 v[146:149], v220 offset:36896
	ds_read_b128 v[150:153], v219 offset:41504
	s_waitcnt lgkmcnt(13)
	v_mfma_f32_32x32x16_bf16 v[2:17], v[162:165], v[158:161], v[2:17]
	s_waitcnt lgkmcnt(11)
	v_mfma_f32_32x32x16_bf16 v[18:33], v[166:169], v[170:173], v[18:33]
	s_waitcnt lgkmcnt(10)
	v_mfma_f32_32x32x16_bf16 v[2:17], v[174:177], v[170:173], v[2:17]
	s_waitcnt lgkmcnt(0)
	s_barrier
; DI f32x16 mfma(bf16x8 a, bf16x8 b, f32x16 c) { return __builtin_amdgcn_mfma_f32_32x32x16_bf16(a, b, c, 0, 0, 0); }
; template <bool RFA, bool RFB, class LA, class LB, class EPI>
; DI void gemm_tile2s(u16* smem, int nk, LA la, LB lb, EPI epi) {
;     ...
;   auto compute = [&](int buf) __attribute__((always_inline)) {
;     const u16* Ab = As + buf * TILE_ELEMS + (wm * 64 + lr) * LDT + lh * 8;
;     const u16* Bb = Bs + buf * TILE_ELEMS + (wn * 32 + lr) * LDT + lh * 8;
; #pragma unroll
;     for (int ks = 0; ks < 4; ++ks) {
;       const bf16x8 a0 = *(const bf16x8*)(Ab + ks * 16);
;       const bf16x8 a1 = *(const bf16x8*)(Ab + 32 * LDT + ks * 16);
;       const bf16x8 b = *(const bf16x8*)(Bb + ks * 16);
;       acc[0] = mfma(a0, b, acc[0]);
;       acc[1] = mfma(a1, b, acc[1]);
;     }
;   };
;   ld(ra0, rb0, 0);
;   if (nk > 1) ld(ra1, rb1, 1);
;   stl(ra0, rb0, 0);
;   if (nk > 2) ld(ra0, rb0, 2);
;   __syncthreads();
; #pragma unroll 1
;   for (int kt = 0; kt < nk; kt += 2) {
;     compute(0);
;     if (kt + 1 < nk) { stl(ra1, rb1, 1); if (kt + 3 < nk) ld(ra1, rb1, kt + 3); }
;     __syncthreads();
;     if (kt + 1 < nk) {
;       compute(1);
;       if (kt + 2 < nk) { stl(ra0, rb0, 0); if (kt + 4 < nk) ld(ra0, rb0, kt + 4); }
;       __syncthreads();
; template <class ACC>
; DI void merge_branch(const Prm& p, u16* smem, const u16* W, const u16* X, int ld, int bi, int n0, int m0, ACC& macc) {
;   auto la = [&](int row, int k) __attribute__((always_inline)) { return *(const u32x4*)(W + (size_t)(n0 + (row & ~31) + perm_m(row & 31)) * ld + k); };
;   auto lb = [&](int row, int k) __attribute__((always_inline)) { return *(const u32x4*)(X + (size_t)(m0 + row) * ld + k); };
	ds_read_b128 v[154:157], v219 offset:36928
	ds_read_b128 v[158:161], v220 offset:36928
	ds_read_b128 v[162:165], v219 offset:41536
	v_mfma_f32_32x32x16_bf16 v[18:33], v[130:133], v[134:137], v[18:33]
	ds_read_b128 v[166:169], v219 offset:36960
	ds_read_b128 v[170:173], v220 offset:36960
	ds_read_b128 v[174:177], v219 offset:41568
	v_mfma_f32_32x32x16_bf16 v[2:17], v[138:141], v[134:137], v[2:17]
	s_waitcnt vmcnt(16)
	ds_write_b128 v218, v[82:85] offset:18432
	ds_write_b128 v218, v[86:89] offset:27648
	v_mfma_f32_32x32x16_bf16 v[18:33], v[142:145], v[146:149], v[18:33]
	ds_write_b128 v223, v[90:93] offset:18432
	ds_write_b128 v223, v[94:97] offset:27648
	v_mfma_f32_32x32x16_bf16 v[2:17], v[150:153], v[146:149], v[2:17]
	global_load_dwordx4 v[82:85], v211, s[0:1] offset:128
	global_load_dwordx4 v[86:89], v211, s[2:3] offset:128
	global_load_dwordx4 v[90:93], v215, s[4:5] offset:128
	global_load_dwordx4 v[94:97], v215, s[6:7] offset:128
	ds_read_b128 v[130:133], v219
	ds_read_b128 v[134:137], v220
	ds_read_b128 v[138:141], v219 offset:4608
	s_waitcnt lgkmcnt(11)
	v_mfma_f32_32x32x16_bf16 v[18:33], v[154:157], v[158:161], v[18:33]
	ds_read_b128 v[142:145], v219 offset:32
	ds_read_b128 v[146:149], v220 offset:32
	ds_read_b128 v[150:153], v219 offset:4640
	s_waitcnt lgkmcnt(13)
	v_mfma_f32_32x32x16_bf16 v[2:17], v[162:165], v[158:161], v[2:17]
	s_waitcnt lgkmcnt(11)
	v_mfma_f32_32x32x16_bf16 v[18:33], v[166:169], v[170:173], v[18:33]
	s_waitcnt lgkmcnt(10)
	v_mfma_f32_32x32x16_bf16 v[2:17], v[174:177], v[170:173], v[2:17]
	s_waitcnt lgkmcnt(0)
	s_barrier
	ds_read_b128 v[154:157], v219 offset:64
	ds_read_b128 v[158:161], v220 offset:64
	ds_read_b128 v[162:165], v219 offset:4672
	v_mfma_f32_32x32x16_bf16 v[18:33], v[130:133], v[134:137], v[18:33]
	ds_read_b128 v[166:169], v219 offset:96
	ds_read_b128 v[170:173], v220 offset:96
	ds_read_b128 v[174:177], v219 offset:4704
	v_mfma_f32_32x32x16_bf16 v[2:17], v[138:141], v[134:137], v[2:17]
	s_waitcnt vmcnt(12)
	ds_write_b128 v218, v[98:101] offset:36864
	ds_write_b128 v218, v[102:105] offset:46080
	v_mfma_f32_32x32x16_bf16 v[18:33], v[142:145], v[146:149], v[18:33]
	ds_write_b128 v223, v[106:109] offset:36864
	ds_write_b128 v223, v[110:113] offset:46080
	v_mfma_f32_32x32x16_bf16 v[2:17], v[150:153], v[146:149], v[2:17]
	s_mul_i32 s52, s58, 0x300
	s_add_u32 s0, s22, s52
	s_addc_u32 s1, s23, 0
	s_add_u32 s2, s0, 0xc000
	s_addc_u32 s3, s1, 0
	s_mul_i32 s52, s59, 0x300
	s_add_u32 s4, s38, s52
	s_addc_u32 s5, s39, 0
	s_add_u32 s6, s4, 0xc000
	s_addc_u32 s7, s5, 0
	global_load_dwordx4 v[98:101], v212, s[0:1]
	global_load_dwordx4 v[102:105], v212, s[2:3]
	global_load_dwordx4 v[106:109], v216, s[4:5]
	global_load_dwordx4 v[110:113], v216, s[6:7]
	ds_read_b128 v[130:133], v219 offset:18432
	ds_read_b128 v[134:137], v220 offset:18432
	ds_read_b128 v[138:141], v219 offset:23040
	s_waitcnt lgkmcnt(11)
	v_mfma_f32_32x32x16_bf16 v[18:33], v[154:157], v[158:161], v[18:33]
	ds_read_b128 v[142:145], v219 offset:18464
	ds_read_b128 v[146:149], v220 offset:18464
	ds_read_b128 v[150:153], v219 offset:23072
	s_waitcnt lgkmcnt(13)
	v_mfma_f32_32x32x16_bf16 v[2:17], v[162:165], v[158:161], v[2:17]
	s_waitcnt lgkmcnt(11)
	v_mfma_f32_32x32x16_bf16 v[18:33], v[166:169], v[170:173], v[18:33]
	s_waitcnt lgkmcnt(10)
	v_mfma_f32_32x32x16_bf16 v[2:17], v[174:177], v[170:173], v[2:17]
	s_waitcnt lgkmcnt(0)
	s_barrier
	ds_read_b128 v[154:157], v219 offset:18496
	ds_read_b128 v[158:161], v220 offset:18496
	ds_read_b128 v[162:165], v219 offset:23104
	v_mfma_f32_32x32x16_bf16 v[18:33], v[130:133], v[134:137], v[18:33]
	ds_read_b128 v[166:169], v219 offset:18528
	ds_read_b128 v[170:173], v220 offset:18528
	ds_read_b128 v[174:177], v219 offset:23136
	v_mfma_f32_32x32x16_bf16 v[2:17], v[138:141], v[134:137], v[2:17]
	s_waitcnt vmcnt(12)
	ds_write_b128 v218, v[66:69]
	ds_write_b128 v218, v[70:73] offset:9216
	v_mfma_f32_32x32x16_bf16 v[18:33], v[142:145], v[146:149], v[18:33]
	ds_write_b128 v223, v[74:77]
	ds_write_b128 v223, v[78:81] offset:9216
	v_mfma_f32_32x32x16_bf16 v[2:17], v[150:153], v[146:149], v[2:17]
	global_load_dwordx4 v[66:69], v212, s[0:1] offset:128
	global_load_dwordx4 v[70:73], v212, s[2:3] offset:128
	global_load_dwordx4 v[74:77], v216, s[4:5] offset:128
	global_load_dwordx4 v[78:81], v216, s[6:7] offset:128
	ds_read_b128 v[130:133], v219 offset:36864
	ds_read_b128 v[134:137], v220 offset:36864
	ds_read_b128 v[138:141], v219 offset:41472
	s_waitcnt lgkmcnt(11)
	v_mfma_f32_32x32x16_bf16 v[18:33], v[154:157], v[158:161], v[18:33]
	ds_read_b128 v[142:145], v219 offset:36896
	ds_read_b128 v[146:149], v220 offset:36896
	ds_read_b128 v[150:153], v219 offset:41504
	s_waitcnt lgkmcnt(13)
	v_mfma_f32_32x32x16_bf16 v[2:17], v[162:165], v[158:161], v[2:17]
	s_waitcnt lgkmcnt(11)
	v_mfma_f32_32x32x16_bf16 v[18:33], v[166:169], v[170:173], v[18:33]
	s_waitcnt lgkmcnt(10)
	v_mfma_f32_32x32x16_bf16 v[2:17], v[174:177], v[170:173], v[2:17]
	s_waitcnt lgkmcnt(0)
	s_barrier
; DI float bflo(unsigned w) { return __uint_as_float(w << 16); }
; DI float bfhi(unsigned w) { return __uint_as_float(w & 0xffff0000u); }
; DI f32x16 mfma(bf16x8 a, bf16x8 b, f32x16 c) { return __builtin_amdgcn_mfma_f32_32x32x16_bf16(a, b, c, 0, 0, 0); }
; template <bool RFA, bool RFB, class LA, class LB, class EPI>
; DI void gemm_tile2s(u16* smem, int nk, LA la, LB lb, EPI epi) {
;     ...
;   auto compute = [&](int buf) __attribute__((always_inline)) {
;     const u16* Ab = As + buf * TILE_ELEMS + (wm * 64 + lr) * LDT + lh * 8;
;     const u16* Bb = Bs + buf * TILE_ELEMS + (wn * 32 + lr) * LDT + lh * 8;
; #pragma unroll
;     for (int ks = 0; ks < 4; ++ks) {
;       const bf16x8 a0 = *(const bf16x8*)(Ab + ks * 16);
;       const bf16x8 a1 = *(const bf16x8*)(Ab + 32 * LDT + ks * 16);
;       const bf16x8 b = *(const bf16x8*)(Bb + ks * 16);
;       acc[0] = mfma(a0, b, acc[0]);
;       acc[1] = mfma(a1, b, acc[1]);
;     }
;   };
;   ld(ra0, rb0, 0);
;   if (nk > 1) ld(ra1, rb1, 1);
;   stl(ra0, rb0, 0);
;   if (nk > 2) ld(ra0, rb0, 2);
;   __syncthreads();
; #pragma unroll 1
;   for (int kt = 0; kt < nk; kt += 2) {
;     compute(0);
;     if (kt + 1 < nk) { stl(ra1, rb1, 1); if (kt + 3 < nk) ld(ra1, rb1, kt + 3); }
;     __syncthreads();
;     if (kt + 1 < nk) {
;       compute(1);
;       if (kt + 2 < nk) { stl(ra0, rb0, 0); if (kt + 4 < nk) ld(ra0, rb0, kt + 4); }
;       __syncthreads();
; template <class ACC>
; DI void merge_branch(const Prm& p, u16* smem, const u16* W, const u16* X, int ld, int bi, int n0, int m0, ACC& macc) {
;     ...
;   auto epi = [&](f32x16 (&acc)[2], int wm, int wn, int lane) __attribute__((always_inline)) {
;     const int lr = lane & 31, lh = lane >> 5;
;     const int tok = m0 + wn * 32 + lr;
; #pragma unroll
;     for (int i = 0; i < 2; ++i)
; #pragma unroll
;       for (int h2 = 0; h2 < 2; ++h2) {
;         const int n = n0 + wm * 64 + i * 32 + 16 * lh + 8 * h2;
;         const u32x4 gz = *(const u32x4*)(p.zg + (size_t)tok * 4096 + bi * 1024 + n);
; #pragma unroll
;         for (int e = 0; e < 4; ++e) {
;           macc[i][8 * h2 + 2 * e] += bflo(gz[e]) * acc[i][8 * h2 + 2 * e];
;           macc[i][8 * h2 + 2 * e + 1] += bfhi(gz[e]) * acc[i][8 * h2 + 2 * e + 1];
;         }
;       }
	ds_read_b128 v[154:157], v219 offset:36928
	ds_read_b128 v[158:161], v220 offset:36928
	ds_read_b128 v[162:165], v219 offset:41536
	v_mfma_f32_32x32x16_bf16 v[18:33], v[130:133], v[134:137], v[18:33]
	ds_read_b128 v[166:169], v219 offset:36960
	ds_read_b128 v[170:173], v220 offset:36960
	ds_read_b128 v[174:177], v219 offset:41568
	v_mfma_f32_32x32x16_bf16 v[2:17], v[138:141], v[134:137], v[2:17]
	s_waitcnt vmcnt(8)
	ds_write_b128 v218, v[82:85] offset:18432
	ds_write_b128 v218, v[86:89] offset:27648
	v_mfma_f32_32x32x16_bf16 v[18:33], v[142:145], v[146:149], v[18:33]
	ds_write_b128 v223, v[90:93] offset:18432
	ds_write_b128 v223, v[94:97] offset:27648
	v_mfma_f32_32x32x16_bf16 v[2:17], v[150:153], v[146:149], v[2:17]
	global_load_dwordx4 v[82:85], v212, s[0:1] offset:256
	global_load_dwordx4 v[86:89], v212, s[2:3] offset:256
	global_load_dwordx4 v[90:93], v216, s[4:5] offset:256
	global_load_dwordx4 v[94:97], v216, s[6:7] offset:256
	ds_read_b128 v[130:133], v219
	ds_read_b128 v[134:137], v220
	ds_read_b128 v[138:141], v219 offset:4608
	s_waitcnt lgkmcnt(11)
	v_mfma_f32_32x32x16_bf16 v[18:33], v[154:157], v[158:161], v[18:33]
	ds_read_b128 v[142:145], v219 offset:32
	ds_read_b128 v[146:149], v220 offset:32
	ds_read_b128 v[150:153], v219 offset:4640
	s_waitcnt lgkmcnt(13)
	v_mfma_f32_32x32x16_bf16 v[2:17], v[162:165], v[158:161], v[2:17]
	s_waitcnt lgkmcnt(11)
	v_mfma_f32_32x32x16_bf16 v[18:33], v[166:169], v[170:173], v[18:33]
	s_waitcnt lgkmcnt(10)
	v_mfma_f32_32x32x16_bf16 v[2:17], v[174:177], v[170:173], v[2:17]
	s_waitcnt vmcnt(28)
	s_nop 15
	v_lshlrev_b32_e32 v226, 16, v178
	v_and_b32_e32 v227, 0xffff0000, v178
	v_pk_mul_f32 v[34:35], v[226:227], v[18:19]
	v_lshlrev_b32_e32 v228, 16, v179
	v_and_b32_e32 v229, 0xffff0000, v179
	v_pk_mul_f32 v[36:37], v[228:229], v[20:21]
	v_lshlrev_b32_e32 v234, 16, v180
	v_and_b32_e32 v235, 0xffff0000, v180
	v_pk_mul_f32 v[38:39], v[234:235], v[22:23]
	v_lshlrev_b32_e32 v236, 16, v181
	v_and_b32_e32 v237, 0xffff0000, v181
	v_pk_mul_f32 v[40:41], v[236:237], v[24:25]
	v_lshlrev_b32_e32 v226, 16, v182
	v_and_b32_e32 v227, 0xffff0000, v182
	v_pk_mul_f32 v[42:43], v[226:227], v[26:27]
	v_lshlrev_b32_e32 v228, 16, v183
	v_and_b32_e32 v229, 0xffff0000, v183
	v_pk_mul_f32 v[44:45], v[228:229], v[28:29]
	v_lshlrev_b32_e32 v234, 16, v184
	v_and_b32_e32 v235, 0xffff0000, v184
	v_pk_mul_f32 v[46:47], v[234:235], v[30:31]
	v_lshlrev_b32_e32 v236, 16, v185
	v_and_b32_e32 v237, 0xffff0000, v185
	v_pk_mul_f32 v[48:49], v[236:237], v[32:33]
	v_lshlrev_b32_e32 v226, 16, v186
	v_and_b32_e32 v227, 0xffff0000, v186
	v_pk_mul_f32 v[50:51], v[226:227], v[2:3]
	v_lshlrev_b32_e32 v228, 16, v187
	v_and_b32_e32 v229, 0xffff0000, v187
	v_pk_mul_f32 v[52:53], v[228:229], v[4:5]
	v_lshlrev_b32_e32 v234, 16, v188
	v_and_b32_e32 v235, 0xffff0000, v188
	v_pk_mul_f32 v[54:55], v[234:235], v[6:7]
	v_lshlrev_b32_e32 v236, 16, v189
	v_and_b32_e32 v237, 0xffff0000, v189
	v_pk_mul_f32 v[56:57], v[236:237], v[8:9]
	v_lshlrev_b32_e32 v226, 16, v190
	v_and_b32_e32 v227, 0xffff0000, v190
	v_pk_mul_f32 v[58:59], v[226:227], v[10:11]
	v_lshlrev_b32_e32 v228, 16, v191
	v_and_b32_e32 v229, 0xffff0000, v191
	v_pk_mul_f32 v[60:61], v[228:229], v[12:13]
	v_lshlrev_b32_e32 v234, 16, v192
	v_and_b32_e32 v235, 0xffff0000, v192
	v_pk_mul_f32 v[62:63], v[234:235], v[14:15]
	v_lshlrev_b32_e32 v236, 16, v193
	v_and_b32_e32 v237, 0xffff0000, v193
	v_pk_mul_f32 v[64:65], v[236:237], v[16:17]
	s_waitcnt lgkmcnt(0)
	s_barrier
	ds_read_b128 v[154:157], v219 offset:64
	ds_read_b128 v[158:161], v220 offset:64
	ds_read_b128 v[162:165], v219 offset:4672
	v_mfma_f32_32x32x16_bf16 v[18:33], v[130:133], v[134:137], 0
	ds_read_b128 v[166:169], v219 offset:96
	ds_read_b128 v[170:173], v220 offset:96
	ds_read_b128 v[174:177], v219 offset:4704
	v_mfma_f32_32x32x16_bf16 v[2:17], v[138:141], v[134:137], 0
	s_waitcnt vmcnt(8)
	ds_write_b128 v218, v[98:101] offset:36864
	ds_write_b128 v218, v[102:105] offset:46080
	v_mfma_f32_32x32x16_bf16 v[18:33], v[142:145], v[146:149], v[18:33]
	ds_write_b128 v223, v[106:109] offset:36864
	ds_write_b128 v223, v[110:113] offset:46080
	v_mfma_f32_32x32x16_bf16 v[2:17], v[150:153], v[146:149], v[2:17]
	global_load_dwordx4 v[98:101], v212, s[0:1] offset:384
	global_load_dwordx4 v[102:105], v212, s[2:3] offset:384
	global_load_dwordx4 v[106:109], v216, s[4:5] offset:384
	global_load_dwordx4 v[110:113], v216, s[6:7] offset:384
	global_load_dwordx4 v[178:181], v221, s[10:11]
	global_load_dwordx4 v[182:185], v221, s[10:11] offset:16
	global_load_dwordx4 v[186:189], v221, s[10:11] offset:64
	global_load_dwordx4 v[190:193], v221, s[10:11] offset:80
	ds_read_b128 v[130:133], v219 offset:18432
	ds_read_b128 v[134:137], v220 offset:18432
	ds_read_b128 v[138:141], v219 offset:23040
	s_waitcnt lgkmcnt(11)
	v_mfma_f32_32x32x16_bf16 v[18:33], v[154:157], v[158:161], v[18:33]
	ds_read_b128 v[142:145], v219 offset:18464
	ds_read_b128 v[146:149], v220 offset:18464
	ds_read_b128 v[150:153], v219 offset:23072
	s_waitcnt lgkmcnt(13)
	v_mfma_f32_32x32x16_bf16 v[2:17], v[162:165], v[158:161], v[2:17]
	s_waitcnt lgkmcnt(11)
	v_mfma_f32_32x32x16_bf16 v[18:33], v[166:169], v[170:173], v[18:33]
	s_waitcnt lgkmcnt(10)
	v_mfma_f32_32x32x16_bf16 v[2:17], v[174:177], v[170:173], v[2:17]
	s_waitcnt lgkmcnt(0)
	s_barrier
; DI float bflo(unsigned w) { return __uint_as_float(w << 16); }
; DI float bfhi(unsigned w) { return __uint_as_float(w & 0xffff0000u); }
; DI f32x16 mfma(bf16x8 a, bf16x8 b, f32x16 c) { return __builtin_amdgcn_mfma_f32_32x32x16_bf16(a, b, c, 0, 0, 0); }
; template <bool RFA, bool RFB, class LA, class LB, class EPI>
; DI void gemm_tile2s(u16* smem, int nk, LA la, LB lb, EPI epi) {
;     ...
;   auto compute = [&](int buf) __attribute__((always_inline)) {
;     const u16* Ab = As + buf * TILE_ELEMS + (wm * 64 + lr) * LDT + lh * 8;
;     const u16* Bb = Bs + buf * TILE_ELEMS + (wn * 32 + lr) * LDT + lh * 8;
; #pragma unroll
;     for (int ks = 0; ks < 4; ++ks) {
;       const bf16x8 a0 = *(const bf16x8*)(Ab + ks * 16);
;       const bf16x8 a1 = *(const bf16x8*)(Ab + 32 * LDT + ks * 16);
;       const bf16x8 b = *(const bf16x8*)(Bb + ks * 16);
;       acc[0] = mfma(a0, b, acc[0]);
;       acc[1] = mfma(a1, b, acc[1]);
;     }
;   };
;   ld(ra0, rb0, 0);
;   if (nk > 1) ld(ra1, rb1, 1);
;   stl(ra0, rb0, 0);
;   if (nk > 2) ld(ra0, rb0, 2);
;   __syncthreads();
; #pragma unroll 1
;   for (int kt = 0; kt < nk; kt += 2) {
;     compute(0);
;     if (kt + 1 < nk) { stl(ra1, rb1, 1); if (kt + 3 < nk) ld(ra1, rb1, kt + 3); }
;     __syncthreads();
;     if (kt + 1 < nk) {
;       compute(1);
;       if (kt + 2 < nk) { stl(ra0, rb0, 0); if (kt + 4 < nk) ld(ra0, rb0, kt + 4); }
;       __syncthreads();
; template <class ACC>
; DI void merge_branch(const Prm& p, u16* smem, const u16* W, const u16* X, int ld, int bi, int n0, int m0, ACC& macc) {
;     ...
;   auto epi = [&](f32x16 (&acc)[2], int wm, int wn, int lane) __attribute__((always_inline)) {
;     const int lr = lane & 31, lh = lane >> 5;
;     const int tok = m0 + wn * 32 + lr;
; #pragma unroll
;     for (int i = 0; i < 2; ++i)
; #pragma unroll
;       for (int h2 = 0; h2 < 2; ++h2) {
;         const int n = n0 + wm * 64 + i * 32 + 16 * lh + 8 * h2;
;         const u32x4 gz = *(const u32x4*)(p.zg + (size_t)tok * 4096 + bi * 1024 + n);
; #pragma unroll
;         for (int e = 0; e < 4; ++e) {
;           macc[i][8 * h2 + 2 * e] += bflo(gz[e]) * acc[i][8 * h2 + 2 * e];
;           macc[i][8 * h2 + 2 * e + 1] += bfhi(gz[e]) * acc[i][8 * h2 + 2 * e + 1];
;         }
;       }
	ds_read_b128 v[154:157], v219 offset:18496
	ds_read_b128 v[158:161], v220 offset:18496
	ds_read_b128 v[162:165], v219 offset:23104
	v_mfma_f32_32x32x16_bf16 v[18:33], v[130:133], v[134:137], v[18:33]
	ds_read_b128 v[166:169], v219 offset:18528
	ds_read_b128 v[170:173], v220 offset:18528
	ds_read_b128 v[174:177], v219 offset:23136
	v_mfma_f32_32x32x16_bf16 v[2:17], v[138:141], v[134:137], v[2:17]
	s_waitcnt vmcnt(12)
	ds_write_b128 v218, v[66:69]
	ds_write_b128 v218, v[70:73] offset:9216
	v_mfma_f32_32x32x16_bf16 v[18:33], v[142:145], v[146:149], v[18:33]
	ds_write_b128 v223, v[74:77]
	ds_write_b128 v223, v[78:81] offset:9216
	v_mfma_f32_32x32x16_bf16 v[2:17], v[150:153], v[146:149], v[2:17]
	global_load_dwordx4 v[66:69], v212, s[0:1] offset:512
	global_load_dwordx4 v[70:73], v212, s[2:3] offset:512
	global_load_dwordx4 v[74:77], v216, s[4:5] offset:512
	global_load_dwordx4 v[78:81], v216, s[6:7] offset:512
	ds_read_b128 v[130:133], v219 offset:36864
	ds_read_b128 v[134:137], v220 offset:36864
	ds_read_b128 v[138:141], v219 offset:41472
	s_waitcnt lgkmcnt(11)
	v_mfma_f32_32x32x16_bf16 v[18:33], v[154:157], v[158:161], v[18:33]
	ds_read_b128 v[142:145], v219 offset:36896
	ds_read_b128 v[146:149], v220 offset:36896
	ds_read_b128 v[150:153], v219 offset:41504
	s_waitcnt lgkmcnt(13)
	v_mfma_f32_32x32x16_bf16 v[2:17], v[162:165], v[158:161], v[2:17]
	s_waitcnt lgkmcnt(11)
	v_mfma_f32_32x32x16_bf16 v[18:33], v[166:169], v[170:173], v[18:33]
	s_waitcnt lgkmcnt(10)
	v_mfma_f32_32x32x16_bf16 v[2:17], v[174:177], v[170:173], v[2:17]
	s_waitcnt vmcnt(28)
	s_nop 15
	v_lshlrev_b32_e32 v226, 16, v194
	v_and_b32_e32 v227, 0xffff0000, v194
	v_pk_fma_f32 v[34:35], v[226:227], v[18:19], v[34:35]
	v_lshlrev_b32_e32 v228, 16, v195
	v_and_b32_e32 v229, 0xffff0000, v195
	v_pk_fma_f32 v[36:37], v[228:229], v[20:21], v[36:37]
	v_lshlrev_b32_e32 v234, 16, v196
	v_and_b32_e32 v235, 0xffff0000, v196
	v_pk_fma_f32 v[38:39], v[234:235], v[22:23], v[38:39]
	v_lshlrev_b32_e32 v236, 16, v197
	v_and_b32_e32 v237, 0xffff0000, v197
	v_pk_fma_f32 v[40:41], v[236:237], v[24:25], v[40:41]
	v_lshlrev_b32_e32 v226, 16, v198
	v_and_b32_e32 v227, 0xffff0000, v198
	v_pk_fma_f32 v[42:43], v[226:227], v[26:27], v[42:43]
	v_lshlrev_b32_e32 v228, 16, v199
	v_and_b32_e32 v229, 0xffff0000, v199
	v_pk_fma_f32 v[44:45], v[228:229], v[28:29], v[44:45]
	v_lshlrev_b32_e32 v234, 16, v200
	v_and_b32_e32 v235, 0xffff0000, v200
	v_pk_fma_f32 v[46:47], v[234:235], v[30:31], v[46:47]
	v_lshlrev_b32_e32 v236, 16, v201
	v_and_b32_e32 v237, 0xffff0000, v201
	v_pk_fma_f32 v[48:49], v[236:237], v[32:33], v[48:49]
	v_lshlrev_b32_e32 v226, 16, v202
	v_and_b32_e32 v227, 0xffff0000, v202
	v_pk_fma_f32 v[50:51], v[226:227], v[2:3], v[50:51]
	v_lshlrev_b32_e32 v228, 16, v203
	v_and_b32_e32 v229, 0xffff0000, v203
	v_pk_fma_f32 v[52:53], v[228:229], v[4:5], v[52:53]
	v_lshlrev_b32_e32 v234, 16, v204
	v_and_b32_e32 v235, 0xffff0000, v204
	v_pk_fma_f32 v[54:55], v[234:235], v[6:7], v[54:55]
	v_lshlrev_b32_e32 v236, 16, v205
	v_and_b32_e32 v237, 0xffff0000, v205
	v_pk_fma_f32 v[56:57], v[236:237], v[8:9], v[56:57]
	v_lshlrev_b32_e32 v226, 16, v206
	v_and_b32_e32 v227, 0xffff0000, v206
	v_pk_fma_f32 v[58:59], v[226:227], v[10:11], v[58:59]
	v_lshlrev_b32_e32 v228, 16, v207
	v_and_b32_e32 v229, 0xffff0000, v207
	v_pk_fma_f32 v[60:61], v[228:229], v[12:13], v[60:61]
	v_lshlrev_b32_e32 v234, 16, v208
	v_and_b32_e32 v235, 0xffff0000, v208
	v_pk_fma_f32 v[62:63], v[234:235], v[14:15], v[62:63]
	v_lshlrev_b32_e32 v236, 16, v209
	v_and_b32_e32 v237, 0xffff0000, v209
	v_pk_fma_f32 v[64:65], v[236:237], v[16:17], v[64:65]
	s_waitcnt lgkmcnt(0)
	s_barrier
	ds_read_b128 v[154:157], v219 offset:36928
	ds_read_b128 v[158:161], v220 offset:36928
	ds_read_b128 v[162:165], v219 offset:41536
	v_mfma_f32_32x32x16_bf16 v[18:33], v[130:133], v[134:137], 0
	ds_read_b128 v[166:169], v219 offset:36960
	ds_read_b128 v[170:173], v220 offset:36960
	ds_read_b128 v[174:177], v219 offset:41568
	v_mfma_f32_32x32x16_bf16 v[2:17], v[138:141], v[134:137], 0
	s_waitcnt vmcnt(12)
	ds_write_b128 v218, v[82:85] offset:18432
	ds_write_b128 v218, v[86:89] offset:27648
	v_mfma_f32_32x32x16_bf16 v[18:33], v[142:145], v[146:149], v[18:33]
	ds_write_b128 v223, v[90:93] offset:18432
	ds_write_b128 v223, v[94:97] offset:27648
	v_mfma_f32_32x32x16_bf16 v[2:17], v[150:153], v[146:149], v[2:17]
	global_load_dwordx4 v[82:85], v212, s[0:1] offset:640
	global_load_dwordx4 v[86:89], v212, s[2:3] offset:640
	global_load_dwordx4 v[90:93], v216, s[4:5] offset:640
	global_load_dwordx4 v[94:97], v216, s[6:7] offset:640
	global_load_dwordx4 v[194:197], v221, s[10:11] offset:2048
	global_load_dwordx4 v[198:201], v221, s[10:11] offset:2064
	global_load_dwordx4 v[202:205], v221, s[10:11] offset:2112
	global_load_dwordx4 v[206:209], v221, s[10:11] offset:2128
	ds_read_b128 v[130:133], v219
	ds_read_b128 v[134:137], v220
	ds_read_b128 v[138:141], v219 offset:4608
	s_waitcnt lgkmcnt(11)
	v_mfma_f32_32x32x16_bf16 v[18:33], v[154:157], v[158:161], v[18:33]
	ds_read_b128 v[142:145], v219 offset:32
	ds_read_b128 v[146:149], v220 offset:32
	ds_read_b128 v[150:153], v219 offset:4640
	s_waitcnt lgkmcnt(13)
	v_mfma_f32_32x32x16_bf16 v[2:17], v[162:165], v[158:161], v[2:17]
	s_waitcnt lgkmcnt(11)
	v_mfma_f32_32x32x16_bf16 v[18:33], v[166:169], v[170:173], v[18:33]
	s_waitcnt lgkmcnt(10)
	v_mfma_f32_32x32x16_bf16 v[2:17], v[174:177], v[170:173], v[2:17]
	s_waitcnt lgkmcnt(0)
	s_barrier
; DI f32x16 mfma(bf16x8 a, bf16x8 b, f32x16 c) { return __builtin_amdgcn_mfma_f32_32x32x16_bf16(a, b, c, 0, 0, 0); }
; template <bool RFA, bool RFB, class LA, class LB, class EPI>
; DI void gemm_tile2s(u16* smem, int nk, LA la, LB lb, EPI epi) {
;     ...
;   auto compute = [&](int buf) __attribute__((always_inline)) {
;     const u16* Ab = As + buf * TILE_ELEMS + (wm * 64 + lr) * LDT + lh * 8;
;     const u16* Bb = Bs + buf * TILE_ELEMS + (wn * 32 + lr) * LDT + lh * 8;
; #pragma unroll
;     for (int ks = 0; ks < 4; ++ks) {
;       const bf16x8 a0 = *(const bf16x8*)(Ab + ks * 16);
;       const bf16x8 a1 = *(const bf16x8*)(Ab + 32 * LDT + ks * 16);
;       const bf16x8 b = *(const bf16x8*)(Bb + ks * 16);
;       acc[0] = mfma(a0, b, acc[0]);
;       acc[1] = mfma(a1, b, acc[1]);
;     }
;   };
;   ld(ra0, rb0, 0);
;   if (nk > 1) ld(ra1, rb1, 1);
;   stl(ra0, rb0, 0);
;   if (nk > 2) ld(ra0, rb0, 2);
;   __syncthreads();
; #pragma unroll 1
;   for (int kt = 0; kt < nk; kt += 2) {
;     compute(0);
;     if (kt + 1 < nk) { stl(ra1, rb1, 1); if (kt + 3 < nk) ld(ra1, rb1, kt + 3); }
;     __syncthreads();
;     if (kt + 1 < nk) {
;       compute(1);
;       if (kt + 2 < nk) { stl(ra0, rb0, 0); if (kt + 4 < nk) ld(ra0, rb0, kt + 4); }
;       __syncthreads();
; template <class ACC>
; DI void merge_branch(const Prm& p, u16* smem, const u16* W, const u16* X, int ld, int bi, int n0, int m0, ACC& macc) {
;   auto la = [&](int row, int k) __attribute__((always_inline)) { return *(const u32x4*)(W + (size_t)(n0 + (row & ~31) + perm_m(row & 31)) * ld + k); };
;   auto lb = [&](int row, int k) __attribute__((always_inline)) { return *(const u32x4*)(X + (size_t)(m0 + row) * ld + k); };
	ds_read_b128 v[154:157], v219 offset:64
	ds_read_b128 v[158:161], v220 offset:64
	ds_read_b128 v[162:165], v219 offset:4672
	v_mfma_f32_32x32x16_bf16 v[18:33], v[130:133], v[134:137], v[18:33]
	ds_read_b128 v[166:169], v219 offset:96
	ds_read_b128 v[170:173], v220 offset:96
	ds_read_b128 v[174:177], v219 offset:4704
	v_mfma_f32_32x32x16_bf16 v[2:17], v[138:141], v[134:137], v[2:17]
	s_waitcnt vmcnt(16)
	ds_write_b128 v218, v[98:101] offset:36864
	ds_write_b128 v218, v[102:105] offset:46080
	v_mfma_f32_32x32x16_bf16 v[18:33], v[142:145], v[146:149], v[18:33]
	ds_write_b128 v223, v[106:109] offset:36864
	ds_write_b128 v223, v[110:113] offset:46080
	v_mfma_f32_32x32x16_bf16 v[2:17], v[150:153], v[146:149], v[2:17]
	s_mul_i32 s52, s58, 0x200
	s_add_u32 s0, s44, s52
	s_addc_u32 s1, s45, 0
	s_add_u32 s2, s0, 0x8000
	s_addc_u32 s3, s1, 0
	s_mul_i32 s52, s59, 0x200
	s_add_u32 s4, s40, s52
	s_addc_u32 s5, s41, 0
	s_add_u32 s6, s4, 0x8000
	s_addc_u32 s7, s5, 0
	global_load_dwordx4 v[98:101], v213, s[0:1]
	global_load_dwordx4 v[102:105], v213, s[2:3]
	global_load_dwordx4 v[106:109], v217, s[4:5]
	global_load_dwordx4 v[110:113], v217, s[6:7]
	ds_read_b128 v[130:133], v219 offset:18432
	ds_read_b128 v[134:137], v220 offset:18432
	ds_read_b128 v[138:141], v219 offset:23040
	s_waitcnt lgkmcnt(11)
	v_mfma_f32_32x32x16_bf16 v[18:33], v[154:157], v[158:161], v[18:33]
	ds_read_b128 v[142:145], v219 offset:18464
	ds_read_b128 v[146:149], v220 offset:18464
	ds_read_b128 v[150:153], v219 offset:23072
	s_waitcnt lgkmcnt(13)
	v_mfma_f32_32x32x16_bf16 v[2:17], v[162:165], v[158:161], v[2:17]
	s_waitcnt lgkmcnt(11)
	v_mfma_f32_32x32x16_bf16 v[18:33], v[166:169], v[170:173], v[18:33]
	s_waitcnt lgkmcnt(10)
	v_mfma_f32_32x32x16_bf16 v[2:17], v[174:177], v[170:173], v[2:17]
	s_waitcnt lgkmcnt(0)
	s_barrier
	ds_read_b128 v[154:157], v219 offset:18496
	ds_read_b128 v[158:161], v220 offset:18496
	ds_read_b128 v[162:165], v219 offset:23104
	v_mfma_f32_32x32x16_bf16 v[18:33], v[130:133], v[134:137], v[18:33]
	ds_read_b128 v[166:169], v219 offset:18528
	ds_read_b128 v[170:173], v220 offset:18528
	ds_read_b128 v[174:177], v219 offset:23136
	v_mfma_f32_32x32x16_bf16 v[2:17], v[138:141], v[134:137], v[2:17]
	s_waitcnt vmcnt(12)
	ds_write_b128 v218, v[66:69]
	ds_write_b128 v218, v[70:73] offset:9216
	v_mfma_f32_32x32x16_bf16 v[18:33], v[142:145], v[146:149], v[18:33]
	ds_write_b128 v223, v[74:77]
	ds_write_b128 v223, v[78:81] offset:9216
	v_mfma_f32_32x32x16_bf16 v[2:17], v[150:153], v[146:149], v[2:17]
	global_load_dwordx4 v[66:69], v213, s[0:1] offset:128
	global_load_dwordx4 v[70:73], v213, s[2:3] offset:128
	global_load_dwordx4 v[74:77], v217, s[4:5] offset:128
	global_load_dwordx4 v[78:81], v217, s[6:7] offset:128
	ds_read_b128 v[130:133], v219 offset:36864
	ds_read_b128 v[134:137], v220 offset:36864
	ds_read_b128 v[138:141], v219 offset:41472
	s_waitcnt lgkmcnt(11)
	v_mfma_f32_32x32x16_bf16 v[18:33], v[154:157], v[158:161], v[18:33]
	ds_read_b128 v[142:145], v219 offset:36896
	ds_read_b128 v[146:149], v220 offset:36896
	ds_read_b128 v[150:153], v219 offset:41504
	s_waitcnt lgkmcnt(13)
	v_mfma_f32_32x32x16_bf16 v[2:17], v[162:165], v[158:161], v[2:17]
	s_waitcnt lgkmcnt(11)
	v_mfma_f32_32x32x16_bf16 v[18:33], v[166:169], v[170:173], v[18:33]
	s_waitcnt lgkmcnt(10)
	v_mfma_f32_32x32x16_bf16 v[2:17], v[174:177], v[170:173], v[2:17]
	s_waitcnt lgkmcnt(0)
	s_barrier
	ds_read_b128 v[154:157], v219 offset:36928
	ds_read_b128 v[158:161], v220 offset:36928
	ds_read_b128 v[162:165], v219 offset:41536
	v_mfma_f32_32x32x16_bf16 v[18:33], v[130:133], v[134:137], v[18:33]
	ds_read_b128 v[166:169], v219 offset:36960
	ds_read_b128 v[170:173], v220 offset:36960
	ds_read_b128 v[174:177], v219 offset:41568
	v_mfma_f32_32x32x16_bf16 v[2:17], v[138:141], v[134:137], v[2:17]
	s_waitcnt vmcnt(12)
	ds_write_b128 v218, v[82:85] offset:18432
	ds_write_b128 v218, v[86:89] offset:27648
	v_mfma_f32_32x32x16_bf16 v[18:33], v[142:145], v[146:149], v[18:33]
	ds_write_b128 v223, v[90:93] offset:18432
	ds_write_b128 v223, v[94:97] offset:27648
	v_mfma_f32_32x32x16_bf16 v[2:17], v[150:153], v[146:149], v[2:17]
	global_load_dwordx4 v[82:85], v213, s[0:1] offset:256
	global_load_dwordx4 v[86:89], v213, s[2:3] offset:256
	global_load_dwordx4 v[90:93], v217, s[4:5] offset:256
	global_load_dwordx4 v[94:97], v217, s[6:7] offset:256
	ds_read_b128 v[130:133], v219
	ds_read_b128 v[134:137], v220
	ds_read_b128 v[138:141], v219 offset:4608
	s_waitcnt lgkmcnt(11)
	v_mfma_f32_32x32x16_bf16 v[18:33], v[154:157], v[158:161], v[18:33]
	ds_read_b128 v[142:145], v219 offset:32
	ds_read_b128 v[146:149], v220 offset:32
	ds_read_b128 v[150:153], v219 offset:4640
	s_waitcnt lgkmcnt(13)
	v_mfma_f32_32x32x16_bf16 v[2:17], v[162:165], v[158:161], v[2:17]
	s_waitcnt lgkmcnt(11)
	v_mfma_f32_32x32x16_bf16 v[18:33], v[166:169], v[170:173], v[18:33]
	s_waitcnt lgkmcnt(10)
	v_mfma_f32_32x32x16_bf16 v[2:17], v[174:177], v[170:173], v[2:17]
	s_waitcnt lgkmcnt(0)
	s_barrier
; DI float bflo(unsigned w) { return __uint_as_float(w << 16); }
; DI float bfhi(unsigned w) { return __uint_as_float(w & 0xffff0000u); }
; template <bool RFA, bool RFB, class LA, class LB, class EPI>
; DI void gemm_tile2s(u16* smem, int nk, LA la, LB lb, EPI epi) {
;     ...
;   auto compute = [&](int buf) __attribute__((always_inline)) {
;     const u16* Ab = As + buf * TILE_ELEMS + (wm * 64 + lr) * LDT + lh * 8;
;     const u16* Bb = Bs + buf * TILE_ELEMS + (wn * 32 + lr) * LDT + lh * 8;
; #pragma unroll
;     for (int ks = 0; ks < 4; ++ks) {
;       const bf16x8 a0 = *(const bf16x8*)(Ab + ks * 16);
;       const bf16x8 a1 = *(const bf16x8*)(Ab + 32 * LDT + ks * 16);
;       const bf16x8 b = *(const bf16x8*)(Bb + ks * 16);
;       acc[0] = mfma(a0, b, acc[0]);
;       acc[1] = mfma(a1, b, acc[1]);
;     }
;   };
;   ld(ra0, rb0, 0);
;   if (nk > 1) ld(ra1, rb1, 1);
;   stl(ra0, rb0, 0);
;   if (nk > 2) ld(ra0, rb0, 2);
;   __syncthreads();
; #pragma unroll 1
;   for (int kt = 0; kt < nk; kt += 2) {
;     compute(0);
;     if (kt + 1 < nk) { stl(ra1, rb1, 1); if (kt + 3 < nk) ld(ra1, rb1, kt + 3); }
;     __syncthreads();
;     if (kt + 1 < nk) {
;       compute(1);
;       if (kt + 2 < nk) { stl(ra0, rb0, 0); if (kt + 4 < nk) ld(ra0, rb0, kt + 4); }
;       __syncthreads();
; template <class ACC>
; DI void merge_branch(const Prm& p, u16* smem, const u16* W, const u16* X, int ld, int bi, int n0, int m0, ACC& macc) {
;     ...
;   auto epi = [&](f32x16 (&acc)[2], int wm, int wn, int lane) __attribute__((always_inline)) {
;     const int lr = lane & 31, lh = lane >> 5;
;     const int tok = m0 + wn * 32 + lr;
; #pragma unroll
;     for (int i = 0; i < 2; ++i)
; #pragma unroll
;       for (int h2 = 0; h2 < 2; ++h2) {
;         const int n = n0 + wm * 64 + i * 32 + 16 * lh + 8 * h2;
;         const u32x4 gz = *(const u32x4*)(p.zg + (size_t)tok * 4096 + bi * 1024 + n);
; #pragma unroll
;         for (int e = 0; e < 4; ++e) {
;           macc[i][8 * h2 + 2 * e] += bflo(gz[e]) * acc[i][8 * h2 + 2 * e];
;           macc[i][8 * h2 + 2 * e + 1] += bfhi(gz[e]) * acc[i][8 * h2 + 2 * e + 1];
;         }
;       }
; DI void phase_merge(const Prm& p, u16* smem, int l, int& base) {
;   TASK_LOOP(t, 8 * 128, base) {
;     const int tn = t & 7, tm = t >> 3, n0 = tn * 128, m0 = tm * 128;
	ds_read_b128 v[154:157], v219 offset:64
	ds_read_b128 v[158:161], v220 offset:64
	ds_read_b128 v[162:165], v219 offset:4672
	v_mfma_f32_32x32x16_bf16 v[18:33], v[130:133], v[134:137], v[18:33]
	ds_read_b128 v[166:169], v219 offset:96
	ds_read_b128 v[170:173], v220 offset:96
	ds_read_b128 v[174:177], v219 offset:4704
	v_mfma_f32_32x32x16_bf16 v[2:17], v[138:141], v[134:137], v[2:17]
	s_waitcnt vmcnt(8)
	ds_write_b128 v218, v[98:101] offset:36864
	ds_write_b128 v218, v[102:105] offset:46080
	v_mfma_f32_32x32x16_bf16 v[18:33], v[142:145], v[146:149], v[18:33]
	ds_write_b128 v223, v[106:109] offset:36864
	ds_write_b128 v223, v[110:113] offset:46080
	v_mfma_f32_32x32x16_bf16 v[2:17], v[150:153], v[146:149], v[2:17]
	global_load_dwordx4 v[98:101], v213, s[0:1] offset:384
	global_load_dwordx4 v[102:105], v213, s[2:3] offset:384
	global_load_dwordx4 v[106:109], v217, s[4:5] offset:384
	global_load_dwordx4 v[110:113], v217, s[6:7] offset:384
	ds_read_b128 v[130:133], v219 offset:18432
	ds_read_b128 v[134:137], v220 offset:18432
	ds_read_b128 v[138:141], v219 offset:23040
	s_waitcnt lgkmcnt(11)
	v_mfma_f32_32x32x16_bf16 v[18:33], v[154:157], v[158:161], v[18:33]
	ds_read_b128 v[142:145], v219 offset:18464
	ds_read_b128 v[146:149], v220 offset:18464
	ds_read_b128 v[150:153], v219 offset:23072
	s_waitcnt lgkmcnt(13)
	v_mfma_f32_32x32x16_bf16 v[2:17], v[162:165], v[158:161], v[2:17]
	s_waitcnt lgkmcnt(11)
	v_mfma_f32_32x32x16_bf16 v[18:33], v[166:169], v[170:173], v[18:33]
	s_waitcnt lgkmcnt(10)
	v_mfma_f32_32x32x16_bf16 v[2:17], v[174:177], v[170:173], v[2:17]
	s_waitcnt lgkmcnt(0)
	s_barrier
	ds_read_b128 v[154:157], v219 offset:18496
	ds_read_b128 v[158:161], v220 offset:18496
	ds_read_b128 v[162:165], v219 offset:23104
	v_mfma_f32_32x32x16_bf16 v[18:33], v[130:133], v[134:137], v[18:33]
	ds_read_b128 v[166:169], v219 offset:18528
	ds_read_b128 v[170:173], v220 offset:18528
	ds_read_b128 v[174:177], v219 offset:23136
	v_mfma_f32_32x32x16_bf16 v[2:17], v[138:141], v[134:137], v[2:17]
	s_waitcnt vmcnt(8)
	ds_write_b128 v218, v[66:69]
	ds_write_b128 v218, v[70:73] offset:9216
	v_mfma_f32_32x32x16_bf16 v[18:33], v[142:145], v[146:149], v[18:33]
	ds_write_b128 v223, v[74:77]
	ds_write_b128 v223, v[78:81] offset:9216
	v_mfma_f32_32x32x16_bf16 v[2:17], v[150:153], v[146:149], v[2:17]
	s_add_i32 s50, s31, s30
	s_cmpk_lt_i32 s50, 0x400
	s_cselect_b32 s50, s50, s31
	s_and_b32 s60, s50, 7
	s_lshl_b32 s60, s60, 7
	s_lshr_b32 s61, s50, 3
	s_lshl_b32 s61, s61, 7
	s_mul_i32 s52, s60, 0x600
	s_add_u32 s0, s16, s52
	s_addc_u32 s1, s17, 0
	s_add_u32 s2, s0, 0x18000
	s_addc_u32 s3, s1, 0
	s_mul_i32 s52, s61, 0x600
	s_add_u32 s4, s14, s52
	s_addc_u32 s5, s15, 0
	s_add_u32 s6, s4, 0x18000
	s_addc_u32 s7, s5, 0
	global_load_dwordx4 v[66:69], v210, s[0:1]
	global_load_dwordx4 v[70:73], v210, s[2:3]
	global_load_dwordx4 v[74:77], v214, s[4:5]
	global_load_dwordx4 v[78:81], v214, s[6:7]
	ds_read_b128 v[130:133], v219 offset:36864
	ds_read_b128 v[134:137], v220 offset:36864
	ds_read_b128 v[138:141], v219 offset:41472
	s_waitcnt lgkmcnt(11)
	v_mfma_f32_32x32x16_bf16 v[18:33], v[154:157], v[158:161], v[18:33]
	ds_read_b128 v[142:145], v219 offset:36896
	ds_read_b128 v[146:149], v220 offset:36896
	ds_read_b128 v[150:153], v219 offset:41504
	s_waitcnt lgkmcnt(13)
	v_mfma_f32_32x32x16_bf16 v[2:17], v[162:165], v[158:161], v[2:17]
	s_waitcnt lgkmcnt(11)
	v_mfma_f32_32x32x16_bf16 v[18:33], v[166:169], v[170:173], v[18:33]
	s_waitcnt lgkmcnt(10)
	v_mfma_f32_32x32x16_bf16 v[2:17], v[174:177], v[170:173], v[2:17]
	s_waitcnt vmcnt(32)
	s_nop 15
	v_lshlrev_b32_e32 v226, 16, v178
	v_and_b32_e32 v227, 0xffff0000, v178
	v_pk_fma_f32 v[34:35], v[226:227], v[18:19], v[34:35]
	v_lshlrev_b32_e32 v228, 16, v179
	v_and_b32_e32 v229, 0xffff0000, v179
	v_pk_fma_f32 v[36:37], v[228:229], v[20:21], v[36:37]
	v_lshlrev_b32_e32 v234, 16, v180
	v_and_b32_e32 v235, 0xffff0000, v180
	v_pk_fma_f32 v[38:39], v[234:235], v[22:23], v[38:39]
	v_lshlrev_b32_e32 v236, 16, v181
	v_and_b32_e32 v237, 0xffff0000, v181
	v_pk_fma_f32 v[40:41], v[236:237], v[24:25], v[40:41]
	v_lshlrev_b32_e32 v226, 16, v182
	v_and_b32_e32 v227, 0xffff0000, v182
	v_pk_fma_f32 v[42:43], v[226:227], v[26:27], v[42:43]
	v_lshlrev_b32_e32 v228, 16, v183
	v_and_b32_e32 v229, 0xffff0000, v183
	v_pk_fma_f32 v[44:45], v[228:229], v[28:29], v[44:45]
	v_lshlrev_b32_e32 v234, 16, v184
	v_and_b32_e32 v235, 0xffff0000, v184
	v_pk_fma_f32 v[46:47], v[234:235], v[30:31], v[46:47]
	v_lshlrev_b32_e32 v236, 16, v185
	v_and_b32_e32 v237, 0xffff0000, v185
	v_pk_fma_f32 v[48:49], v[236:237], v[32:33], v[48:49]
	v_lshlrev_b32_e32 v226, 16, v186
	v_and_b32_e32 v227, 0xffff0000, v186
	v_pk_fma_f32 v[50:51], v[226:227], v[2:3], v[50:51]
	v_lshlrev_b32_e32 v228, 16, v187
	v_and_b32_e32 v229, 0xffff0000, v187
	v_pk_fma_f32 v[52:53], v[228:229], v[4:5], v[52:53]
	v_lshlrev_b32_e32 v234, 16, v188
	v_and_b32_e32 v235, 0xffff0000, v188
	v_pk_fma_f32 v[54:55], v[234:235], v[6:7], v[54:55]
	v_lshlrev_b32_e32 v236, 16, v189
	v_and_b32_e32 v237, 0xffff0000, v189
	v_pk_fma_f32 v[56:57], v[236:237], v[8:9], v[56:57]
	v_lshlrev_b32_e32 v226, 16, v190
	v_and_b32_e32 v227, 0xffff0000, v190
	v_pk_fma_f32 v[58:59], v[226:227], v[10:11], v[58:59]
	v_lshlrev_b32_e32 v228, 16, v191
	v_and_b32_e32 v229, 0xffff0000, v191
	v_pk_fma_f32 v[60:61], v[228:229], v[12:13], v[60:61]
	v_lshlrev_b32_e32 v234, 16, v192
	v_and_b32_e32 v235, 0xffff0000, v192
	v_pk_fma_f32 v[62:63], v[234:235], v[14:15], v[62:63]
	v_lshlrev_b32_e32 v236, 16, v193
	v_and_b32_e32 v237, 0xffff0000, v193
	v_pk_fma_f32 v[64:65], v[236:237], v[16:17], v[64:65]
	s_waitcnt lgkmcnt(0)
	s_barrier
; DI f32x16 mfma(bf16x8 a, bf16x8 b, f32x16 c) { return __builtin_amdgcn_mfma_f32_32x32x16_bf16(a, b, c, 0, 0, 0); }
; template <bool RFA, bool RFB, class LA, class LB, class EPI>
; DI void gemm_tile2s(u16* smem, int nk, LA la, LB lb, EPI epi) {
;     ...
;   auto ld = [&](u32x4 (&ra)[2], u32x4 (&rb)[2], int kt) __attribute__((always_inline)) {
;     const int k0 = kt * 64;
; #pragma unroll
;     for (int i = 0; i < 2; ++i) { const int c = tid + NTH * i; ra[i] = la(A_ROW(c), k0 + A_KC(c) * 8); rb[i] = lb(B_ROW(c), k0 + B_KC(c) * 8); }
;   };
;   auto stl = [&](u32x4 (&ra)[2], u32x4 (&rb)[2], int buf) __attribute__((always_inline)) {
; #pragma unroll
;     for (int i = 0; i < 2; ++i) {
;       const int c = tid + NTH * i;
;       *(u32x4*)(As + buf * TILE_ELEMS + A_ROW(c) * LDT + A_KC(c) * 8) = ra[i];
;       *(u32x4*)(Bs + buf * TILE_ELEMS + B_ROW(c) * LDT + B_KC(c) * 8) = rb[i];
;     }
;   };
;   auto compute = [&](int buf) __attribute__((always_inline)) {
;     const u16* Ab = As + buf * TILE_ELEMS + (wm * 64 + lr) * LDT + lh * 8;
;     const u16* Bb = Bs + buf * TILE_ELEMS + (wn * 32 + lr) * LDT + lh * 8;
; #pragma unroll
;     for (int ks = 0; ks < 4; ++ks) {
;       const bf16x8 a0 = *(const bf16x8*)(Ab + ks * 16);
;       const bf16x8 a1 = *(const bf16x8*)(Ab + 32 * LDT + ks * 16);
;       const bf16x8 b = *(const bf16x8*)(Bb + ks * 16);
;       acc[0] = mfma(a0, b, acc[0]);
;       acc[1] = mfma(a1, b, acc[1]);
;     }
;   };
;   ld(ra0, rb0, 0);
;   if (nk > 1) ld(ra1, rb1, 1);
;   stl(ra0, rb0, 0);
;   if (nk > 2) ld(ra0, rb0, 2);
;   __syncthreads();
; #pragma unroll 1
;   for (int kt = 0; kt < nk; kt += 2) {
;     compute(0);
;     if (kt + 1 < nk) { stl(ra1, rb1, 1); if (kt + 3 < nk) ld(ra1, rb1, kt + 3); }
;     __syncthreads();
;     if (kt + 1 < nk) {
;       compute(1);
;       if (kt + 2 < nk) { stl(ra0, rb0, 0); if (kt + 4 < nk) ld(ra0, rb0, kt + 4); }
;       __syncthreads();
	ds_read_b128 v[154:157], v219 offset:36928
	ds_read_b128 v[158:161], v220 offset:36928
	ds_read_b128 v[162:165], v219 offset:41536
	v_mfma_f32_32x32x16_bf16 v[18:33], v[130:133], v[134:137], 0
	ds_read_b128 v[166:169], v219 offset:36960
	ds_read_b128 v[170:173], v220 offset:36960
	ds_read_b128 v[174:177], v219 offset:41568
	v_mfma_f32_32x32x16_bf16 v[2:17], v[138:141], v[134:137], 0
	s_waitcnt vmcnt(8)
	ds_write_b128 v218, v[82:85] offset:18432
	ds_write_b128 v218, v[86:89] offset:27648
	v_mfma_f32_32x32x16_bf16 v[18:33], v[142:145], v[146:149], v[18:33]
	ds_write_b128 v223, v[90:93] offset:18432
	ds_write_b128 v223, v[94:97] offset:27648
	v_mfma_f32_32x32x16_bf16 v[2:17], v[150:153], v[146:149], v[2:17]
	global_load_dwordx4 v[82:85], v210, s[0:1] offset:128
	global_load_dwordx4 v[86:89], v210, s[2:3] offset:128
	global_load_dwordx4 v[90:93], v214, s[4:5] offset:128
	global_load_dwordx4 v[94:97], v214, s[6:7] offset:128
	ds_read_b128 v[130:133], v219
	ds_read_b128 v[134:137], v220
	ds_read_b128 v[138:141], v219 offset:4608
	s_waitcnt lgkmcnt(11)
	v_mfma_f32_32x32x16_bf16 v[18:33], v[154:157], v[158:161], v[18:33]
	ds_read_b128 v[142:145], v219 offset:32
	ds_read_b128 v[146:149], v220 offset:32
	ds_read_b128 v[150:153], v219 offset:4640
	s_waitcnt lgkmcnt(13)
	v_mfma_f32_32x32x16_bf16 v[2:17], v[162:165], v[158:161], v[2:17]
	s_waitcnt lgkmcnt(11)
	v_mfma_f32_32x32x16_bf16 v[18:33], v[166:169], v[170:173], v[18:33]
	s_waitcnt lgkmcnt(10)
	v_mfma_f32_32x32x16_bf16 v[2:17], v[174:177], v[170:173], v[2:17]
	s_waitcnt lgkmcnt(0)
	s_barrier
	ds_read_b128 v[154:157], v219 offset:64
	ds_read_b128 v[158:161], v220 offset:64
	ds_read_b128 v[162:165], v219 offset:4672
	v_mfma_f32_32x32x16_bf16 v[18:33], v[130:133], v[134:137], v[18:33]
	ds_read_b128 v[166:169], v219 offset:96
	ds_read_b128 v[170:173], v220 offset:96
	ds_read_b128 v[174:177], v219 offset:4704
	v_mfma_f32_32x32x16_bf16 v[2:17], v[138:141], v[134:137], v[2:17]
	s_waitcnt vmcnt(8)
	ds_write_b128 v218, v[98:101] offset:36864
	ds_write_b128 v218, v[102:105] offset:46080
	v_mfma_f32_32x32x16_bf16 v[18:33], v[142:145], v[146:149], v[18:33]
	ds_write_b128 v223, v[106:109] offset:36864
	ds_write_b128 v223, v[110:113] offset:46080
	v_mfma_f32_32x32x16_bf16 v[2:17], v[150:153], v[146:149], v[2:17]
	global_load_dwordx4 v[98:101], v210, s[0:1] offset:256
	global_load_dwordx4 v[102:105], v210, s[2:3] offset:256
	global_load_dwordx4 v[106:109], v214, s[4:5] offset:256
	global_load_dwordx4 v[110:113], v214, s[6:7] offset:256
	ds_read_b128 v[130:133], v219 offset:18432
	ds_read_b128 v[134:137], v220 offset:18432
	ds_read_b128 v[138:141], v219 offset:23040
	s_waitcnt lgkmcnt(11)
	v_mfma_f32_32x32x16_bf16 v[18:33], v[154:157], v[158:161], v[18:33]
	ds_read_b128 v[142:145], v219 offset:18464
	ds_read_b128 v[146:149], v220 offset:18464
	ds_read_b128 v[150:153], v219 offset:23072
	s_waitcnt lgkmcnt(13)
	v_mfma_f32_32x32x16_bf16 v[2:17], v[162:165], v[158:161], v[2:17]
	s_waitcnt lgkmcnt(11)
	v_mfma_f32_32x32x16_bf16 v[18:33], v[166:169], v[170:173], v[18:33]
	s_waitcnt lgkmcnt(10)
	v_mfma_f32_32x32x16_bf16 v[2:17], v[174:177], v[170:173], v[2:17]
	s_waitcnt lgkmcnt(0)
	s_barrier
	ds_read_b128 v[154:157], v219 offset:18496
	ds_read_b128 v[158:161], v220 offset:18496
	ds_read_b128 v[162:165], v219 offset:23104
	v_mfma_f32_32x32x16_bf16 v[18:33], v[130:133], v[134:137], v[18:33]
	ds_read_b128 v[166:169], v219 offset:18528
	ds_read_b128 v[170:173], v220 offset:18528
	ds_read_b128 v[174:177], v219 offset:23136
	v_mfma_f32_32x32x16_bf16 v[2:17], v[138:141], v[134:137], v[2:17]
	s_waitcnt vmcnt(8)
	ds_write_b128 v218, v[66:69]
	ds_write_b128 v218, v[70:73] offset:9216
	v_mfma_f32_32x32x16_bf16 v[18:33], v[142:145], v[146:149], v[18:33]
	ds_write_b128 v223, v[74:77]
	ds_write_b128 v223, v[78:81] offset:9216
	v_mfma_f32_32x32x16_bf16 v[2:17], v[150:153], v[146:149], v[2:17]
	global_load_dwordx4 v[66:69], v210, s[0:1] offset:384
	global_load_dwordx4 v[70:73], v210, s[2:3] offset:384
	global_load_dwordx4 v[74:77], v214, s[4:5] offset:384
	global_load_dwordx4 v[78:81], v214, s[6:7] offset:384
	ds_read_b128 v[130:133], v219 offset:36864
	ds_read_b128 v[134:137], v220 offset:36864
	ds_read_b128 v[138:141], v219 offset:41472
	s_waitcnt lgkmcnt(11)
	v_mfma_f32_32x32x16_bf16 v[18:33], v[154:157], v[158:161], v[18:33]
	ds_read_b128 v[142:145], v219 offset:36896
	ds_read_b128 v[146:149], v220 offset:36896
	ds_read_b128 v[150:153], v219 offset:41504
	s_waitcnt lgkmcnt(13)
	v_mfma_f32_32x32x16_bf16 v[2:17], v[162:165], v[158:161], v[2:17]
	s_waitcnt lgkmcnt(11)
	v_mfma_f32_32x32x16_bf16 v[18:33], v[166:169], v[170:173], v[18:33]
	s_waitcnt lgkmcnt(10)
	v_mfma_f32_32x32x16_bf16 v[2:17], v[174:177], v[170:173], v[2:17]
	s_waitcnt lgkmcnt(0)
	s_barrier
; DI float bflo(unsigned w) { return __uint_as_float(w << 16); }
; DI float bfhi(unsigned w) { return __uint_as_float(w & 0xffff0000u); }
; template <class ACC>
; DI void merge_branch(const Prm& p, u16* smem, const u16* W, const u16* X, int ld, int bi, int n0, int m0, ACC& macc) {
;   auto la = [&](int row, int k) __attribute__((always_inline)) { return *(const u32x4*)(W + (size_t)(n0 + (row & ~31) + perm_m(row & 31)) * ld + k); };
;   auto lb = [&](int row, int k) __attribute__((always_inline)) { return *(const u32x4*)(X + (size_t)(m0 + row) * ld + k); };
;   auto epi = [&](f32x16 (&acc)[2], int wm, int wn, int lane) __attribute__((always_inline)) {
;     const int lr = lane & 31, lh = lane >> 5;
;     const int tok = m0 + wn * 32 + lr;
; #pragma unroll
;     for (int i = 0; i < 2; ++i)
; #pragma unroll
;       for (int h2 = 0; h2 < 2; ++h2) {
;         const int n = n0 + wm * 64 + i * 32 + 16 * lh + 8 * h2;
;         const u32x4 gz = *(const u32x4*)(p.zg + (size_t)tok * 4096 + bi * 1024 + n);
; #pragma unroll
;         for (int e = 0; e < 4; ++e) {
;           macc[i][8 * h2 + 2 * e] += bflo(gz[e]) * acc[i][8 * h2 + 2 * e];
;           macc[i][8 * h2 + 2 * e + 1] += bfhi(gz[e]) * acc[i][8 * h2 + 2 * e + 1];
;         }
;       }
;   };
;   gemm_tile2s<false, false>(smem, ld >> 6, la, lb, epi);
; }
; DI void phase_merge(const Prm& p, u16* smem, int l, int& base) {
;   TASK_LOOP(t, 8 * 128, base) {
;     const int tn = t & 7, tm = t >> 3, n0 = tn * 128, m0 = tm * 128;
;     f32x16 macc[2];
;     macc[0] = zero16(); macc[1] = zero16();
;     merge_branch(p, smem, p.PaT + (size_t)l * 1024 * 768, p.UT, 768, 0, n0, m0, macc);
;     merge_branch(p, smem, p.PbT + (size_t)l * 1024 * 128, p.ob, 128, 1, n0, m0, macc);
;     ...
;     merge_branch(p, smem, p.PdT + (size_t)l * 1024 * 256, p.od, 256, 3, n0, m0, macc);
;     const int tid2 = tidx(), lane = tid2 & 63, wave = tid2 >> 6, wm = wave >> 2, wn = wave & 3, lr = lane & 31, lh = lane >> 5;
;     const int tok = m0 + wn * 32 + lr;
; #pragma unroll
;     for (int i = 0; i < 2; ++i)
; #pragma unroll
;       for (int h2 = 0; h2 < 2; ++h2) {
;         u32x4 o;
; #pragma unroll
;         for (int e = 0; e < 4; ++e) o[e] = pack2(macc[i][8 * h2 + 2 * e], macc[i][8 * h2 + 2 * e + 1]);
;         *(u32x4*)(p.hbuf + (size_t)tok * 1024 + n0 + wm * 64 + i * 32 + 16 * lh + 8 * h2) = o;
;       }
;   }
;   base += 8 * 128;
; }
	ds_read_b128 v[154:157], v219 offset:36928
	ds_read_b128 v[158:161], v220 offset:36928
	ds_read_b128 v[162:165], v219 offset:41536
	v_mfma_f32_32x32x16_bf16 v[18:33], v[130:133], v[134:137], v[18:33]
	ds_read_b128 v[166:169], v219 offset:36960
	ds_read_b128 v[170:173], v220 offset:36960
	ds_read_b128 v[174:177], v219 offset:41568
	v_mfma_f32_32x32x16_bf16 v[2:17], v[138:141], v[134:137], v[2:17]
	s_waitcnt vmcnt(8)
	ds_write_b128 v218, v[82:85] offset:18432
	ds_write_b128 v218, v[86:89] offset:27648
	v_mfma_f32_32x32x16_bf16 v[18:33], v[142:145], v[146:149], v[18:33]
	ds_write_b128 v223, v[90:93] offset:18432
	ds_write_b128 v223, v[94:97] offset:27648
	v_mfma_f32_32x32x16_bf16 v[2:17], v[150:153], v[146:149], v[2:17]
	global_load_dwordx4 v[82:85], v210, s[0:1] offset:512
	global_load_dwordx4 v[86:89], v210, s[2:3] offset:512
	global_load_dwordx4 v[90:93], v214, s[4:5] offset:512
	global_load_dwordx4 v[94:97], v214, s[6:7] offset:512
	ds_read_b128 v[130:133], v219
	ds_read_b128 v[134:137], v220
	ds_read_b128 v[138:141], v219 offset:4608
	s_waitcnt lgkmcnt(11)
	v_mfma_f32_32x32x16_bf16 v[18:33], v[154:157], v[158:161], v[18:33]
	ds_read_b128 v[142:145], v219 offset:32
	ds_read_b128 v[146:149], v220 offset:32
	ds_read_b128 v[150:153], v219 offset:4640
	s_waitcnt lgkmcnt(13)
	v_mfma_f32_32x32x16_bf16 v[2:17], v[162:165], v[158:161], v[2:17]
	s_waitcnt lgkmcnt(11)
	v_mfma_f32_32x32x16_bf16 v[18:33], v[166:169], v[170:173], v[18:33]
	s_waitcnt lgkmcnt(10)
	v_mfma_f32_32x32x16_bf16 v[2:17], v[174:177], v[170:173], v[2:17]
	s_waitcnt vmcnt(36)
	s_nop 15
	v_lshlrev_b32_e32 v226, 16, v194
	v_and_b32_e32 v227, 0xffff0000, v194
	v_pk_fma_f32 v[34:35], v[226:227], v[18:19], v[34:35]
	v_lshlrev_b32_e32 v228, 16, v195
	v_and_b32_e32 v229, 0xffff0000, v195
	v_pk_fma_f32 v[36:37], v[228:229], v[20:21], v[36:37]
	v_lshlrev_b32_e32 v234, 16, v196
	v_and_b32_e32 v235, 0xffff0000, v196
	v_pk_fma_f32 v[38:39], v[234:235], v[22:23], v[38:39]
	v_lshlrev_b32_e32 v236, 16, v197
	v_and_b32_e32 v237, 0xffff0000, v197
	v_pk_fma_f32 v[40:41], v[236:237], v[24:25], v[40:41]
	v_lshlrev_b32_e32 v226, 16, v198
	v_and_b32_e32 v227, 0xffff0000, v198
	v_pk_fma_f32 v[42:43], v[226:227], v[26:27], v[42:43]
	v_lshlrev_b32_e32 v228, 16, v199
	v_and_b32_e32 v229, 0xffff0000, v199
	v_pk_fma_f32 v[44:45], v[228:229], v[28:29], v[44:45]
	v_lshlrev_b32_e32 v234, 16, v200
	v_and_b32_e32 v235, 0xffff0000, v200
	v_pk_fma_f32 v[46:47], v[234:235], v[30:31], v[46:47]
	v_lshlrev_b32_e32 v236, 16, v201
	v_and_b32_e32 v237, 0xffff0000, v201
	v_pk_fma_f32 v[48:49], v[236:237], v[32:33], v[48:49]
	v_lshlrev_b32_e32 v226, 16, v202
	v_and_b32_e32 v227, 0xffff0000, v202
	v_pk_fma_f32 v[50:51], v[226:227], v[2:3], v[50:51]
	v_lshlrev_b32_e32 v228, 16, v203
	v_and_b32_e32 v229, 0xffff0000, v203
	v_pk_fma_f32 v[52:53], v[228:229], v[4:5], v[52:53]
	v_lshlrev_b32_e32 v234, 16, v204
	v_and_b32_e32 v235, 0xffff0000, v204
	v_pk_fma_f32 v[54:55], v[234:235], v[6:7], v[54:55]
	v_lshlrev_b32_e32 v236, 16, v205
	v_and_b32_e32 v237, 0xffff0000, v205
	v_pk_fma_f32 v[56:57], v[236:237], v[8:9], v[56:57]
	v_lshlrev_b32_e32 v226, 16, v206
	v_and_b32_e32 v227, 0xffff0000, v206
	v_pk_fma_f32 v[58:59], v[226:227], v[10:11], v[58:59]
	v_lshlrev_b32_e32 v228, 16, v207
	v_and_b32_e32 v229, 0xffff0000, v207
	v_pk_fma_f32 v[60:61], v[228:229], v[12:13], v[60:61]
	v_lshlrev_b32_e32 v234, 16, v208
	v_and_b32_e32 v235, 0xffff0000, v208
	v_pk_fma_f32 v[62:63], v[234:235], v[14:15], v[62:63]
	v_lshlrev_b32_e32 v236, 16, v209
	v_and_b32_e32 v237, 0xffff0000, v209
	v_pk_fma_f32 v[64:65], v[236:237], v[16:17], v[64:65]
	v_cvt_pk_bf16_f32 v178, v34, v35
	v_cvt_pk_bf16_f32 v179, v36, v37
	v_cvt_pk_bf16_f32 v180, v38, v39
	v_cvt_pk_bf16_f32 v181, v40, v41
	v_cvt_pk_bf16_f32 v182, v42, v43
	v_cvt_pk_bf16_f32 v183, v44, v45
	v_cvt_pk_bf16_f32 v184, v46, v47
	v_cvt_pk_bf16_f32 v185, v48, v49
	v_cvt_pk_bf16_f32 v186, v50, v51
	v_cvt_pk_bf16_f32 v187, v52, v53
	v_cvt_pk_bf16_f32 v188, v54, v55
	v_cvt_pk_bf16_f32 v189, v56, v57
	v_cvt_pk_bf16_f32 v190, v58, v59
	v_cvt_pk_bf16_f32 v191, v60, v61
	v_cvt_pk_bf16_f32 v192, v62, v63
	v_cvt_pk_bf16_f32 v193, v64, v65
	global_store_dwordx4 v222, v[178:181], s[12:13]
	global_store_dwordx4 v222, v[182:185], s[12:13] offset:16
	global_store_dwordx4 v222, v[186:189], s[12:13] offset:64
	global_store_dwordx4 v222, v[190:193], s[12:13] offset:80
	s_waitcnt lgkmcnt(0)
	s_barrier
	s_add_i32 s31, s31, s30
	s_mov_b32 s58, s60
	s_mov_b32 s59, s61
	s_cmpk_lt_i32 s31, 0x400
	s_cbranch_scc1 .Lmrg_task_e
	s_branch .Lmrg_done

; DI f32x16 mfma(bf16x8 a, bf16x8 b, f32x16 c) { return __builtin_amdgcn_mfma_f32_32x32x16_bf16(a, b, c, 0, 0, 0); }
; DI f32x16 zero16() { f32x16 z; for (int i = 0; i < 16; ++i) z[i] = 0.f; return z; }
; template <bool RFA, bool RFB, class LA, class LB, class EPI>
; DI void gemm_tile2s(u16* smem, int nk, LA la, LB lb, EPI epi) {
;     ...
;   auto ld = [&](u32x4 (&ra)[2], u32x4 (&rb)[2], int kt) __attribute__((always_inline)) {
;     const int k0 = kt * 64;
; #pragma unroll
;     for (int i = 0; i < 2; ++i) { const int c = tid + NTH * i; ra[i] = la(A_ROW(c), k0 + A_KC(c) * 8); rb[i] = lb(B_ROW(c), k0 + B_KC(c) * 8); }
;   };
;   auto stl = [&](u32x4 (&ra)[2], u32x4 (&rb)[2], int buf) __attribute__((always_inline)) {
; #pragma unroll
;     for (int i = 0; i < 2; ++i) {
;       const int c = tid + NTH * i;
;       *(u32x4*)(As + buf * TILE_ELEMS + A_ROW(c) * LDT + A_KC(c) * 8) = ra[i];
;       *(u32x4*)(Bs + buf * TILE_ELEMS + B_ROW(c) * LDT + B_KC(c) * 8) = rb[i];
;     }
;   };
;   auto compute = [&](int buf) __attribute__((always_inline)) {
;     const u16* Ab = As + buf * TILE_ELEMS + (wm * 64 + lr) * LDT + lh * 8;
;     const u16* Bb = Bs + buf * TILE_ELEMS + (wn * 32 + lr) * LDT + lh * 8;
; #pragma unroll
;     for (int ks = 0; ks < 4; ++ks) {
;       const bf16x8 a0 = *(const bf16x8*)(Ab + ks * 16);
;       const bf16x8 a1 = *(const bf16x8*)(Ab + 32 * LDT + ks * 16);
;       const bf16x8 b = *(const bf16x8*)(Bb + ks * 16);
;       acc[0] = mfma(a0, b, acc[0]);
;       acc[1] = mfma(a1, b, acc[1]);
;     }
;   };
;   ld(ra0, rb0, 0);
;   if (nk > 1) ld(ra1, rb1, 1);
;   stl(ra0, rb0, 0);
;   if (nk > 2) ld(ra0, rb0, 2);
;   __syncthreads();
; #pragma unroll 1
;   for (int kt = 0; kt < nk; kt += 2) {
;     compute(0);
;     if (kt + 1 < nk) { stl(ra1, rb1, 1); if (kt + 3 < nk) ld(ra1, rb1, kt + 3); }
;     __syncthreads();
;     if (kt + 1 < nk) {
;       compute(1);
;       if (kt + 2 < nk) { stl(ra0, rb0, 0); if (kt + 4 < nk) ld(ra0, rb0, kt + 4); }
;       __syncthreads();
; DI void phase_merge(const Prm& p, u16* smem, int l, int& base) {
;   TASK_LOOP(t, 8 * 128, base) {
;     const int tn = t & 7, tm = t >> 3, n0 = tn * 128, m0 = tm * 128;
;     f32x16 macc[2];
;     macc[0] = zero16(); macc[1] = zero16();
;     merge_branch(p, smem, p.PaT + (size_t)l * 1024 * 768, p.UT, 768, 0, n0, m0, macc);
.Lmrg_task_o:
	s_lshl_b32 s52, s59, 13
	s_lshl_b32 s53, s58, 1
	s_add_u32 s52, s52, s53
	s_add_u32 s8, s42, s52
	s_addc_u32 s9, s43, 0
	s_add_u32 s10, s8, 0x1000
	s_addc_u32 s11, s9, 0
	s_lshl_b32 s52, s59, 11
	s_add_u32 s52, s52, s53
	s_add_u32 s12, s48, s52
	s_addc_u32 s13, s49, 0
	ds_read_b128 v[154:157], v219 offset:64
	ds_read_b128 v[158:161], v220 offset:64
	ds_read_b128 v[162:165], v219 offset:4672
	v_mfma_f32_32x32x16_bf16 v[18:33], v[130:133], v[134:137], 0
	ds_read_b128 v[166:169], v219 offset:96
	ds_read_b128 v[170:173], v220 offset:96
	ds_read_b128 v[174:177], v219 offset:4704
	v_mfma_f32_32x32x16_bf16 v[2:17], v[138:141], v[134:137], 0
	s_waitcnt vmcnt(16)
	ds_write_b128 v218, v[98:101] offset:36864
	ds_write_b128 v218, v[102:105] offset:46080
	v_mfma_f32_32x32x16_bf16 v[18:33], v[142:145], v[146:149], v[18:33]
	ds_write_b128 v223, v[106:109] offset:36864
	ds_write_b128 v223, v[110:113] offset:46080
	v_mfma_f32_32x32x16_bf16 v[2:17], v[150:153], v[146:149], v[2:17]
	global_load_dwordx4 v[98:101], v210, s[0:1] offset:768
	global_load_dwordx4 v[102:105], v210, s[2:3] offset:768
	global_load_dwordx4 v[106:109], v214, s[4:5] offset:768
	global_load_dwordx4 v[110:113], v214, s[6:7] offset:768
	ds_read_b128 v[130:133], v219 offset:18432
	ds_read_b128 v[134:137], v220 offset:18432
	ds_read_b128 v[138:141], v219 offset:23040
	s_waitcnt lgkmcnt(11)
	v_mfma_f32_32x32x16_bf16 v[18:33], v[154:157], v[158:161], v[18:33]
	ds_read_b128 v[142:145], v219 offset:18464
	ds_read_b128 v[146:149], v220 offset:18464
	ds_read_b128 v[150:153], v219 offset:23072
	s_waitcnt lgkmcnt(13)
	v_mfma_f32_32x32x16_bf16 v[2:17], v[162:165], v[158:161], v[2:17]
	s_waitcnt lgkmcnt(11)
	v_mfma_f32_32x32x16_bf16 v[18:33], v[166:169], v[170:173], v[18:33]
	s_waitcnt lgkmcnt(10)
	v_mfma_f32_32x32x16_bf16 v[2:17], v[174:177], v[170:173], v[2:17]
	s_waitcnt lgkmcnt(0)
	s_barrier
	ds_read_b128 v[154:157], v219 offset:18496
	ds_read_b128 v[158:161], v220 offset:18496
	ds_read_b128 v[162:165], v219 offset:23104
	v_mfma_f32_32x32x16_bf16 v[18:33], v[130:133], v[134:137], v[18:33]
	ds_read_b128 v[166:169], v219 offset:18528
	ds_read_b128 v[170:173], v220 offset:18528
	ds_read_b128 v[174:177], v219 offset:23136
	v_mfma_f32_32x32x16_bf16 v[2:17], v[138:141], v[134:137], v[2:17]
	s_waitcnt vmcnt(16)
	ds_write_b128 v218, v[114:117]
	ds_write_b128 v218, v[118:121] offset:9216
	v_mfma_f32_32x32x16_bf16 v[18:33], v[142:145], v[146:149], v[18:33]
	ds_write_b128 v223, v[122:125]
	ds_write_b128 v223, v[126:129] offset:9216
	v_mfma_f32_32x32x16_bf16 v[2:17], v[150:153], v[146:149], v[2:17]
	global_load_dwordx4 v[114:117], v210, s[0:1] offset:896
	global_load_dwordx4 v[118:121], v210, s[2:3] offset:896
	global_load_dwordx4 v[122:125], v214, s[4:5] offset:896
	global_load_dwordx4 v[126:129], v214, s[6:7] offset:896
	ds_read_b128 v[130:133], v219 offset:36864
	ds_read_b128 v[134:137], v220 offset:36864
	ds_read_b128 v[138:141], v219 offset:41472
	s_waitcnt lgkmcnt(11)
	v_mfma_f32_32x32x16_bf16 v[18:33], v[154:157], v[158:161], v[18:33]
	ds_read_b128 v[142:145], v219 offset:36896
	ds_read_b128 v[146:149], v220 offset:36896
	ds_read_b128 v[150:153], v219 offset:41504
	s_waitcnt lgkmcnt(13)
	v_mfma_f32_32x32x16_bf16 v[2:17], v[162:165], v[158:161], v[2:17]
	s_waitcnt lgkmcnt(11)
	v_mfma_f32_32x32x16_bf16 v[18:33], v[166:169], v[170:173], v[18:33]
	s_waitcnt lgkmcnt(10)
	v_mfma_f32_32x32x16_bf16 v[2:17], v[174:177], v[170:173], v[2:17]
	s_waitcnt lgkmcnt(0)
	s_barrier
	ds_read_b128 v[154:157], v219 offset:36928
	ds_read_b128 v[158:161], v220 offset:36928
	ds_read_b128 v[162:165], v219 offset:41536
	v_mfma_f32_32x32x16_bf16 v[18:33], v[130:133], v[134:137], v[18:33]
	ds_read_b128 v[166:169], v219 offset:36960
	ds_read_b128 v[170:173], v220 offset:36960
	ds_read_b128 v[174:177], v219 offset:41568
	v_mfma_f32_32x32x16_bf16 v[2:17], v[138:141], v[134:137], v[2:17]
	s_waitcnt vmcnt(16)
	ds_write_b128 v218, v[66:69] offset:18432
	ds_write_b128 v218, v[70:73] offset:27648
	v_mfma_f32_32x32x16_bf16 v[18:33], v[142:145], v[146:149], v[18:33]
	ds_write_b128 v223, v[74:77] offset:18432
	ds_write_b128 v223, v[78:81] offset:27648
	v_mfma_f32_32x32x16_bf16 v[2:17], v[150:153], v[146:149], v[2:17]
	global_load_dwordx4 v[66:69], v210, s[0:1] offset:1024
	global_load_dwordx4 v[70:73], v210, s[2:3] offset:1024
	global_load_dwordx4 v[74:77], v214, s[4:5] offset:1024
	global_load_dwordx4 v[78:81], v214, s[6:7] offset:1024
	ds_read_b128 v[130:133], v219
	ds_read_b128 v[134:137], v220
	ds_read_b128 v[138:141], v219 offset:4608
	s_waitcnt lgkmcnt(11)
	v_mfma_f32_32x32x16_bf16 v[18:33], v[154:157], v[158:161], v[18:33]
	ds_read_b128 v[142:145], v219 offset:32
	ds_read_b128 v[146:149], v220 offset:32
	ds_read_b128 v[150:153], v219 offset:4640
	s_waitcnt lgkmcnt(13)
	v_mfma_f32_32x32x16_bf16 v[2:17], v[162:165], v[158:161], v[2:17]
	s_waitcnt lgkmcnt(11)
	v_mfma_f32_32x32x16_bf16 v[18:33], v[166:169], v[170:173], v[18:33]
	s_waitcnt lgkmcnt(10)
	v_mfma_f32_32x32x16_bf16 v[2:17], v[174:177], v[170:173], v[2:17]
	s_waitcnt lgkmcnt(0)
	s_barrier
; DI f32x16 mfma(bf16x8 a, bf16x8 b, f32x16 c) { return __builtin_amdgcn_mfma_f32_32x32x16_bf16(a, b, c, 0, 0, 0); }
; template <bool RFA, bool RFB, class LA, class LB, class EPI>
; DI void gemm_tile2s(u16* smem, int nk, LA la, LB lb, EPI epi) {
;     ...
;   auto ld = [&](u32x4 (&ra)[2], u32x4 (&rb)[2], int kt) __attribute__((always_inline)) {
;     const int k0 = kt * 64;
; #pragma unroll
;     for (int i = 0; i < 2; ++i) { const int c = tid + NTH * i; ra[i] = la(A_ROW(c), k0 + A_KC(c) * 8); rb[i] = lb(B_ROW(c), k0 + B_KC(c) * 8); }
;   };
;   auto stl = [&](u32x4 (&ra)[2], u32x4 (&rb)[2], int buf) __attribute__((always_inline)) {
; #pragma unroll
;     for (int i = 0; i < 2; ++i) {
;       const int c = tid + NTH * i;
;       *(u32x4*)(As + buf * TILE_ELEMS + A_ROW(c) * LDT + A_KC(c) * 8) = ra[i];
;       *(u32x4*)(Bs + buf * TILE_ELEMS + B_ROW(c) * LDT + B_KC(c) * 8) = rb[i];
;     }
;   };
;   auto compute = [&](int buf) __attribute__((always_inline)) {
;     const u16* Ab = As + buf * TILE_ELEMS + (wm * 64 + lr) * LDT + lh * 8;
;     const u16* Bb = Bs + buf * TILE_ELEMS + (wn * 32 + lr) * LDT + lh * 8;
; #pragma unroll
;     for (int ks = 0; ks < 4; ++ks) {
;       const bf16x8 a0 = *(const bf16x8*)(Ab + ks * 16);
;       const bf16x8 a1 = *(const bf16x8*)(Ab + 32 * LDT + ks * 16);
;       const bf16x8 b = *(const bf16x8*)(Bb + ks * 16);
;       acc[0] = mfma(a0, b, acc[0]);
;       acc[1] = mfma(a1, b, acc[1]);
;     }
;   };
;   ld(ra0, rb0, 0);
;   if (nk > 1) ld(ra1, rb1, 1);
;   stl(ra0, rb0, 0);
;   if (nk > 2) ld(ra0, rb0, 2);
;   __syncthreads();
; #pragma unroll 1
;   for (int kt = 0; kt < nk; kt += 2) {
;     compute(0);
;     if (kt + 1 < nk) { stl(ra1, rb1, 1); if (kt + 3 < nk) ld(ra1, rb1, kt + 3); }
;     __syncthreads();
;     if (kt + 1 < nk) {
;       compute(1);
;       if (kt + 2 < nk) { stl(ra0, rb0, 0); if (kt + 4 < nk) ld(ra0, rb0, kt + 4); }
;       __syncthreads();
	ds_read_b128 v[154:157], v219 offset:64
	ds_read_b128 v[158:161], v220 offset:64
	ds_read_b128 v[162:165], v219 offset:4672
	v_mfma_f32_32x32x16_bf16 v[18:33], v[130:133], v[134:137], v[18:33]
	ds_read_b128 v[166:169], v219 offset:96
	ds_read_b128 v[170:173], v220 offset:96
	ds_read_b128 v[174:177], v219 offset:4704
	v_mfma_f32_32x32x16_bf16 v[2:17], v[138:141], v[134:137], v[2:17]
	s_waitcnt vmcnt(16)
	ds_write_b128 v218, v[82:85] offset:36864
	ds_write_b128 v218, v[86:89] offset:46080
	v_mfma_f32_32x32x16_bf16 v[18:33], v[142:145], v[146:149], v[18:33]
	ds_write_b128 v223, v[90:93] offset:36864
	ds_write_b128 v223, v[94:97] offset:46080
	v_mfma_f32_32x32x16_bf16 v[2:17], v[150:153], v[146:149], v[2:17]
	global_load_dwordx4 v[82:85], v210, s[0:1] offset:1152
	global_load_dwordx4 v[86:89], v210, s[2:3] offset:1152
	global_load_dwordx4 v[90:93], v214, s[4:5] offset:1152
	global_load_dwordx4 v[94:97], v214, s[6:7] offset:1152
	ds_read_b128 v[130:133], v219 offset:18432
	ds_read_b128 v[134:137], v220 offset:18432
	ds_read_b128 v[138:141], v219 offset:23040
	s_waitcnt lgkmcnt(11)
	v_mfma_f32_32x32x16_bf16 v[18:33], v[154:157], v[158:161], v[18:33]
	ds_read_b128 v[142:145], v219 offset:18464
	ds_read_b128 v[146:149], v220 offset:18464
	ds_read_b128 v[150:153], v219 offset:23072
	s_waitcnt lgkmcnt(13)
	v_mfma_f32_32x32x16_bf16 v[2:17], v[162:165], v[158:161], v[2:17]
	s_waitcnt lgkmcnt(11)
	v_mfma_f32_32x32x16_bf16 v[18:33], v[166:169], v[170:173], v[18:33]
	s_waitcnt lgkmcnt(10)
	v_mfma_f32_32x32x16_bf16 v[2:17], v[174:177], v[170:173], v[2:17]
	s_waitcnt lgkmcnt(0)
	s_barrier
	ds_read_b128 v[154:157], v219 offset:18496
	ds_read_b128 v[158:161], v220 offset:18496
	ds_read_b128 v[162:165], v219 offset:23104
	v_mfma_f32_32x32x16_bf16 v[18:33], v[130:133], v[134:137], v[18:33]
	ds_read_b128 v[166:169], v219 offset:18528
	ds_read_b128 v[170:173], v220 offset:18528
	ds_read_b128 v[174:177], v219 offset:23136
	v_mfma_f32_32x32x16_bf16 v[2:17], v[138:141], v[134:137], v[2:17]
	s_waitcnt vmcnt(12)
	ds_write_b128 v218, v[98:101]
	ds_write_b128 v218, v[102:105] offset:9216
	v_mfma_f32_32x32x16_bf16 v[18:33], v[142:145], v[146:149], v[18:33]
	ds_write_b128 v223, v[106:109]
	ds_write_b128 v223, v[110:113] offset:9216
	v_mfma_f32_32x32x16_bf16 v[2:17], v[150:153], v[146:149], v[2:17]
	global_load_dwordx4 v[98:101], v210, s[0:1] offset:1280
	global_load_dwordx4 v[102:105], v210, s[2:3] offset:1280
	global_load_dwordx4 v[106:109], v214, s[4:5] offset:1280
	global_load_dwordx4 v[110:113], v214, s[6:7] offset:1280
	ds_read_b128 v[130:133], v219 offset:36864
	ds_read_b128 v[134:137], v220 offset:36864
	ds_read_b128 v[138:141], v219 offset:41472
	s_waitcnt lgkmcnt(11)
	v_mfma_f32_32x32x16_bf16 v[18:33], v[154:157], v[158:161], v[18:33]
	ds_read_b128 v[142:145], v219 offset:36896
	ds_read_b128 v[146:149], v220 offset:36896
	ds_read_b128 v[150:153], v219 offset:41504
	s_waitcnt lgkmcnt(13)
	v_mfma_f32_32x32x16_bf16 v[2:17], v[162:165], v[158:161], v[2:17]
	s_waitcnt lgkmcnt(11)
	v_mfma_f32_32x32x16_bf16 v[18:33], v[166:169], v[170:173], v[18:33]
	s_waitcnt lgkmcnt(10)
	v_mfma_f32_32x32x16_bf16 v[2:17], v[174:177], v[170:173], v[2:17]
	s_waitcnt lgkmcnt(0)
	s_barrier
	ds_read_b128 v[154:157], v219 offset:36928
	ds_read_b128 v[158:161], v220 offset:36928
	ds_read_b128 v[162:165], v219 offset:41536
	v_mfma_f32_32x32x16_bf16 v[18:33], v[130:133], v[134:137], v[18:33]
	ds_read_b128 v[166:169], v219 offset:36960
	ds_read_b128 v[170:173], v220 offset:36960
	ds_read_b128 v[174:177], v219 offset:41568
	v_mfma_f32_32x32x16_bf16 v[2:17], v[138:141], v[134:137], v[2:17]
	s_waitcnt vmcnt(12)
	ds_write_b128 v218, v[114:117] offset:18432
	ds_write_b128 v218, v[118:121] offset:27648
	v_mfma_f32_32x32x16_bf16 v[18:33], v[142:145], v[146:149], v[18:33]
	ds_write_b128 v223, v[122:125] offset:18432
	ds_write_b128 v223, v[126:129] offset:27648
	v_mfma_f32_32x32x16_bf16 v[2:17], v[150:153], v[146:149], v[2:17]
	global_load_dwordx4 v[114:117], v210, s[0:1] offset:1408
	global_load_dwordx4 v[118:121], v210, s[2:3] offset:1408
	global_load_dwordx4 v[122:125], v214, s[4:5] offset:1408
	global_load_dwordx4 v[126:129], v214, s[6:7] offset:1408
	global_load_dwordx4 v[178:181], v221, s[8:9]
	global_load_dwordx4 v[182:185], v221, s[8:9] offset:16
	global_load_dwordx4 v[186:189], v221, s[8:9] offset:64
	global_load_dwordx4 v[190:193], v221, s[8:9] offset:80
	ds_read_b128 v[130:133], v219
	ds_read_b128 v[134:137], v220
	ds_read_b128 v[138:141], v219 offset:4608
	s_waitcnt lgkmcnt(11)
	v_mfma_f32_32x32x16_bf16 v[18:33], v[154:157], v[158:161], v[18:33]
	ds_read_b128 v[142:145], v219 offset:32
	ds_read_b128 v[146:149], v220 offset:32
	ds_read_b128 v[150:153], v219 offset:4640
	s_waitcnt lgkmcnt(13)
	v_mfma_f32_32x32x16_bf16 v[2:17], v[162:165], v[158:161], v[2:17]
	s_waitcnt lgkmcnt(11)
	v_mfma_f32_32x32x16_bf16 v[18:33], v[166:169], v[170:173], v[18:33]
	s_waitcnt lgkmcnt(10)
	v_mfma_f32_32x32x16_bf16 v[2:17], v[174:177], v[170:173], v[2:17]
	s_waitcnt lgkmcnt(0)
	s_barrier
; DI f32x16 mfma(bf16x8 a, bf16x8 b, f32x16 c) { return __builtin_amdgcn_mfma_f32_32x32x16_bf16(a, b, c, 0, 0, 0); }
; template <bool RFA, bool RFB, class LA, class LB, class EPI>
; DI void gemm_tile2s(u16* smem, int nk, LA la, LB lb, EPI epi) {
;     ...
;   auto ld = [&](u32x4 (&ra)[2], u32x4 (&rb)[2], int kt) __attribute__((always_inline)) {
;     const int k0 = kt * 64;
; #pragma unroll
;     for (int i = 0; i < 2; ++i) { const int c = tid + NTH * i; ra[i] = la(A_ROW(c), k0 + A_KC(c) * 8); rb[i] = lb(B_ROW(c), k0 + B_KC(c) * 8); }
;   };
;   auto stl = [&](u32x4 (&ra)[2], u32x4 (&rb)[2], int buf) __attribute__((always_inline)) {
; #pragma unroll
;     for (int i = 0; i < 2; ++i) {
;       const int c = tid + NTH * i;
;       *(u32x4*)(As + buf * TILE_ELEMS + A_ROW(c) * LDT + A_KC(c) * 8) = ra[i];
;       *(u32x4*)(Bs + buf * TILE_ELEMS + B_ROW(c) * LDT + B_KC(c) * 8) = rb[i];
;     }
;   };
;   auto compute = [&](int buf) __attribute__((always_inline)) {
;     const u16* Ab = As + buf * TILE_ELEMS + (wm * 64 + lr) * LDT + lh * 8;
;     const u16* Bb = Bs + buf * TILE_ELEMS + (wn * 32 + lr) * LDT + lh * 8;
; #pragma unroll
;     for (int ks = 0; ks < 4; ++ks) {
;       const bf16x8 a0 = *(const bf16x8*)(Ab + ks * 16);
;       const bf16x8 a1 = *(const bf16x8*)(Ab + 32 * LDT + ks * 16);
;       const bf16x8 b = *(const bf16x8*)(Bb + ks * 16);
;       acc[0] = mfma(a0, b, acc[0]);
;       acc[1] = mfma(a1, b, acc[1]);
;     }
;   };
;   ld(ra0, rb0, 0);
;   if (nk > 1) ld(ra1, rb1, 1);
;   stl(ra0, rb0, 0);
;   if (nk > 2) ld(ra0, rb0, 2);
;   __syncthreads();
; #pragma unroll 1
;   for (int kt = 0; kt < nk; kt += 2) {
;     compute(0);
;     if (kt + 1 < nk) { stl(ra1, rb1, 1); if (kt + 3 < nk) ld(ra1, rb1, kt + 3); }
;     __syncthreads();
;     if (kt + 1 < nk) {
;       compute(1);
;       if (kt + 2 < nk) { stl(ra0, rb0, 0); if (kt + 4 < nk) ld(ra0, rb0, kt + 4); }
;       __syncthreads();
; DI void phase_merge(const Prm& p, u16* smem, int l, int& base) {
;     ...
;     merge_branch(p, smem, p.PaT + (size_t)l * 1024 * 768, p.UT, 768, 0, n0, m0, macc);
;     merge_branch(p, smem, p.PbT + (size_t)l * 1024 * 128, p.ob, 128, 1, n0, m0, macc);
	ds_read_b128 v[154:157], v219 offset:64
	ds_read_b128 v[158:161], v220 offset:64
	ds_read_b128 v[162:165], v219 offset:4672
	v_mfma_f32_32x32x16_bf16 v[18:33], v[130:133], v[134:137], v[18:33]
	ds_read_b128 v[166:169], v219 offset:96
	ds_read_b128 v[170:173], v220 offset:96
	ds_read_b128 v[174:177], v219 offset:4704
	v_mfma_f32_32x32x16_bf16 v[2:17], v[138:141], v[134:137], v[2:17]
	s_waitcnt vmcnt(16)
	ds_write_b128 v218, v[66:69] offset:36864
	ds_write_b128 v218, v[70:73] offset:46080
	v_mfma_f32_32x32x16_bf16 v[18:33], v[142:145], v[146:149], v[18:33]
	ds_write_b128 v223, v[74:77] offset:36864
	ds_write_b128 v223, v[78:81] offset:46080
	v_mfma_f32_32x32x16_bf16 v[2:17], v[150:153], v[146:149], v[2:17]
	s_mul_i32 s52, s58, 0x100
	s_add_u32 s0, s20, s52
	s_addc_u32 s1, s21, 0
	s_add_u32 s2, s0, 0x4000
	s_addc_u32 s3, s1, 0
	s_mul_i32 s52, s59, 0x100
	s_add_u32 s4, s36, s52
	s_addc_u32 s5, s37, 0
	s_add_u32 s6, s4, 0x4000
	s_addc_u32 s7, s5, 0
	global_load_dwordx4 v[66:69], v211, s[0:1]
	global_load_dwordx4 v[70:73], v211, s[2:3]
	global_load_dwordx4 v[74:77], v215, s[4:5]
	global_load_dwordx4 v[78:81], v215, s[6:7]
	ds_read_b128 v[130:133], v219 offset:18432
	ds_read_b128 v[134:137], v220 offset:18432
	ds_read_b128 v[138:141], v219 offset:23040
	s_waitcnt lgkmcnt(11)
	v_mfma_f32_32x32x16_bf16 v[18:33], v[154:157], v[158:161], v[18:33]
	ds_read_b128 v[142:145], v219 offset:18464
	ds_read_b128 v[146:149], v220 offset:18464
	ds_read_b128 v[150:153], v219 offset:23072
	s_waitcnt lgkmcnt(13)
	v_mfma_f32_32x32x16_bf16 v[2:17], v[162:165], v[158:161], v[2:17]
	s_waitcnt lgkmcnt(11)
	v_mfma_f32_32x32x16_bf16 v[18:33], v[166:169], v[170:173], v[18:33]
	s_waitcnt lgkmcnt(10)
	v_mfma_f32_32x32x16_bf16 v[2:17], v[174:177], v[170:173], v[2:17]
	s_waitcnt lgkmcnt(0)
	s_barrier
	ds_read_b128 v[154:157], v219 offset:18496
	ds_read_b128 v[158:161], v220 offset:18496
	ds_read_b128 v[162:165], v219 offset:23104
	v_mfma_f32_32x32x16_bf16 v[18:33], v[130:133], v[134:137], v[18:33]
	ds_read_b128 v[166:169], v219 offset:18528
	ds_read_b128 v[170:173], v220 offset:18528
	ds_read_b128 v[174:177], v219 offset:23136
	v_mfma_f32_32x32x16_bf16 v[2:17], v[138:141], v[134:137], v[2:17]
	s_waitcnt vmcnt(16)
	ds_write_b128 v218, v[82:85]
	ds_write_b128 v218, v[86:89] offset:9216
	v_mfma_f32_32x32x16_bf16 v[18:33], v[142:145], v[146:149], v[18:33]
	ds_write_b128 v223, v[90:93]
	ds_write_b128 v223, v[94:97] offset:9216
	v_mfma_f32_32x32x16_bf16 v[2:17], v[150:153], v[146:149], v[2:17]
	global_load_dwordx4 v[82:85], v211, s[0:1] offset:128
	global_load_dwordx4 v[86:89], v211, s[2:3] offset:128
	global_load_dwordx4 v[90:93], v215, s[4:5] offset:128
	global_load_dwordx4 v[94:97], v215, s[6:7] offset:128
	global_load_dwordx4 v[194:197], v221, s[8:9] offset:2048
	global_load_dwordx4 v[198:201], v221, s[8:9] offset:2064
	global_load_dwordx4 v[202:205], v221, s[8:9] offset:2112
	global_load_dwordx4 v[206:209], v221, s[8:9] offset:2128
	ds_read_b128 v[130:133], v219 offset:36864
	ds_read_b128 v[134:137], v220 offset:36864
	ds_read_b128 v[138:141], v219 offset:41472
	s_waitcnt lgkmcnt(11)
	v_mfma_f32_32x32x16_bf16 v[18:33], v[154:157], v[158:161], v[18:33]
	ds_read_b128 v[142:145], v219 offset:36896
	ds_read_b128 v[146:149], v220 offset:36896
	ds_read_b128 v[150:153], v219 offset:41504
	s_waitcnt lgkmcnt(13)
	v_mfma_f32_32x32x16_bf16 v[2:17], v[162:165], v[158:161], v[2:17]
	s_waitcnt lgkmcnt(11)
	v_mfma_f32_32x32x16_bf16 v[18:33], v[166:169], v[170:173], v[18:33]
	s_waitcnt lgkmcnt(10)
	v_mfma_f32_32x32x16_bf16 v[2:17], v[174:177], v[170:173], v[2:17]
	s_waitcnt lgkmcnt(0)
	s_barrier
	ds_read_b128 v[154:157], v219 offset:36928
	ds_read_b128 v[158:161], v220 offset:36928
	ds_read_b128 v[162:165], v219 offset:41536
	v_mfma_f32_32x32x16_bf16 v[18:33], v[130:133], v[134:137], v[18:33]
	ds_read_b128 v[166:169], v219 offset:36960
	ds_read_b128 v[170:173], v220 offset:36960
	ds_read_b128 v[174:177], v219 offset:41568
	v_mfma_f32_32x32x16_bf16 v[2:17], v[138:141], v[134:137], v[2:17]
	s_waitcnt vmcnt(20)
	ds_write_b128 v218, v[98:101] offset:18432
	ds_write_b128 v218, v[102:105] offset:27648
	v_mfma_f32_32x32x16_bf16 v[18:33], v[142:145], v[146:149], v[18:33]
	ds_write_b128 v223, v[106:109] offset:18432
	ds_write_b128 v223, v[110:113] offset:27648
	v_mfma_f32_32x32x16_bf16 v[2:17], v[150:153], v[146:149], v[2:17]
	s_mul_i32 s52, s58, 0x300
	s_add_u32 s0, s22, s52
	s_addc_u32 s1, s23, 0
	s_add_u32 s2, s0, 0xc000
	s_addc_u32 s3, s1, 0
	s_mul_i32 s52, s59, 0x300
	s_add_u32 s4, s38, s52
	s_addc_u32 s5, s39, 0
	s_add_u32 s6, s4, 0xc000
	s_addc_u32 s7, s5, 0
	global_load_dwordx4 v[98:101], v212, s[0:1]
	global_load_dwordx4 v[102:105], v212, s[2:3]
	global_load_dwordx4 v[106:109], v216, s[4:5]
	global_load_dwordx4 v[110:113], v216, s[6:7]
	ds_read_b128 v[130:133], v219
	ds_read_b128 v[134:137], v220
	ds_read_b128 v[138:141], v219 offset:4608
	s_waitcnt lgkmcnt(11)
	v_mfma_f32_32x32x16_bf16 v[18:33], v[154:157], v[158:161], v[18:33]
	ds_read_b128 v[142:145], v219 offset:32
	ds_read_b128 v[146:149], v220 offset:32
	ds_read_b128 v[150:153], v219 offset:4640
	s_waitcnt lgkmcnt(13)
	v_mfma_f32_32x32x16_bf16 v[2:17], v[162:165], v[158:161], v[2:17]
	s_waitcnt lgkmcnt(11)
	v_mfma_f32_32x32x16_bf16 v[18:33], v[166:169], v[170:173], v[18:33]
	s_waitcnt lgkmcnt(10)
	v_mfma_f32_32x32x16_bf16 v[2:17], v[174:177], v[170:173], v[2:17]
	s_waitcnt lgkmcnt(0)
	s_barrier
; template <bool RFA, bool RFB, class LA, class LB, class EPI>
; DI void gemm_tile2s(u16* smem, int nk, LA la, LB lb, EPI epi) {
;     ...
;   auto ld = [&](u32x4 (&ra)[2], u32x4 (&rb)[2], int kt) __attribute__((always_inline)) {
;     const int k0 = kt * 64;
; #pragma unroll
;     for (int i = 0; i < 2; ++i) { const int c = tid + NTH * i; ra[i] = la(A_ROW(c), k0 + A_KC(c) * 8); rb[i] = lb(B_ROW(c), k0 + B_KC(c) * 8); }
;   };
;   auto stl = [&](u32x4 (&ra)[2], u32x4 (&rb)[2], int buf) __attribute__((always_inline)) {
; #pragma unroll
;     for (int i = 0; i < 2; ++i) {
;       const int c = tid + NTH * i;
;       *(u32x4*)(As + buf * TILE_ELEMS + A_ROW(c) * LDT + A_KC(c) * 8) = ra[i];
;       *(u32x4*)(Bs + buf * TILE_ELEMS + B_ROW(c) * LDT + B_KC(c) * 8) = rb[i];
;     }
;   };
;   auto compute = [&](int buf) __attribute__((always_inline)) {
;     const u16* Ab = As + buf * TILE_ELEMS + (wm * 64 + lr) * LDT + lh * 8;
;     const u16* Bb = Bs + buf * TILE_ELEMS + (wn * 32 + lr) * LDT + lh * 8;
; #pragma unroll
;     for (int ks = 0; ks < 4; ++ks) {
;       const bf16x8 a0 = *(const bf16x8*)(Ab + ks * 16);
;       const bf16x8 a1 = *(const bf16x8*)(Ab + 32 * LDT + ks * 16);
;       const bf16x8 b = *(const bf16x8*)(Bb + ks * 16);
;       acc[0] = mfma(a0, b, acc[0]);
;       acc[1] = mfma(a1, b, acc[1]);
;     }
;   };
;   ld(ra0, rb0, 0);
;   if (nk > 1) ld(ra1, rb1, 1);
;   stl(ra0, rb0, 0);
;   if (nk > 2) ld(ra0, rb0, 2);
;   __syncthreads();
; #pragma unroll 1
;   for (int kt = 0; kt < nk; kt += 2) {
;     compute(0);
;     if (kt + 1 < nk) { stl(ra1, rb1, 1); if (kt + 3 < nk) ld(ra1, rb1, kt + 3); }
;     __syncthreads();
;     if (kt + 1 < nk) {
;       compute(1);
;       if (kt + 2 < nk) { stl(ra0, rb0, 0); if (kt + 4 < nk) ld(ra0, rb0, kt + 4); }
;       __syncthreads();
; template <class ACC>
; DI void merge_branch(const Prm& p, u16* smem, const u16* W, const u16* X, int ld, int bi, int n0, int m0, ACC& macc) {
;     ...
;   auto epi = [&](f32x16 (&acc)[2], int wm, int wn, int lane) __attribute__((always_inline)) {
;     const int lr = lane & 31, lh = lane >> 5;
;     const int tok = m0 + wn * 32 + lr;
; #pragma unroll
;     for (int i = 0; i < 2; ++i)
; #pragma unroll
;       for (int h2 = 0; h2 < 2; ++h2) {
;         const int n = n0 + wm * 64 + i * 32 + 16 * lh + 8 * h2;
;         const u32x4 gz = *(const u32x4*)(p.zg + (size_t)tok * 4096 + bi * 1024 + n);
	ds_read_b128 v[154:157], v219 offset:64
	ds_read_b128 v[158:161], v220 offset:64
	ds_read_b128 v[162:165], v219 offset:4672
	v_mfma_f32_32x32x16_bf16 v[18:33], v[130:133], v[134:137], v[18:33]
	ds_read_b128 v[166:169], v219 offset:96
	ds_read_b128 v[170:173], v220 offset:96
	ds_read_b128 v[174:177], v219 offset:4704
	v_mfma_f32_32x32x16_bf16 v[2:17], v[138:141], v[134:137], v[2:17]
	s_waitcnt vmcnt(20)
	ds_write_b128 v218, v[114:117] offset:36864
	ds_write_b128 v218, v[118:121] offset:46080
	v_mfma_f32_32x32x16_bf16 v[18:33], v[142:145], v[146:149], v[18:33]
	ds_write_b128 v223, v[122:125] offset:36864
	ds_write_b128 v223, v[126:129] offset:46080
	v_mfma_f32_32x32x16_bf16 v[2:17], v[150:153], v[146:149], v[2:17]
	global_load_dwordx4 v[114:117], v212, s[0:1] offset:128
	global_load_dwordx4 v[118:121], v212, s[2:3] offset:128
	global_load_dwordx4 v[122:125], v216, s[4:5] offset:128
	global_load_dwordx4 v[126:129], v216, s[6:7] offset:128
	ds_read_b128 v[130:133], v219 offset:18432
	ds_read_b128 v[134:137], v220 offset:18432
	ds_read_b128 v[138:141], v219 offset:23040
	s_waitcnt lgkmcnt(11)
	v_mfma_f32_32x32x16_bf16 v[18:33], v[154:157], v[158:161], v[18:33]
	ds_read_b128 v[142:145], v219 offset:18464
	ds_read_b128 v[146:149], v220 offset:18464
	ds_read_b128 v[150:153], v219 offset:23072
	s_waitcnt lgkmcnt(13)
	v_mfma_f32_32x32x16_bf16 v[2:17], v[162:165], v[158:161], v[2:17]
	s_waitcnt lgkmcnt(11)
	v_mfma_f32_32x32x16_bf16 v[18:33], v[166:169], v[170:173], v[18:33]
	s_waitcnt lgkmcnt(10)
	v_mfma_f32_32x32x16_bf16 v[2:17], v[174:177], v[170:173], v[2:17]
	s_waitcnt lgkmcnt(0)
	s_barrier
	ds_read_b128 v[154:157], v219 offset:18496
	ds_read_b128 v[158:161], v220 offset:18496
	ds_read_b128 v[162:165], v219 offset:23104
	v_mfma_f32_32x32x16_bf16 v[18:33], v[130:133], v[134:137], v[18:33]
	ds_read_b128 v[166:169], v219 offset:18528
	ds_read_b128 v[170:173], v220 offset:18528
	ds_read_b128 v[174:177], v219 offset:23136
	v_mfma_f32_32x32x16_bf16 v[2:17], v[138:141], v[134:137], v[2:17]
	s_waitcnt vmcnt(16)
	ds_write_b128 v218, v[66:69]
	ds_write_b128 v218, v[70:73] offset:9216
	v_mfma_f32_32x32x16_bf16 v[18:33], v[142:145], v[146:149], v[18:33]
	ds_write_b128 v223, v[74:77]
	ds_write_b128 v223, v[78:81] offset:9216
	v_mfma_f32_32x32x16_bf16 v[2:17], v[150:153], v[146:149], v[2:17]
	global_load_dwordx4 v[66:69], v212, s[0:1] offset:256
	global_load_dwordx4 v[70:73], v212, s[2:3] offset:256
	global_load_dwordx4 v[74:77], v216, s[4:5] offset:256
	global_load_dwordx4 v[78:81], v216, s[6:7] offset:256
	ds_read_b128 v[130:133], v219 offset:36864
	ds_read_b128 v[134:137], v220 offset:36864
	ds_read_b128 v[138:141], v219 offset:41472
	s_waitcnt lgkmcnt(11)
	v_mfma_f32_32x32x16_bf16 v[18:33], v[154:157], v[158:161], v[18:33]
	ds_read_b128 v[142:145], v219 offset:36896
	ds_read_b128 v[146:149], v220 offset:36896
	ds_read_b128 v[150:153], v219 offset:41504
	s_waitcnt lgkmcnt(13)
	v_mfma_f32_32x32x16_bf16 v[2:17], v[162:165], v[158:161], v[2:17]
	s_waitcnt lgkmcnt(11)
	v_mfma_f32_32x32x16_bf16 v[18:33], v[166:169], v[170:173], v[18:33]
	s_waitcnt lgkmcnt(10)
	v_mfma_f32_32x32x16_bf16 v[2:17], v[174:177], v[170:173], v[2:17]
	s_waitcnt lgkmcnt(0)
	s_barrier
	ds_read_b128 v[154:157], v219 offset:36928
	ds_read_b128 v[158:161], v220 offset:36928
	ds_read_b128 v[162:165], v219 offset:41536
	v_mfma_f32_32x32x16_bf16 v[18:33], v[130:133], v[134:137], v[18:33]
	ds_read_b128 v[166:169], v219 offset:36960
	ds_read_b128 v[170:173], v220 offset:36960
	ds_read_b128 v[174:177], v219 offset:41568
	v_mfma_f32_32x32x16_bf16 v[2:17], v[138:141], v[134:137], v[2:17]
	s_waitcnt vmcnt(16)
	ds_write_b128 v218, v[82:85] offset:18432
	ds_write_b128 v218, v[86:89] offset:27648
	v_mfma_f32_32x32x16_bf16 v[18:33], v[142:145], v[146:149], v[18:33]
	ds_write_b128 v223, v[90:93] offset:18432
	ds_write_b128 v223, v[94:97] offset:27648
	v_mfma_f32_32x32x16_bf16 v[2:17], v[150:153], v[146:149], v[2:17]
	global_load_dwordx4 v[82:85], v212, s[0:1] offset:384
	global_load_dwordx4 v[86:89], v212, s[2:3] offset:384
	global_load_dwordx4 v[90:93], v216, s[4:5] offset:384
	global_load_dwordx4 v[94:97], v216, s[6:7] offset:384
	ds_read_b128 v[130:133], v219
	ds_read_b128 v[134:137], v220
	ds_read_b128 v[138:141], v219 offset:4608
	s_waitcnt lgkmcnt(11)
	v_mfma_f32_32x32x16_bf16 v[18:33], v[154:157], v[158:161], v[18:33]
	ds_read_b128 v[142:145], v219 offset:32
	ds_read_b128 v[146:149], v220 offset:32
	ds_read_b128 v[150:153], v219 offset:4640
	s_waitcnt lgkmcnt(13)
	v_mfma_f32_32x32x16_bf16 v[2:17], v[162:165], v[158:161], v[2:17]
	s_waitcnt lgkmcnt(11)
	v_mfma_f32_32x32x16_bf16 v[18:33], v[166:169], v[170:173], v[18:33]
	s_waitcnt lgkmcnt(10)
	v_mfma_f32_32x32x16_bf16 v[2:17], v[174:177], v[170:173], v[2:17]
	s_waitcnt vmcnt(28)
	s_nop 15
	v_lshlrev_b32_e32 v226, 16, v178
	v_and_b32_e32 v227, 0xffff0000, v178
	v_pk_mul_f32 v[34:35], v[226:227], v[18:19]
	v_lshlrev_b32_e32 v228, 16, v179
	v_and_b32_e32 v229, 0xffff0000, v179
	v_pk_mul_f32 v[36:37], v[228:229], v[20:21]
	v_lshlrev_b32_e32 v234, 16, v180
	v_and_b32_e32 v235, 0xffff0000, v180
	v_pk_mul_f32 v[38:39], v[234:235], v[22:23]
	v_lshlrev_b32_e32 v236, 16, v181
	v_and_b32_e32 v237, 0xffff0000, v181
	v_pk_mul_f32 v[40:41], v[236:237], v[24:25]
	v_lshlrev_b32_e32 v226, 16, v182
	v_and_b32_e32 v227, 0xffff0000, v182
	v_pk_mul_f32 v[42:43], v[226:227], v[26:27]
	v_lshlrev_b32_e32 v228, 16, v183
	v_and_b32_e32 v229, 0xffff0000, v183
	v_pk_mul_f32 v[44:45], v[228:229], v[28:29]
	v_lshlrev_b32_e32 v234, 16, v184
	v_and_b32_e32 v235, 0xffff0000, v184
	v_pk_mul_f32 v[46:47], v[234:235], v[30:31]
	v_lshlrev_b32_e32 v236, 16, v185
	v_and_b32_e32 v237, 0xffff0000, v185
	v_pk_mul_f32 v[48:49], v[236:237], v[32:33]
	v_lshlrev_b32_e32 v226, 16, v186
	v_and_b32_e32 v227, 0xffff0000, v186
	v_pk_mul_f32 v[50:51], v[226:227], v[2:3]
	v_lshlrev_b32_e32 v228, 16, v187
	v_and_b32_e32 v229, 0xffff0000, v187
	v_pk_mul_f32 v[52:53], v[228:229], v[4:5]
	v_lshlrev_b32_e32 v234, 16, v188
	v_and_b32_e32 v235, 0xffff0000, v188
	v_pk_mul_f32 v[54:55], v[234:235], v[6:7]
	v_lshlrev_b32_e32 v236, 16, v189
	v_and_b32_e32 v237, 0xffff0000, v189
	v_pk_mul_f32 v[56:57], v[236:237], v[8:9]
	v_lshlrev_b32_e32 v226, 16, v190
	v_and_b32_e32 v227, 0xffff0000, v190
	v_pk_mul_f32 v[58:59], v[226:227], v[10:11]
	v_lshlrev_b32_e32 v228, 16, v191
	v_and_b32_e32 v229, 0xffff0000, v191
	v_pk_mul_f32 v[60:61], v[228:229], v[12:13]
	v_lshlrev_b32_e32 v234, 16, v192
	v_and_b32_e32 v235, 0xffff0000, v192
	v_pk_mul_f32 v[62:63], v[234:235], v[14:15]
	v_lshlrev_b32_e32 v236, 16, v193
	v_and_b32_e32 v237, 0xffff0000, v193
	v_pk_mul_f32 v[64:65], v[236:237], v[16:17]
	s_waitcnt lgkmcnt(0)
	s_barrier
; template <bool RFA, bool RFB, class LA, class LB, class EPI>
; DI void gemm_tile2s(u16* smem, int nk, LA la, LB lb, EPI epi) {
;     ...
;   auto ld = [&](u32x4 (&ra)[2], u32x4 (&rb)[2], int kt) __attribute__((always_inline)) {
;     const int k0 = kt * 64;
; #pragma unroll
;     for (int i = 0; i < 2; ++i) { const int c = tid + NTH * i; ra[i] = la(A_ROW(c), k0 + A_KC(c) * 8); rb[i] = lb(B_ROW(c), k0 + B_KC(c) * 8); }
;   };
;   auto stl = [&](u32x4 (&ra)[2], u32x4 (&rb)[2], int buf) __attribute__((always_inline)) {
; #pragma unroll
;     for (int i = 0; i < 2; ++i) {
;       const int c = tid + NTH * i;
;       *(u32x4*)(As + buf * TILE_ELEMS + A_ROW(c) * LDT + A_KC(c) * 8) = ra[i];
;       *(u32x4*)(Bs + buf * TILE_ELEMS + B_ROW(c) * LDT + B_KC(c) * 8) = rb[i];
;     }
;   };
;   auto compute = [&](int buf) __attribute__((always_inline)) {
;     const u16* Ab = As + buf * TILE_ELEMS + (wm * 64 + lr) * LDT + lh * 8;
;     const u16* Bb = Bs + buf * TILE_ELEMS + (wn * 32 + lr) * LDT + lh * 8;
; #pragma unroll
;     for (int ks = 0; ks < 4; ++ks) {
;       const bf16x8 a0 = *(const bf16x8*)(Ab + ks * 16);
;       const bf16x8 a1 = *(const bf16x8*)(Ab + 32 * LDT + ks * 16);
;       const bf16x8 b = *(const bf16x8*)(Bb + ks * 16);
;       acc[0] = mfma(a0, b, acc[0]);
;       acc[1] = mfma(a1, b, acc[1]);
;     }
;   };
;   ld(ra0, rb0, 0);
;   if (nk > 1) ld(ra1, rb1, 1);
;   stl(ra0, rb0, 0);
;   if (nk > 2) ld(ra0, rb0, 2);
;   __syncthreads();
; #pragma unroll 1
;   for (int kt = 0; kt < nk; kt += 2) {
;     compute(0);
;     if (kt + 1 < nk) { stl(ra1, rb1, 1); if (kt + 3 < nk) ld(ra1, rb1, kt + 3); }
;     __syncthreads();
;     if (kt + 1 < nk) {
;       compute(1);
;       if (kt + 2 < nk) { stl(ra0, rb0, 0); if (kt + 4 < nk) ld(ra0, rb0, kt + 4); }
;       __syncthreads();
; template <class ACC>
; DI void merge_branch(const Prm& p, u16* smem, const u16* W, const u16* X, int ld, int bi, int n0, int m0, ACC& macc) {
;     ...
;   auto epi = [&](f32x16 (&acc)[2], int wm, int wn, int lane) __attribute__((always_inline)) {
;     const int lr = lane & 31, lh = lane >> 5;
;     const int tok = m0 + wn * 32 + lr;
; #pragma unroll
;     for (int i = 0; i < 2; ++i)
; #pragma unroll
;       for (int h2 = 0; h2 < 2; ++h2) {
;         const int n = n0 + wm * 64 + i * 32 + 16 * lh + 8 * h2;
;         const u32x4 gz = *(const u32x4*)(p.zg + (size_t)tok * 4096 + bi * 1024 + n);
	ds_read_b128 v[154:157], v219 offset:64
	ds_read_b128 v[158:161], v220 offset:64
	ds_read_b128 v[162:165], v219 offset:4672
	v_mfma_f32_32x32x16_bf16 v[18:33], v[130:133], v[134:137], 0
	ds_read_b128 v[166:169], v219 offset:96
	ds_read_b128 v[170:173], v220 offset:96
	ds_read_b128 v[174:177], v219 offset:4704
	v_mfma_f32_32x32x16_bf16 v[2:17], v[138:141], v[134:137], 0
	s_waitcnt vmcnt(12)
	ds_write_b128 v218, v[98:101] offset:36864
	ds_write_b128 v218, v[102:105] offset:46080
	v_mfma_f32_32x32x16_bf16 v[18:33], v[142:145], v[146:149], v[18:33]
	ds_write_b128 v223, v[106:109] offset:36864
	ds_write_b128 v223, v[110:113] offset:46080
	v_mfma_f32_32x32x16_bf16 v[2:17], v[150:153], v[146:149], v[2:17]
	global_load_dwordx4 v[98:101], v212, s[0:1] offset:512
	global_load_dwordx4 v[102:105], v212, s[2:3] offset:512
	global_load_dwordx4 v[106:109], v216, s[4:5] offset:512
	global_load_dwordx4 v[110:113], v216, s[6:7] offset:512
	global_load_dwordx4 v[178:181], v221, s[10:11]
	global_load_dwordx4 v[182:185], v221, s[10:11] offset:16
	global_load_dwordx4 v[186:189], v221, s[10:11] offset:64
	global_load_dwordx4 v[190:193], v221, s[10:11] offset:80
	ds_read_b128 v[130:133], v219 offset:18432
	ds_read_b128 v[134:137], v220 offset:18432
	ds_read_b128 v[138:141], v219 offset:23040
	s_waitcnt lgkmcnt(11)
	v_mfma_f32_32x32x16_bf16 v[18:33], v[154:157], v[158:161], v[18:33]
	ds_read_b128 v[142:145], v219 offset:18464
	ds_read_b128 v[146:149], v220 offset:18464
	ds_read_b128 v[150:153], v219 offset:23072
	s_waitcnt lgkmcnt(13)
	v_mfma_f32_32x32x16_bf16 v[2:17], v[162:165], v[158:161], v[2:17]
	s_waitcnt lgkmcnt(11)
	v_mfma_f32_32x32x16_bf16 v[18:33], v[166:169], v[170:173], v[18:33]
	s_waitcnt lgkmcnt(10)
	v_mfma_f32_32x32x16_bf16 v[2:17], v[174:177], v[170:173], v[2:17]
	s_waitcnt lgkmcnt(0)
	s_barrier
	ds_read_b128 v[154:157], v219 offset:18496
	ds_read_b128 v[158:161], v220 offset:18496
	ds_read_b128 v[162:165], v219 offset:23104
	v_mfma_f32_32x32x16_bf16 v[18:33], v[130:133], v[134:137], v[18:33]
	ds_read_b128 v[166:169], v219 offset:18528
	ds_read_b128 v[170:173], v220 offset:18528
	ds_read_b128 v[174:177], v219 offset:23136
	v_mfma_f32_32x32x16_bf16 v[2:17], v[138:141], v[134:137], v[2:17]
	s_waitcnt vmcnt(16)
	ds_write_b128 v218, v[114:117]
	ds_write_b128 v218, v[118:121] offset:9216
	v_mfma_f32_32x32x16_bf16 v[18:33], v[142:145], v[146:149], v[18:33]
	ds_write_b128 v223, v[122:125]
	ds_write_b128 v223, v[126:129] offset:9216
	v_mfma_f32_32x32x16_bf16 v[2:17], v[150:153], v[146:149], v[2:17]
	global_load_dwordx4 v[114:117], v212, s[0:1] offset:640
	global_load_dwordx4 v[118:121], v212, s[2:3] offset:640
	global_load_dwordx4 v[122:125], v216, s[4:5] offset:640
	global_load_dwordx4 v[126:129], v216, s[6:7] offset:640
	ds_read_b128 v[130:133], v219 offset:36864
	ds_read_b128 v[134:137], v220 offset:36864
	ds_read_b128 v[138:141], v219 offset:41472
	s_waitcnt lgkmcnt(11)
	v_mfma_f32_32x32x16_bf16 v[18:33], v[154:157], v[158:161], v[18:33]
	ds_read_b128 v[142:145], v219 offset:36896
	ds_read_b128 v[146:149], v220 offset:36896
	ds_read_b128 v[150:153], v219 offset:41504
	s_waitcnt lgkmcnt(13)
	v_mfma_f32_32x32x16_bf16 v[2:17], v[162:165], v[158:161], v[2:17]
	s_waitcnt lgkmcnt(11)
	v_mfma_f32_32x32x16_bf16 v[18:33], v[166:169], v[170:173], v[18:33]
	s_waitcnt lgkmcnt(10)
	v_mfma_f32_32x32x16_bf16 v[2:17], v[174:177], v[170:173], v[2:17]
	s_waitcnt vmcnt(28)
	s_nop 15
	v_lshlrev_b32_e32 v226, 16, v194
	v_and_b32_e32 v227, 0xffff0000, v194
	v_pk_fma_f32 v[34:35], v[226:227], v[18:19], v[34:35]
	v_lshlrev_b32_e32 v228, 16, v195
	v_and_b32_e32 v229, 0xffff0000, v195
	v_pk_fma_f32 v[36:37], v[228:229], v[20:21], v[36:37]
	v_lshlrev_b32_e32 v234, 16, v196
	v_and_b32_e32 v235, 0xffff0000, v196
	v_pk_fma_f32 v[38:39], v[234:235], v[22:23], v[38:39]
	v_lshlrev_b32_e32 v236, 16, v197
	v_and_b32_e32 v237, 0xffff0000, v197
	v_pk_fma_f32 v[40:41], v[236:237], v[24:25], v[40:41]
	v_lshlrev_b32_e32 v226, 16, v198
	v_and_b32_e32 v227, 0xffff0000, v198
	v_pk_fma_f32 v[42:43], v[226:227], v[26:27], v[42:43]
	v_lshlrev_b32_e32 v228, 16, v199
	v_and_b32_e32 v229, 0xffff0000, v199
	v_pk_fma_f32 v[44:45], v[228:229], v[28:29], v[44:45]
	v_lshlrev_b32_e32 v234, 16, v200
	v_and_b32_e32 v235, 0xffff0000, v200
	v_pk_fma_f32 v[46:47], v[234:235], v[30:31], v[46:47]
	v_lshlrev_b32_e32 v236, 16, v201
	v_and_b32_e32 v237, 0xffff0000, v201
	v_pk_fma_f32 v[48:49], v[236:237], v[32:33], v[48:49]
	v_lshlrev_b32_e32 v226, 16, v202
	v_and_b32_e32 v227, 0xffff0000, v202
	v_pk_fma_f32 v[50:51], v[226:227], v[2:3], v[50:51]
	v_lshlrev_b32_e32 v228, 16, v203
	v_and_b32_e32 v229, 0xffff0000, v203
	v_pk_fma_f32 v[52:53], v[228:229], v[4:5], v[52:53]
	v_lshlrev_b32_e32 v234, 16, v204
	v_and_b32_e32 v235, 0xffff0000, v204
	v_pk_fma_f32 v[54:55], v[234:235], v[6:7], v[54:55]
	v_lshlrev_b32_e32 v236, 16, v205
	v_and_b32_e32 v237, 0xffff0000, v205
	v_pk_fma_f32 v[56:57], v[236:237], v[8:9], v[56:57]
	v_lshlrev_b32_e32 v226, 16, v206
	v_and_b32_e32 v227, 0xffff0000, v206
	v_pk_fma_f32 v[58:59], v[226:227], v[10:11], v[58:59]
	v_lshlrev_b32_e32 v228, 16, v207
	v_and_b32_e32 v229, 0xffff0000, v207
	v_pk_fma_f32 v[60:61], v[228:229], v[12:13], v[60:61]
	v_lshlrev_b32_e32 v234, 16, v208
	v_and_b32_e32 v235, 0xffff0000, v208
	v_pk_fma_f32 v[62:63], v[234:235], v[14:15], v[62:63]
	v_lshlrev_b32_e32 v236, 16, v209
	v_and_b32_e32 v237, 0xffff0000, v209
	v_pk_fma_f32 v[64:65], v[236:237], v[16:17], v[64:65]
	s_waitcnt lgkmcnt(0)
	s_barrier
; DI f32x16 mfma(bf16x8 a, bf16x8 b, f32x16 c) { return __builtin_amdgcn_mfma_f32_32x32x16_bf16(a, b, c, 0, 0, 0); }
; template <bool RFA, bool RFB, class LA, class LB, class EPI>
; DI void gemm_tile2s(u16* smem, int nk, LA la, LB lb, EPI epi) {
;     ...
;   auto ld = [&](u32x4 (&ra)[2], u32x4 (&rb)[2], int kt) __attribute__((always_inline)) {
;     const int k0 = kt * 64;
; #pragma unroll
;     for (int i = 0; i < 2; ++i) { const int c = tid + NTH * i; ra[i] = la(A_ROW(c), k0 + A_KC(c) * 8); rb[i] = lb(B_ROW(c), k0 + B_KC(c) * 8); }
;   };
;   auto stl = [&](u32x4 (&ra)[2], u32x4 (&rb)[2], int buf) __attribute__((always_inline)) {
; #pragma unroll
;     for (int i = 0; i < 2; ++i) {
;       const int c = tid + NTH * i;
;       *(u32x4*)(As + buf * TILE_ELEMS + A_ROW(c) * LDT + A_KC(c) * 8) = ra[i];
;       *(u32x4*)(Bs + buf * TILE_ELEMS + B_ROW(c) * LDT + B_KC(c) * 8) = rb[i];
;     }
;   };
;   auto compute = [&](int buf) __attribute__((always_inline)) {
;     const u16* Ab = As + buf * TILE_ELEMS + (wm * 64 + lr) * LDT + lh * 8;
;     const u16* Bb = Bs + buf * TILE_ELEMS + (wn * 32 + lr) * LDT + lh * 8;
; #pragma unroll
;     for (int ks = 0; ks < 4; ++ks) {
;       const bf16x8 a0 = *(const bf16x8*)(Ab + ks * 16);
;       const bf16x8 a1 = *(const bf16x8*)(Ab + 32 * LDT + ks * 16);
;       const bf16x8 b = *(const bf16x8*)(Bb + ks * 16);
;       acc[0] = mfma(a0, b, acc[0]);
;       acc[1] = mfma(a1, b, acc[1]);
;     }
;   };
;   ld(ra0, rb0, 0);
;   if (nk > 1) ld(ra1, rb1, 1);
;   stl(ra0, rb0, 0);
;   if (nk > 2) ld(ra0, rb0, 2);
;   __syncthreads();
; #pragma unroll 1
;   for (int kt = 0; kt < nk; kt += 2) {
;     compute(0);
;     if (kt + 1 < nk) { stl(ra1, rb1, 1); if (kt + 3 < nk) ld(ra1, rb1, kt + 3); }
;     __syncthreads();
;     if (kt + 1 < nk) {
;       compute(1);
;       if (kt + 2 < nk) { stl(ra0, rb0, 0); if (kt + 4 < nk) ld(ra0, rb0, kt + 4); }
;       __syncthreads();
; DI void phase_merge(const Prm& p, u16* smem, int l, int& base) {
;     ...
;     merge_branch(p, smem, p.PdT + (size_t)l * 1024 * 256, p.od, 256, 3, n0, m0, macc);
	ds_read_b128 v[154:157], v219 offset:36928
	ds_read_b128 v[158:161], v220 offset:36928
	ds_read_b128 v[162:165], v219 offset:41536
	v_mfma_f32_32x32x16_bf16 v[18:33], v[130:133], v[134:137], 0
	ds_read_b128 v[166:169], v219 offset:36960
	ds_read_b128 v[170:173], v220 offset:36960
	ds_read_b128 v[174:177], v219 offset:41568
	v_mfma_f32_32x32x16_bf16 v[2:17], v[138:141], v[134:137], 0
	s_waitcnt vmcnt(16)
	ds_write_b128 v218, v[66:69] offset:18432
	ds_write_b128 v218, v[70:73] offset:27648
	v_mfma_f32_32x32x16_bf16 v[18:33], v[142:145], v[146:149], v[18:33]
	ds_write_b128 v223, v[74:77] offset:18432
	ds_write_b128 v223, v[78:81] offset:27648
	v_mfma_f32_32x32x16_bf16 v[2:17], v[150:153], v[146:149], v[2:17]
	s_mul_i32 s52, s58, 0x200
	s_add_u32 s0, s44, s52
	s_addc_u32 s1, s45, 0
	s_add_u32 s2, s0, 0x8000
	s_addc_u32 s3, s1, 0
	s_mul_i32 s52, s59, 0x200
	s_add_u32 s4, s40, s52
	s_addc_u32 s5, s41, 0
	s_add_u32 s6, s4, 0x8000
	s_addc_u32 s7, s5, 0
	global_load_dwordx4 v[66:69], v213, s[0:1]
	global_load_dwordx4 v[70:73], v213, s[2:3]
	global_load_dwordx4 v[74:77], v217, s[4:5]
	global_load_dwordx4 v[78:81], v217, s[6:7]
	global_load_dwordx4 v[194:197], v221, s[10:11] offset:2048
	global_load_dwordx4 v[198:201], v221, s[10:11] offset:2064
	global_load_dwordx4 v[202:205], v221, s[10:11] offset:2112
	global_load_dwordx4 v[206:209], v221, s[10:11] offset:2128
	ds_read_b128 v[130:133], v219
	ds_read_b128 v[134:137], v220
	ds_read_b128 v[138:141], v219 offset:4608
	s_waitcnt lgkmcnt(11)
	v_mfma_f32_32x32x16_bf16 v[18:33], v[154:157], v[158:161], v[18:33]
	ds_read_b128 v[142:145], v219 offset:32
	ds_read_b128 v[146:149], v220 offset:32
	ds_read_b128 v[150:153], v219 offset:4640
	s_waitcnt lgkmcnt(13)
	v_mfma_f32_32x32x16_bf16 v[2:17], v[162:165], v[158:161], v[2:17]
	s_waitcnt lgkmcnt(11)
	v_mfma_f32_32x32x16_bf16 v[18:33], v[166:169], v[170:173], v[18:33]
	s_waitcnt lgkmcnt(10)
	v_mfma_f32_32x32x16_bf16 v[2:17], v[174:177], v[170:173], v[2:17]
	s_waitcnt lgkmcnt(0)
	s_barrier
	ds_read_b128 v[154:157], v219 offset:64
	ds_read_b128 v[158:161], v220 offset:64
	ds_read_b128 v[162:165], v219 offset:4672
	v_mfma_f32_32x32x16_bf16 v[18:33], v[130:133], v[134:137], v[18:33]
	ds_read_b128 v[166:169], v219 offset:96
	ds_read_b128 v[170:173], v220 offset:96
	ds_read_b128 v[174:177], v219 offset:4704
	v_mfma_f32_32x32x16_bf16 v[2:17], v[138:141], v[134:137], v[2:17]
	s_waitcnt vmcnt(20)
	ds_write_b128 v218, v[82:85] offset:36864
	ds_write_b128 v218, v[86:89] offset:46080
	v_mfma_f32_32x32x16_bf16 v[18:33], v[142:145], v[146:149], v[18:33]
	ds_write_b128 v223, v[90:93] offset:36864
	ds_write_b128 v223, v[94:97] offset:46080
	v_mfma_f32_32x32x16_bf16 v[2:17], v[150:153], v[146:149], v[2:17]
	global_load_dwordx4 v[82:85], v213, s[0:1] offset:128
	global_load_dwordx4 v[86:89], v213, s[2:3] offset:128
	global_load_dwordx4 v[90:93], v217, s[4:5] offset:128
	global_load_dwordx4 v[94:97], v217, s[6:7] offset:128
	ds_read_b128 v[130:133], v219 offset:18432
	ds_read_b128 v[134:137], v220 offset:18432
	ds_read_b128 v[138:141], v219 offset:23040
	s_waitcnt lgkmcnt(11)
	v_mfma_f32_32x32x16_bf16 v[18:33], v[154:157], v[158:161], v[18:33]
	ds_read_b128 v[142:145], v219 offset:18464
	ds_read_b128 v[146:149], v220 offset:18464
	ds_read_b128 v[150:153], v219 offset:23072
	s_waitcnt lgkmcnt(13)
	v_mfma_f32_32x32x16_bf16 v[2:17], v[162:165], v[158:161], v[2:17]
	s_waitcnt lgkmcnt(11)
	v_mfma_f32_32x32x16_bf16 v[18:33], v[166:169], v[170:173], v[18:33]
	s_waitcnt lgkmcnt(10)
	v_mfma_f32_32x32x16_bf16 v[2:17], v[174:177], v[170:173], v[2:17]
	s_waitcnt lgkmcnt(0)
	s_barrier
	ds_read_b128 v[154:157], v219 offset:18496
	ds_read_b128 v[158:161], v220 offset:18496
	ds_read_b128 v[162:165], v219 offset:23104
	v_mfma_f32_32x32x16_bf16 v[18:33], v[130:133], v[134:137], v[18:33]
	ds_read_b128 v[166:169], v219 offset:18528
	ds_read_b128 v[170:173], v220 offset:18528
	ds_read_b128 v[174:177], v219 offset:23136
	v_mfma_f32_32x32x16_bf16 v[2:17], v[138:141], v[134:137], v[2:17]
	s_waitcnt vmcnt(20)
	ds_write_b128 v218, v[98:101]
	ds_write_b128 v218, v[102:105] offset:9216
	v_mfma_f32_32x32x16_bf16 v[18:33], v[142:145], v[146:149], v[18:33]
	ds_write_b128 v223, v[106:109]
	ds_write_b128 v223, v[110:113] offset:9216
	v_mfma_f32_32x32x16_bf16 v[2:17], v[150:153], v[146:149], v[2:17]
	global_load_dwordx4 v[98:101], v213, s[0:1] offset:256
	global_load_dwordx4 v[102:105], v213, s[2:3] offset:256
	global_load_dwordx4 v[106:109], v217, s[4:5] offset:256
	global_load_dwordx4 v[110:113], v217, s[6:7] offset:256
	ds_read_b128 v[130:133], v219 offset:36864
	ds_read_b128 v[134:137], v220 offset:36864
	ds_read_b128 v[138:141], v219 offset:41472
	s_waitcnt lgkmcnt(11)
	v_mfma_f32_32x32x16_bf16 v[18:33], v[154:157], v[158:161], v[18:33]
	ds_read_b128 v[142:145], v219 offset:36896
	ds_read_b128 v[146:149], v220 offset:36896
	ds_read_b128 v[150:153], v219 offset:41504
	s_waitcnt lgkmcnt(13)
	v_mfma_f32_32x32x16_bf16 v[2:17], v[162:165], v[158:161], v[2:17]
	s_waitcnt lgkmcnt(11)
	v_mfma_f32_32x32x16_bf16 v[18:33], v[166:169], v[170:173], v[18:33]
	s_waitcnt lgkmcnt(10)
	v_mfma_f32_32x32x16_bf16 v[2:17], v[174:177], v[170:173], v[2:17]
	s_waitcnt lgkmcnt(0)
	s_barrier
; DI f32x16 mfma(bf16x8 a, bf16x8 b, f32x16 c) { return __builtin_amdgcn_mfma_f32_32x32x16_bf16(a, b, c, 0, 0, 0); }
; #define TASK_LOOP(t, nt, base) for (int t = (int)((blockIdx.x + gridDim.x - ((unsigned)(base) % gridDim.x)) % gridDim.x); t < (nt); t += gridDim.x)
; template <bool RFA, bool RFB, class LA, class LB, class EPI>
; DI void gemm_tile2s(u16* smem, int nk, LA la, LB lb, EPI epi) {
;     ...
;   auto ld = [&](u32x4 (&ra)[2], u32x4 (&rb)[2], int kt) __attribute__((always_inline)) {
;     const int k0 = kt * 64;
; #pragma unroll
;     for (int i = 0; i < 2; ++i) { const int c = tid + NTH * i; ra[i] = la(A_ROW(c), k0 + A_KC(c) * 8); rb[i] = lb(B_ROW(c), k0 + B_KC(c) * 8); }
;   };
;   auto stl = [&](u32x4 (&ra)[2], u32x4 (&rb)[2], int buf) __attribute__((always_inline)) {
; #pragma unroll
;     for (int i = 0; i < 2; ++i) {
;       const int c = tid + NTH * i;
;       *(u32x4*)(As + buf * TILE_ELEMS + A_ROW(c) * LDT + A_KC(c) * 8) = ra[i];
;       *(u32x4*)(Bs + buf * TILE_ELEMS + B_ROW(c) * LDT + B_KC(c) * 8) = rb[i];
;     }
;   };
;   auto compute = [&](int buf) __attribute__((always_inline)) {
;     const u16* Ab = As + buf * TILE_ELEMS + (wm * 64 + lr) * LDT + lh * 8;
;     const u16* Bb = Bs + buf * TILE_ELEMS + (wn * 32 + lr) * LDT + lh * 8;
; #pragma unroll
;     for (int ks = 0; ks < 4; ++ks) {
;       const bf16x8 a0 = *(const bf16x8*)(Ab + ks * 16);
;       const bf16x8 a1 = *(const bf16x8*)(Ab + 32 * LDT + ks * 16);
;       const bf16x8 b = *(const bf16x8*)(Bb + ks * 16);
;       acc[0] = mfma(a0, b, acc[0]);
;       acc[1] = mfma(a1, b, acc[1]);
;     }
;   };
;   ld(ra0, rb0, 0);
;   if (nk > 1) ld(ra1, rb1, 1);
;   stl(ra0, rb0, 0);
;   if (nk > 2) ld(ra0, rb0, 2);
;   __syncthreads();
; #pragma unroll 1
;   for (int kt = 0; kt < nk; kt += 2) {
;     compute(0);
;     if (kt + 1 < nk) { stl(ra1, rb1, 1); if (kt + 3 < nk) ld(ra1, rb1, kt + 3); }
;     __syncthreads();
;     if (kt + 1 < nk) {
;       compute(1);
;       if (kt + 2 < nk) { stl(ra0, rb0, 0); if (kt + 4 < nk) ld(ra0, rb0, kt + 4); }
;       __syncthreads();
; DI void phase_merge(const Prm& p, u16* smem, int l, int& base) {
;   TASK_LOOP(t, 8 * 128, base) {
;     const int tn = t & 7, tm = t >> 3, n0 = tn * 128, m0 = tm * 128;
	ds_read_b128 v[154:157], v219 offset:36928
	ds_read_b128 v[158:161], v220 offset:36928
	ds_read_b128 v[162:165], v219 offset:41536
	v_mfma_f32_32x32x16_bf16 v[18:33], v[130:133], v[134:137], v[18:33]
	ds_read_b128 v[166:169], v219 offset:36960
	ds_read_b128 v[170:173], v220 offset:36960
	ds_read_b128 v[174:177], v219 offset:41568
	v_mfma_f32_32x32x16_bf16 v[2:17], v[138:141], v[134:137], v[2:17]
	s_waitcnt vmcnt(16)
	ds_write_b128 v218, v[114:117] offset:18432
	ds_write_b128 v218, v[118:121] offset:27648
	v_mfma_f32_32x32x16_bf16 v[18:33], v[142:145], v[146:149], v[18:33]
	ds_write_b128 v223, v[122:125] offset:18432
	ds_write_b128 v223, v[126:129] offset:27648
	v_mfma_f32_32x32x16_bf16 v[2:17], v[150:153], v[146:149], v[2:17]
	global_load_dwordx4 v[114:117], v213, s[0:1] offset:384
	global_load_dwordx4 v[118:121], v213, s[2:3] offset:384
	global_load_dwordx4 v[122:125], v217, s[4:5] offset:384
	global_load_dwordx4 v[126:129], v217, s[6:7] offset:384
	ds_read_b128 v[130:133], v219
	ds_read_b128 v[134:137], v220
	ds_read_b128 v[138:141], v219 offset:4608
	s_waitcnt lgkmcnt(11)
	v_mfma_f32_32x32x16_bf16 v[18:33], v[154:157], v[158:161], v[18:33]
	ds_read_b128 v[142:145], v219 offset:32
	ds_read_b128 v[146:149], v220 offset:32
	ds_read_b128 v[150:153], v219 offset:4640
	s_waitcnt lgkmcnt(13)
	v_mfma_f32_32x32x16_bf16 v[2:17], v[162:165], v[158:161], v[2:17]
	s_waitcnt lgkmcnt(11)
	v_mfma_f32_32x32x16_bf16 v[18:33], v[166:169], v[170:173], v[18:33]
	s_waitcnt lgkmcnt(10)
	v_mfma_f32_32x32x16_bf16 v[2:17], v[174:177], v[170:173], v[2:17]
	s_waitcnt lgkmcnt(0)
	s_barrier
	ds_read_b128 v[154:157], v219 offset:64
	ds_read_b128 v[158:161], v220 offset:64
	ds_read_b128 v[162:165], v219 offset:4672
	v_mfma_f32_32x32x16_bf16 v[18:33], v[130:133], v[134:137], v[18:33]
	ds_read_b128 v[166:169], v219 offset:96
	ds_read_b128 v[170:173], v220 offset:96
	ds_read_b128 v[174:177], v219 offset:4704
	v_mfma_f32_32x32x16_bf16 v[2:17], v[138:141], v[134:137], v[2:17]
	s_waitcnt vmcnt(16)
	ds_write_b128 v218, v[66:69] offset:36864
	ds_write_b128 v218, v[70:73] offset:46080
	v_mfma_f32_32x32x16_bf16 v[18:33], v[142:145], v[146:149], v[18:33]
	ds_write_b128 v223, v[74:77] offset:36864
	ds_write_b128 v223, v[78:81] offset:46080
	v_mfma_f32_32x32x16_bf16 v[2:17], v[150:153], v[146:149], v[2:17]
	s_add_i32 s50, s31, s30
	s_cmpk_lt_i32 s50, 0x400
	s_cselect_b32 s50, s50, s31
	s_and_b32 s60, s50, 7
	s_lshl_b32 s60, s60, 7
	s_lshr_b32 s61, s50, 3
	s_lshl_b32 s61, s61, 7
	s_mul_i32 s52, s60, 0x600
	s_add_u32 s0, s16, s52
	s_addc_u32 s1, s17, 0
	s_add_u32 s2, s0, 0x18000
	s_addc_u32 s3, s1, 0
	s_mul_i32 s52, s61, 0x600
	s_add_u32 s4, s14, s52
	s_addc_u32 s5, s15, 0
	s_add_u32 s6, s4, 0x18000
	s_addc_u32 s7, s5, 0
	global_load_dwordx4 v[66:69], v210, s[0:1]
	global_load_dwordx4 v[70:73], v210, s[2:3]
	global_load_dwordx4 v[74:77], v214, s[4:5]
	global_load_dwordx4 v[78:81], v214, s[6:7]
	ds_read_b128 v[130:133], v219 offset:18432
	ds_read_b128 v[134:137], v220 offset:18432
	ds_read_b128 v[138:141], v219 offset:23040
	s_waitcnt lgkmcnt(11)
	v_mfma_f32_32x32x16_bf16 v[18:33], v[154:157], v[158:161], v[18:33]
	ds_read_b128 v[142:145], v219 offset:18464
	ds_read_b128 v[146:149], v220 offset:18464
	ds_read_b128 v[150:153], v219 offset:23072
	s_waitcnt lgkmcnt(13)
	v_mfma_f32_32x32x16_bf16 v[2:17], v[162:165], v[158:161], v[2:17]
	s_waitcnt lgkmcnt(11)
	v_mfma_f32_32x32x16_bf16 v[18:33], v[166:169], v[170:173], v[18:33]
	s_waitcnt lgkmcnt(10)
	v_mfma_f32_32x32x16_bf16 v[2:17], v[174:177], v[170:173], v[2:17]
	s_waitcnt lgkmcnt(0)
	s_barrier
	ds_read_b128 v[154:157], v219 offset:18496
	ds_read_b128 v[158:161], v220 offset:18496
	ds_read_b128 v[162:165], v219 offset:23104
	v_mfma_f32_32x32x16_bf16 v[18:33], v[130:133], v[134:137], v[18:33]
	ds_read_b128 v[166:169], v219 offset:18528
	ds_read_b128 v[170:173], v220 offset:18528
	ds_read_b128 v[174:177], v219 offset:23136
	v_mfma_f32_32x32x16_bf16 v[2:17], v[138:141], v[134:137], v[2:17]
	s_waitcnt vmcnt(12)
	ds_write_b128 v218, v[82:85]
	ds_write_b128 v218, v[86:89] offset:9216
	v_mfma_f32_32x32x16_bf16 v[18:33], v[142:145], v[146:149], v[18:33]
	ds_write_b128 v223, v[90:93]
	ds_write_b128 v223, v[94:97] offset:9216
	v_mfma_f32_32x32x16_bf16 v[2:17], v[150:153], v[146:149], v[2:17]
	global_load_dwordx4 v[82:85], v210, s[0:1] offset:128
	global_load_dwordx4 v[86:89], v210, s[2:3] offset:128
	global_load_dwordx4 v[90:93], v214, s[4:5] offset:128
	global_load_dwordx4 v[94:97], v214, s[6:7] offset:128
	ds_read_b128 v[130:133], v219 offset:36864
	ds_read_b128 v[134:137], v220 offset:36864
	ds_read_b128 v[138:141], v219 offset:41472
	s_waitcnt lgkmcnt(11)
	v_mfma_f32_32x32x16_bf16 v[18:33], v[154:157], v[158:161], v[18:33]
	ds_read_b128 v[142:145], v219 offset:36896
	ds_read_b128 v[146:149], v220 offset:36896
	ds_read_b128 v[150:153], v219 offset:41504
	s_waitcnt lgkmcnt(13)
	v_mfma_f32_32x32x16_bf16 v[2:17], v[162:165], v[158:161], v[2:17]
	s_waitcnt lgkmcnt(11)
	v_mfma_f32_32x32x16_bf16 v[18:33], v[166:169], v[170:173], v[18:33]
	s_waitcnt lgkmcnt(10)
	v_mfma_f32_32x32x16_bf16 v[2:17], v[174:177], v[170:173], v[2:17]
	s_waitcnt vmcnt(32)
; template <bool RFA, bool RFB, class LA, class LB, class EPI>
; DI void gemm_tile2s(u16* smem, int nk, LA la, LB lb, EPI epi) {
;     ...
;   auto ld = [&](u32x4 (&ra)[2], u32x4 (&rb)[2], int kt) __attribute__((always_inline)) {
;     const int k0 = kt * 64;
; #pragma unroll
;     for (int i = 0; i < 2; ++i) { const int c = tid + NTH * i; ra[i] = la(A_ROW(c), k0 + A_KC(c) * 8); rb[i] = lb(B_ROW(c), k0 + B_KC(c) * 8); }
;   };
;   auto stl = [&](u32x4 (&ra)[2], u32x4 (&rb)[2], int buf) __attribute__((always_inline)) {
; #pragma unroll
;     for (int i = 0; i < 2; ++i) {
;       const int c = tid + NTH * i;
;       *(u32x4*)(As + buf * TILE_ELEMS + A_ROW(c) * LDT + A_KC(c) * 8) = ra[i];
;       *(u32x4*)(Bs + buf * TILE_ELEMS + B_ROW(c) * LDT + B_KC(c) * 8) = rb[i];
;     }
;   };
;   auto compute = [&](int buf) __attribute__((always_inline)) {
;     const u16* Ab = As + buf * TILE_ELEMS + (wm * 64 + lr) * LDT + lh * 8;
;     const u16* Bb = Bs + buf * TILE_ELEMS + (wn * 32 + lr) * LDT + lh * 8;
; #pragma unroll
;     for (int ks = 0; ks < 4; ++ks) {
;       const bf16x8 a0 = *(const bf16x8*)(Ab + ks * 16);
;       const bf16x8 a1 = *(const bf16x8*)(Ab + 32 * LDT + ks * 16);
;       const bf16x8 b = *(const bf16x8*)(Bb + ks * 16);
;       acc[0] = mfma(a0, b, acc[0]);
;       acc[1] = mfma(a1, b, acc[1]);
;     }
;   };
;   ld(ra0, rb0, 0);
;   if (nk > 1) ld(ra1, rb1, 1);
;   stl(ra0, rb0, 0);
;   if (nk > 2) ld(ra0, rb0, 2);
;   __syncthreads();
; #pragma unroll 1
;   for (int kt = 0; kt < nk; kt += 2) {
;     compute(0);
; template <class ACC>
; DI void merge_branch(const Prm& p, u16* smem, const u16* W, const u16* X, int ld, int bi, int n0, int m0, ACC& macc) {
;     ...
;   auto epi = [&](f32x16 (&acc)[2], int wm, int wn, int lane) __attribute__((always_inline)) {
;     const int lr = lane & 31, lh = lane >> 5;
;     const int tok = m0 + wn * 32 + lr;
; #pragma unroll
;     for (int i = 0; i < 2; ++i)
; #pragma unroll
;       for (int h2 = 0; h2 < 2; ++h2) {
;         const int n = n0 + wm * 64 + i * 32 + 16 * lh + 8 * h2;
;         const u32x4 gz = *(const u32x4*)(p.zg + (size_t)tok * 4096 + bi * 1024 + n);
; #pragma unroll
;         for (int e = 0; e < 4; ++e) {
;           macc[i][8 * h2 + 2 * e] += bflo(gz[e]) * acc[i][8 * h2 + 2 * e];
;           macc[i][8 * h2 + 2 * e + 1] += bfhi(gz[e]) * acc[i][8 * h2 + 2 * e + 1];
;         }
;       }
	s_nop 15
	v_lshlrev_b32_e32 v226, 16, v178
	v_and_b32_e32 v227, 0xffff0000, v178
	v_pk_fma_f32 v[34:35], v[226:227], v[18:19], v[34:35]
	v_lshlrev_b32_e32 v228, 16, v179
	v_and_b32_e32 v229, 0xffff0000, v179
	v_pk_fma_f32 v[36:37], v[228:229], v[20:21], v[36:37]
	v_lshlrev_b32_e32 v234, 16, v180
	v_and_b32_e32 v235, 0xffff0000, v180
	v_pk_fma_f32 v[38:39], v[234:235], v[22:23], v[38:39]
	v_lshlrev_b32_e32 v236, 16, v181
	v_and_b32_e32 v237, 0xffff0000, v181
	v_pk_fma_f32 v[40:41], v[236:237], v[24:25], v[40:41]
	v_lshlrev_b32_e32 v226, 16, v182
	v_and_b32_e32 v227, 0xffff0000, v182
	v_pk_fma_f32 v[42:43], v[226:227], v[26:27], v[42:43]
	v_lshlrev_b32_e32 v228, 16, v183
	v_and_b32_e32 v229, 0xffff0000, v183
	v_pk_fma_f32 v[44:45], v[228:229], v[28:29], v[44:45]
	v_lshlrev_b32_e32 v234, 16, v184
	v_and_b32_e32 v235, 0xffff0000, v184
	v_pk_fma_f32 v[46:47], v[234:235], v[30:31], v[46:47]
	v_lshlrev_b32_e32 v236, 16, v185
	v_and_b32_e32 v237, 0xffff0000, v185
	v_pk_fma_f32 v[48:49], v[236:237], v[32:33], v[48:49]
	v_lshlrev_b32_e32 v226, 16, v186
	v_and_b32_e32 v227, 0xffff0000, v186
	v_pk_fma_f32 v[50:51], v[226:227], v[2:3], v[50:51]
	v_lshlrev_b32_e32 v228, 16, v187
	v_and_b32_e32 v229, 0xffff0000, v187
	v_pk_fma_f32 v[52:53], v[228:229], v[4:5], v[52:53]
	v_lshlrev_b32_e32 v234, 16, v188
	v_and_b32_e32 v235, 0xffff0000, v188
	v_pk_fma_f32 v[54:55], v[234:235], v[6:7], v[54:55]
	v_lshlrev_b32_e32 v236, 16, v189
	v_and_b32_e32 v237, 0xffff0000, v189
	v_pk_fma_f32 v[56:57], v[236:237], v[8:9], v[56:57]
	v_lshlrev_b32_e32 v226, 16, v190
	v_and_b32_e32 v227, 0xffff0000, v190
	v_pk_fma_f32 v[58:59], v[226:227], v[10:11], v[58:59]
	v_lshlrev_b32_e32 v228, 16, v191
	v_and_b32_e32 v229, 0xffff0000, v191
	v_pk_fma_f32 v[60:61], v[228:229], v[12:13], v[60:61]
	v_lshlrev_b32_e32 v234, 16, v192
	v_and_b32_e32 v235, 0xffff0000, v192
	v_pk_fma_f32 v[62:63], v[234:235], v[14:15], v[62:63]
	v_lshlrev_b32_e32 v236, 16, v193
	v_and_b32_e32 v237, 0xffff0000, v193
	v_pk_fma_f32 v[64:65], v[236:237], v[16:17], v[64:65]
	s_waitcnt lgkmcnt(0)
	s_barrier
	ds_read_b128 v[154:157], v219 offset:36928
	ds_read_b128 v[158:161], v220 offset:36928
	ds_read_b128 v[162:165], v219 offset:41536
	v_mfma_f32_32x32x16_bf16 v[18:33], v[130:133], v[134:137], 0
	ds_read_b128 v[166:169], v219 offset:36960
	ds_read_b128 v[170:173], v220 offset:36960
	ds_read_b128 v[174:177], v219 offset:41568
	v_mfma_f32_32x32x16_bf16 v[2:17], v[138:141], v[134:137], 0
	s_waitcnt vmcnt(12)
	ds_write_b128 v218, v[98:101] offset:18432
	ds_write_b128 v218, v[102:105] offset:27648
	v_mfma_f32_32x32x16_bf16 v[18:33], v[142:145], v[146:149], v[18:33]
	ds_write_b128 v223, v[106:109] offset:18432
	ds_write_b128 v223, v[110:113] offset:27648
	v_mfma_f32_32x32x16_bf16 v[2:17], v[150:153], v[146:149], v[2:17]
	global_load_dwordx4 v[98:101], v210, s[0:1] offset:256
	global_load_dwordx4 v[102:105], v210, s[2:3] offset:256
	global_load_dwordx4 v[106:109], v214, s[4:5] offset:256
	global_load_dwordx4 v[110:113], v214, s[6:7] offset:256
	ds_read_b128 v[130:133], v219
	ds_read_b128 v[134:137], v220
	ds_read_b128 v[138:141], v219 offset:4608
	s_waitcnt lgkmcnt(11)
	v_mfma_f32_32x32x16_bf16 v[18:33], v[154:157], v[158:161], v[18:33]
	ds_read_b128 v[142:145], v219 offset:32
	ds_read_b128 v[146:149], v220 offset:32
	ds_read_b128 v[150:153], v219 offset:4640
	s_waitcnt lgkmcnt(13)
	v_mfma_f32_32x32x16_bf16 v[2:17], v[162:165], v[158:161], v[2:17]
	s_waitcnt lgkmcnt(11)
	v_mfma_f32_32x32x16_bf16 v[18:33], v[166:169], v[170:173], v[18:33]
	s_waitcnt lgkmcnt(10)
	v_mfma_f32_32x32x16_bf16 v[2:17], v[174:177], v[170:173], v[2:17]
	s_waitcnt lgkmcnt(0)
	s_barrier
	ds_read_b128 v[154:157], v219 offset:64
	ds_read_b128 v[158:161], v220 offset:64
	ds_read_b128 v[162:165], v219 offset:4672
	v_mfma_f32_32x32x16_bf16 v[18:33], v[130:133], v[134:137], v[18:33]
	ds_read_b128 v[166:169], v219 offset:96
	ds_read_b128 v[170:173], v220 offset:96
	ds_read_b128 v[174:177], v219 offset:4704
	v_mfma_f32_32x32x16_bf16 v[2:17], v[138:141], v[134:137], v[2:17]
	s_waitcnt vmcnt(12)
	ds_write_b128 v218, v[114:117] offset:36864
	ds_write_b128 v218, v[118:121] offset:46080
	v_mfma_f32_32x32x16_bf16 v[18:33], v[142:145], v[146:149], v[18:33]
	ds_write_b128 v223, v[122:125] offset:36864
	ds_write_b128 v223, v[126:129] offset:46080
	v_mfma_f32_32x32x16_bf16 v[2:17], v[150:153], v[146:149], v[2:17]
	global_load_dwordx4 v[114:117], v210, s[0:1] offset:384
	global_load_dwordx4 v[118:121], v210, s[2:3] offset:384
	global_load_dwordx4 v[122:125], v214, s[4:5] offset:384
	global_load_dwordx4 v[126:129], v214, s[6:7] offset:384
	ds_read_b128 v[130:133], v219 offset:18432
	ds_read_b128 v[134:137], v220 offset:18432
	ds_read_b128 v[138:141], v219 offset:23040
	s_waitcnt lgkmcnt(11)
	v_mfma_f32_32x32x16_bf16 v[18:33], v[154:157], v[158:161], v[18:33]
	ds_read_b128 v[142:145], v219 offset:18464
	ds_read_b128 v[146:149], v220 offset:18464
	ds_read_b128 v[150:153], v219 offset:23072
	s_waitcnt lgkmcnt(13)
	v_mfma_f32_32x32x16_bf16 v[2:17], v[162:165], v[158:161], v[2:17]
	s_waitcnt lgkmcnt(11)
	v_mfma_f32_32x32x16_bf16 v[18:33], v[166:169], v[170:173], v[18:33]
	s_waitcnt lgkmcnt(10)
	v_mfma_f32_32x32x16_bf16 v[2:17], v[174:177], v[170:173], v[2:17]
	s_waitcnt lgkmcnt(0)
	s_barrier
; DI float bflo(unsigned w) { return __uint_as_float(w << 16); }
; DI float bfhi(unsigned w) { return __uint_as_float(w & 0xffff0000u); }
; template <class ACC>
; DI void merge_branch(const Prm& p, u16* smem, const u16* W, const u16* X, int ld, int bi, int n0, int m0, ACC& macc) {
;   auto la = [&](int row, int k) __attribute__((always_inline)) { return *(const u32x4*)(W + (size_t)(n0 + (row & ~31) + perm_m(row & 31)) * ld + k); };
;   auto lb = [&](int row, int k) __attribute__((always_inline)) { return *(const u32x4*)(X + (size_t)(m0 + row) * ld + k); };
;   auto epi = [&](f32x16 (&acc)[2], int wm, int wn, int lane) __attribute__((always_inline)) {
;     const int lr = lane & 31, lh = lane >> 5;
;     const int tok = m0 + wn * 32 + lr;
; #pragma unroll
;     for (int i = 0; i < 2; ++i)
; #pragma unroll
;       for (int h2 = 0; h2 < 2; ++h2) {
;         const int n = n0 + wm * 64 + i * 32 + 16 * lh + 8 * h2;
;         const u32x4 gz = *(const u32x4*)(p.zg + (size_t)tok * 4096 + bi * 1024 + n);
; #pragma unroll
;         for (int e = 0; e < 4; ++e) {
;           macc[i][8 * h2 + 2 * e] += bflo(gz[e]) * acc[i][8 * h2 + 2 * e];
;           macc[i][8 * h2 + 2 * e + 1] += bfhi(gz[e]) * acc[i][8 * h2 + 2 * e + 1];
;         }
;       }
;   };
;   gemm_tile2s<false, false>(smem, ld >> 6, la, lb, epi);
; }
; DI void phase_merge(const Prm& p, u16* smem, int l, int& base) {
;   TASK_LOOP(t, 8 * 128, base) {
;     const int tn = t & 7, tm = t >> 3, n0 = tn * 128, m0 = tm * 128;
;     f32x16 macc[2];
;     macc[0] = zero16(); macc[1] = zero16();
;     merge_branch(p, smem, p.PaT + (size_t)l * 1024 * 768, p.UT, 768, 0, n0, m0, macc);
;     merge_branch(p, smem, p.PbT + (size_t)l * 1024 * 128, p.ob, 128, 1, n0, m0, macc);
;     ...
;     merge_branch(p, smem, p.PdT + (size_t)l * 1024 * 256, p.od, 256, 3, n0, m0, macc);
;     const int tid2 = tidx(), lane = tid2 & 63, wave = tid2 >> 6, wm = wave >> 2, wn = wave & 3, lr = lane & 31, lh = lane >> 5;
;     const int tok = m0 + wn * 32 + lr;
; #pragma unroll
;     for (int i = 0; i < 2; ++i)
; #pragma unroll
;       for (int h2 = 0; h2 < 2; ++h2) {
;         u32x4 o;
; #pragma unroll
;         for (int e = 0; e < 4; ++e) o[e] = pack2(macc[i][8 * h2 + 2 * e], macc[i][8 * h2 + 2 * e + 1]);
;         *(u32x4*)(p.hbuf + (size_t)tok * 1024 + n0 + wm * 64 + i * 32 + 16 * lh + 8 * h2) = o;
;       }
;   }
;   base += 8 * 128;
; }
	ds_read_b128 v[154:157], v219 offset:18496
	ds_read_b128 v[158:161], v220 offset:18496
	ds_read_b128 v[162:165], v219 offset:23104
	v_mfma_f32_32x32x16_bf16 v[18:33], v[130:133], v[134:137], v[18:33]
	ds_read_b128 v[166:169], v219 offset:18528
	ds_read_b128 v[170:173], v220 offset:18528
	ds_read_b128 v[174:177], v219 offset:23136
	v_mfma_f32_32x32x16_bf16 v[2:17], v[138:141], v[134:137], v[2:17]
	s_waitcnt vmcnt(12)
	ds_write_b128 v218, v[66:69]
	ds_write_b128 v218, v[70:73] offset:9216
	v_mfma_f32_32x32x16_bf16 v[18:33], v[142:145], v[146:149], v[18:33]
	ds_write_b128 v223, v[74:77]
	ds_write_b128 v223, v[78:81] offset:9216
	v_mfma_f32_32x32x16_bf16 v[2:17], v[150:153], v[146:149], v[2:17]
	global_load_dwordx4 v[66:69], v210, s[0:1] offset:512
	global_load_dwordx4 v[70:73], v210, s[2:3] offset:512
	global_load_dwordx4 v[74:77], v214, s[4:5] offset:512
	global_load_dwordx4 v[78:81], v214, s[6:7] offset:512
	ds_read_b128 v[130:133], v219 offset:36864
	ds_read_b128 v[134:137], v220 offset:36864
	ds_read_b128 v[138:141], v219 offset:41472
	s_waitcnt lgkmcnt(11)
	v_mfma_f32_32x32x16_bf16 v[18:33], v[154:157], v[158:161], v[18:33]
	ds_read_b128 v[142:145], v219 offset:36896
	ds_read_b128 v[146:149], v220 offset:36896
	ds_read_b128 v[150:153], v219 offset:41504
	s_waitcnt lgkmcnt(13)
	v_mfma_f32_32x32x16_bf16 v[2:17], v[162:165], v[158:161], v[2:17]
	s_waitcnt lgkmcnt(11)
	v_mfma_f32_32x32x16_bf16 v[18:33], v[166:169], v[170:173], v[18:33]
	s_waitcnt lgkmcnt(10)
	v_mfma_f32_32x32x16_bf16 v[2:17], v[174:177], v[170:173], v[2:17]
	s_waitcnt lgkmcnt(0)
	s_barrier
	ds_read_b128 v[154:157], v219 offset:36928
	ds_read_b128 v[158:161], v220 offset:36928
	ds_read_b128 v[162:165], v219 offset:41536
	v_mfma_f32_32x32x16_bf16 v[18:33], v[130:133], v[134:137], v[18:33]
	ds_read_b128 v[166:169], v219 offset:36960
	ds_read_b128 v[170:173], v220 offset:36960
	ds_read_b128 v[174:177], v219 offset:41568
	v_mfma_f32_32x32x16_bf16 v[2:17], v[138:141], v[134:137], v[2:17]
	s_waitcnt vmcnt(12)
	ds_write_b128 v218, v[82:85] offset:18432
	ds_write_b128 v218, v[86:89] offset:27648
	v_mfma_f32_32x32x16_bf16 v[18:33], v[142:145], v[146:149], v[18:33]
	ds_write_b128 v223, v[90:93] offset:18432
	ds_write_b128 v223, v[94:97] offset:27648
	v_mfma_f32_32x32x16_bf16 v[2:17], v[150:153], v[146:149], v[2:17]
	global_load_dwordx4 v[82:85], v210, s[0:1] offset:640
	global_load_dwordx4 v[86:89], v210, s[2:3] offset:640
	global_load_dwordx4 v[90:93], v214, s[4:5] offset:640
	global_load_dwordx4 v[94:97], v214, s[6:7] offset:640
	ds_read_b128 v[130:133], v219
	ds_read_b128 v[134:137], v220
	ds_read_b128 v[138:141], v219 offset:4608
	s_waitcnt lgkmcnt(11)
	v_mfma_f32_32x32x16_bf16 v[18:33], v[154:157], v[158:161], v[18:33]
	ds_read_b128 v[142:145], v219 offset:32
	ds_read_b128 v[146:149], v220 offset:32
	ds_read_b128 v[150:153], v219 offset:4640
	s_waitcnt lgkmcnt(13)
	v_mfma_f32_32x32x16_bf16 v[2:17], v[162:165], v[158:161], v[2:17]
	s_waitcnt lgkmcnt(11)
	v_mfma_f32_32x32x16_bf16 v[18:33], v[166:169], v[170:173], v[18:33]
	s_waitcnt lgkmcnt(10)
	v_mfma_f32_32x32x16_bf16 v[2:17], v[174:177], v[170:173], v[2:17]
	s_waitcnt vmcnt(36)
	s_nop 15
	v_lshlrev_b32_e32 v226, 16, v194
	v_and_b32_e32 v227, 0xffff0000, v194
	v_pk_fma_f32 v[34:35], v[226:227], v[18:19], v[34:35]
	v_lshlrev_b32_e32 v228, 16, v195
	v_and_b32_e32 v229, 0xffff0000, v195
	v_pk_fma_f32 v[36:37], v[228:229], v[20:21], v[36:37]
	v_lshlrev_b32_e32 v234, 16, v196
	v_and_b32_e32 v235, 0xffff0000, v196
	v_pk_fma_f32 v[38:39], v[234:235], v[22:23], v[38:39]
	v_lshlrev_b32_e32 v236, 16, v197
	v_and_b32_e32 v237, 0xffff0000, v197
	v_pk_fma_f32 v[40:41], v[236:237], v[24:25], v[40:41]
	v_lshlrev_b32_e32 v226, 16, v198
	v_and_b32_e32 v227, 0xffff0000, v198
	v_pk_fma_f32 v[42:43], v[226:227], v[26:27], v[42:43]
	v_lshlrev_b32_e32 v228, 16, v199
	v_and_b32_e32 v229, 0xffff0000, v199
	v_pk_fma_f32 v[44:45], v[228:229], v[28:29], v[44:45]
	v_lshlrev_b32_e32 v234, 16, v200
	v_and_b32_e32 v235, 0xffff0000, v200
	v_pk_fma_f32 v[46:47], v[234:235], v[30:31], v[46:47]
	v_lshlrev_b32_e32 v236, 16, v201
	v_and_b32_e32 v237, 0xffff0000, v201
	v_pk_fma_f32 v[48:49], v[236:237], v[32:33], v[48:49]
	v_lshlrev_b32_e32 v226, 16, v202
	v_and_b32_e32 v227, 0xffff0000, v202
	v_pk_fma_f32 v[50:51], v[226:227], v[2:3], v[50:51]
	v_lshlrev_b32_e32 v228, 16, v203
	v_and_b32_e32 v229, 0xffff0000, v203
	v_pk_fma_f32 v[52:53], v[228:229], v[4:5], v[52:53]
	v_lshlrev_b32_e32 v234, 16, v204
	v_and_b32_e32 v235, 0xffff0000, v204
	v_pk_fma_f32 v[54:55], v[234:235], v[6:7], v[54:55]
	v_lshlrev_b32_e32 v236, 16, v205
	v_and_b32_e32 v237, 0xffff0000, v205
	v_pk_fma_f32 v[56:57], v[236:237], v[8:9], v[56:57]
	v_lshlrev_b32_e32 v226, 16, v206
	v_and_b32_e32 v227, 0xffff0000, v206
	v_pk_fma_f32 v[58:59], v[226:227], v[10:11], v[58:59]
	v_lshlrev_b32_e32 v228, 16, v207
	v_and_b32_e32 v229, 0xffff0000, v207
	v_pk_fma_f32 v[60:61], v[228:229], v[12:13], v[60:61]
	v_lshlrev_b32_e32 v234, 16, v208
	v_and_b32_e32 v235, 0xffff0000, v208
	v_pk_fma_f32 v[62:63], v[234:235], v[14:15], v[62:63]
	v_lshlrev_b32_e32 v236, 16, v209
	v_and_b32_e32 v237, 0xffff0000, v209
	v_pk_fma_f32 v[64:65], v[236:237], v[16:17], v[64:65]
	v_cvt_pk_bf16_f32 v178, v34, v35
	v_cvt_pk_bf16_f32 v179, v36, v37
	v_cvt_pk_bf16_f32 v180, v38, v39
	v_cvt_pk_bf16_f32 v181, v40, v41
	v_cvt_pk_bf16_f32 v182, v42, v43
	v_cvt_pk_bf16_f32 v183, v44, v45
	v_cvt_pk_bf16_f32 v184, v46, v47
	v_cvt_pk_bf16_f32 v185, v48, v49
	v_cvt_pk_bf16_f32 v186, v50, v51
	v_cvt_pk_bf16_f32 v187, v52, v53
	v_cvt_pk_bf16_f32 v188, v54, v55
	v_cvt_pk_bf16_f32 v189, v56, v57
	v_cvt_pk_bf16_f32 v190, v58, v59
	v_cvt_pk_bf16_f32 v191, v60, v61
	v_cvt_pk_bf16_f32 v192, v62, v63
	v_cvt_pk_bf16_f32 v193, v64, v65
	global_store_dwordx4 v222, v[178:181], s[12:13]
	global_store_dwordx4 v222, v[182:185], s[12:13] offset:16
	global_store_dwordx4 v222, v[186:189], s[12:13] offset:64
	global_store_dwordx4 v222, v[190:193], s[12:13] offset:80
	s_waitcnt lgkmcnt(0)
	s_barrier
	s_add_i32 s31, s31, s30
	s_mov_b32 s58, s60
	s_mov_b32 s59, s61
	s_cmpk_lt_i32 s31, 0x400
	s_cbranch_scc1 .Lmrg_task_o
	s_branch .Lmrg_done
